# v60 + two more DMA addresses via SGPR base (up GEMMs) and the 4 redundant post-barrier lgkmcnt(0) per K-loop body removed
# baseline (speedup 1.0000x reference)
; #define PG8_STAGE(bufoff, gbase, voff) do { _Pragma("unroll") for (int _i = 0; _i < 2; ++_i) \
;         __builtin_amdgcn_global_load_lds((const unsigned*)((const char*)(gbase) + (voff)[_i]), (PG8_LAS unsigned*)(lds + (bufoff) + ldsw + _i * 8192), 16, 0, 0); } while (0)
; #define PG8_LDA(dst, b, h) do { _Pragma("unroll") for (int m = 0; m < 4; ++m) _Pragma("unroll") for (int k = 0; k < 2; ++k) dst[m][k] = *(const PG8_LAS bf16x8*)(lds + PG8_SA(b, h) + aoff + m * 2048 + k * 1024); } while (0)
; #define PG8_LDB(dst, b, h) do { _Pragma("unroll") for (int n = 0; n < 2; ++n) _Pragma("unroll") for (int k = 0; k < 2; ++k) dst[n][k] = *(const PG8_LAS bf16x8*)(lds + PG8_SB(b, h) + boff + n * 2048 + k * 1024); } while (0)
; #define PG8_MMA(ai, bj, At, Bt) do { __builtin_amdgcn_s_setprio(1); _Pragma("unroll") for (int m = 0; m < 4; ++m) _Pragma("unroll") for (int n = 0; n < 2; ++n) _Pragma("unroll") for (int k = 0; k < 2; ++k) \
;         acc[ai][bj][m][n] = __builtin_amdgcn_mfma_f32_16x16x32_bf16(Bt[n][k], At[m][k], acc[ai][bj][m][n], 0, 0, 0); __builtin_amdgcn_s_setprio(0); } while (0)
; #define PG8_WAIT_V(n) asm volatile("s_waitcnt vmcnt(" #n ")" ::: "memory")
; #define PG8_BAR __builtin_amdgcn_s_barrier()
; template <class Epi, class Sched, bool ALIGN_EPI = false, bool SP2 = false>
; __device__ __forceinline__ void gemm_phase(PG8_LAS unsigned char* lds, const Gemm g, const Sched& S, const Epi& E, const int wv) {
;     ...
;         for (int t = 0; t < nt; t += 2) {
;             const bool last = (t == nt - 2);
;             const char* a1 = cA + (size_t)(t + 1) * kstep;
;             const char* a2 = last ? nA : cA + (size_t)(t + 2) * kstep; const char* b2 = last ? nB : cB + (size_t)(t + 2) * kstep;
;             const char* a3 = a2 + kstep; const char* b3 = b2 + kstep;
;             if (last && has_next) S.a_ready(nxt);
;             if constexpr (SP2) {
;             PG8_LDB(B0, 0, 0); PG8_LDB(B1, 0, 1); PG8_SCHED; PG8_LDA(At, 0, 0); PG8_STAGE(PG8_SA(1, 1), a1 + hstepA, voffA);
;             PG8_WAIT_V(8); PG8_WAIT_L(0); PG8_BAR; PG8_MMA(0, 0, At, B0); PG8_MMA(0, 1, At, B1); PG8_BAR; PG8_SCHED;
;             PG8_LDA(At, 0, 1); PG8_STAGE(PG8_SB(0, 0), b2, voffB); PG8_STAGE(PG8_SB(0, 1), b2 + hstepB, voffB); PG8_STAGE(PG8_SA(0, 0), a2, voffA);
;             PG8_WAIT_V(8); PG8_WAIT_L(0); PG8_BAR; PG8_MMA(1, 0, At, B0); PG8_MMA(1, 1, At, B1); PG8_BAR; PG8_SCHED;
.LBB0_176:
	s_add_i32 s67, s14, 2
	s_add_u32 s68, s12, 0xfff80080
	s_addc_u32 s15, s13, -1
	s_add_i32 s70, 0, 0x10000
	s_cmp_eq_u32 s61, s14
	s_cselect_b32 s15, s11, s15
	s_cselect_b32 s14, s35, s68
	v_add_u32_e32 v59, s70, v185
	s_cselect_b32 s69, s45, s43
	s_cselect_b32 s68, s44, s42
	s_add_i32 s71, 0, 0x14000
	ds_read_b128 v[66:69], v59
	ds_read_b128 v[74:77], v59 offset:1024
	ds_read_b128 v[82:85], v59 offset:2048
	ds_read_b128 v[86:89], v59 offset:3072
	v_add_u32_e32 v59, s71, v185
	ds_read_b128 v[154:157], v59
	ds_read_b128 v[158:161], v59 offset:1024
	ds_read_b128 v[174:177], v59 offset:2048
	ds_read_b128 v[178:181], v59 offset:3072
	s_add_i32 m0, s54, 0xc000
	ds_read_b128 v[202:205], v200
	ds_read_b128 v[206:209], v200 offset:1024
	ds_read_b128 v[210:213], v200 offset:2048
	ds_read_b128 v[214:217], v200 offset:3072
	ds_read_b128 v[228:231], v200 offset:4096
	ds_read_b128 v[232:235], v200 offset:5120
	ds_read_b128 v[236:239], v200 offset:6144
	ds_read_b128 v[240:243], v200 offset:7168
	global_load_lds_dwordx4 v170, s[12:13]
	s_add_i32 m0, s54, 0xe000
	s_nop 0
	global_load_lds_dwordx4 v172, s[12:13]
	s_waitcnt vmcnt(8)
	s_waitcnt lgkmcnt(0)
	s_barrier
	v_mfma_f32_16x16x32_bf16 v[150:153], v[66:69], v[202:205], v[150:153]
	v_mfma_f32_16x16x32_bf16 v[146:149], v[82:85], v[202:205], v[146:149]
	v_mfma_f32_16x16x32_bf16 v[134:137], v[66:69], v[210:213], v[134:137]
	v_mfma_f32_16x16x32_bf16 v[130:133], v[82:85], v[210:213], v[130:133]
	v_mfma_f32_16x16x32_bf16 v[118:121], v[66:69], v[228:231], v[118:121]
	v_mfma_f32_16x16x32_bf16 v[114:117], v[82:85], v[228:231], v[114:117]
	v_mfma_f32_16x16x32_bf16 v[102:105], v[66:69], v[236:239], v[102:105]
	v_mfma_f32_16x16x32_bf16 v[98:101], v[82:85], v[236:239], v[98:101]
	v_mfma_f32_16x16x32_bf16 v[150:153], v[74:77], v[206:209], v[150:153]
	v_mfma_f32_16x16x32_bf16 v[146:149], v[86:89], v[206:209], v[146:149]
	v_mfma_f32_16x16x32_bf16 v[134:137], v[74:77], v[214:217], v[134:137]
	v_mfma_f32_16x16x32_bf16 v[130:133], v[86:89], v[214:217], v[130:133]
	v_mfma_f32_16x16x32_bf16 v[118:121], v[74:77], v[232:235], v[118:121]
	v_mfma_f32_16x16x32_bf16 v[114:117], v[86:89], v[232:235], v[114:117]
	v_mfma_f32_16x16x32_bf16 v[102:105], v[74:77], v[240:243], v[102:105]
	v_mfma_f32_16x16x32_bf16 v[98:101], v[86:89], v[240:243], v[98:101]
	v_mfma_f32_16x16x32_bf16 v[142:145], v[154:157], v[202:205], v[142:145]
	v_mfma_f32_16x16x32_bf16 v[138:141], v[174:177], v[202:205], v[138:141]
	v_mfma_f32_16x16x32_bf16 v[126:129], v[154:157], v[210:213], v[126:129]
	v_mfma_f32_16x16x32_bf16 v[122:125], v[174:177], v[210:213], v[122:125]
	v_mfma_f32_16x16x32_bf16 v[110:113], v[154:157], v[228:231], v[110:113]
	v_mfma_f32_16x16x32_bf16 v[106:109], v[174:177], v[228:231], v[106:109]
	v_mfma_f32_16x16x32_bf16 v[94:97], v[154:157], v[236:239], v[94:97]
	v_mfma_f32_16x16x32_bf16 v[90:93], v[174:177], v[236:239], v[90:93]
	v_mfma_f32_16x16x32_bf16 v[142:145], v[158:161], v[206:209], v[142:145]
	v_mfma_f32_16x16x32_bf16 v[138:141], v[178:181], v[206:209], v[138:141]
	v_mfma_f32_16x16x32_bf16 v[126:129], v[158:161], v[214:217], v[126:129]
	v_mfma_f32_16x16x32_bf16 v[122:125], v[178:181], v[214:217], v[122:125]
	v_mfma_f32_16x16x32_bf16 v[110:113], v[158:161], v[232:235], v[110:113]
	v_mfma_f32_16x16x32_bf16 v[106:109], v[178:181], v[232:235], v[106:109]
	v_mfma_f32_16x16x32_bf16 v[94:97], v[158:161], v[240:243], v[94:97]
	v_mfma_f32_16x16x32_bf16 v[90:93], v[178:181], v[240:243], v[90:93]
	s_barrier
	s_add_i32 s70, s70, s53
	v_lshl_add_u64 v[218:219], s[68:69], 0, v[0:1]
	s_mov_b32 m0, s70
	ds_read_b128 v[202:205], v200 offset:16384
	ds_read_b128 v[206:209], v200 offset:17408
	ds_read_b128 v[210:213], v200 offset:18432
	ds_read_b128 v[214:217], v200 offset:19456
	ds_read_b128 v[228:231], v200 offset:20480
	ds_read_b128 v[232:235], v200 offset:21504
	ds_read_b128 v[236:239], v200 offset:22528
	ds_read_b128 v[240:243], v200 offset:23552
	global_load_lds_dwordx4 v[218:219], off
	s_add_i32 m0, s70, 0x2000
	v_lshl_add_u64 v[244:245], s[68:69], 0, v[166:167]
	s_add_u32 s68, s68, s24
	s_addc_u32 s69, s69, s25
	s_add_i32 s70, s71, s53
	global_load_lds_dwordx4 v[244:245], off
	v_lshl_add_u64 v[246:247], s[68:69], 0, v[0:1]
	s_mov_b32 m0, s70
	v_lshl_add_u64 v[248:249], s[68:69], 0, v[166:167]
	global_load_lds_dwordx4 v[246:247], off
	s_add_i32 m0, s70, 0x2000
	v_lshl_add_u64 v[250:251], s[14:15], 0, v[162:163]
	global_load_lds_dwordx4 v[248:249], off
	s_mov_b32 m0, s54
	v_lshl_add_u64 v[252:253], s[14:15], 0, v[164:165]
	global_load_lds_dwordx4 v[250:251], off
	s_mov_b32 m0, s55
	s_nop 0
	global_load_lds_dwordx4 v[252:253], off
	s_waitcnt vmcnt(8)
	s_waitcnt lgkmcnt(0)
	s_barrier
; #define PG8_STAGE(bufoff, gbase, voff) do { _Pragma("unroll") for (int _i = 0; _i < 2; ++_i) \
;         __builtin_amdgcn_global_load_lds((const unsigned*)((const char*)(gbase) + (voff)[_i]), (PG8_LAS unsigned*)(lds + (bufoff) + ldsw + _i * 8192), 16, 0, 0); } while (0)
; #define PG8_LDA(dst, b, h) do { _Pragma("unroll") for (int m = 0; m < 4; ++m) _Pragma("unroll") for (int k = 0; k < 2; ++k) dst[m][k] = *(const PG8_LAS bf16x8*)(lds + PG8_SA(b, h) + aoff + m * 2048 + k * 1024); } while (0)
; #define PG8_LDB(dst, b, h) do { _Pragma("unroll") for (int n = 0; n < 2; ++n) _Pragma("unroll") for (int k = 0; k < 2; ++k) dst[n][k] = *(const PG8_LAS bf16x8*)(lds + PG8_SB(b, h) + boff + n * 2048 + k * 1024); } while (0)
; #define PG8_MMA(ai, bj, At, Bt) do { __builtin_amdgcn_s_setprio(1); _Pragma("unroll") for (int m = 0; m < 4; ++m) _Pragma("unroll") for (int n = 0; n < 2; ++n) _Pragma("unroll") for (int k = 0; k < 2; ++k) \
;         acc[ai][bj][m][n] = __builtin_amdgcn_mfma_f32_16x16x32_bf16(Bt[n][k], At[m][k], acc[ai][bj][m][n], 0, 0, 0); __builtin_amdgcn_s_setprio(0); } while (0)
; #define PG8_WAIT_V(n) asm volatile("s_waitcnt vmcnt(" #n ")" ::: "memory")
; #define PG8_WAIT_L(n) asm volatile("s_waitcnt lgkmcnt(" #n ")" ::: "memory")
; #define PG8_BAR __builtin_amdgcn_s_barrier()
; #define PG8_SCHED __builtin_amdgcn_sched_barrier(0)
; template <class Epi, class Sched, bool ALIGN_EPI = false, bool SP2 = false>
; __device__ __forceinline__ void gemm_phase(PG8_LAS unsigned char* lds, const Gemm g, const Sched& S, const Epi& E, const int wv) {
;     ...
;             PG8_WAIT_V(8); PG8_WAIT_L(0); PG8_BAR; PG8_MMA(1, 0, At, B0); PG8_MMA(1, 1, At, B1); PG8_BAR; PG8_SCHED;
;             PG8_LDB(B0, 1, 0); PG8_LDB(B1, 1, 1); PG8_SCHED; PG8_LDA(At, 1, 0); PG8_STAGE(PG8_SA(0, 1), a2 + hstepA, voffA);
;             PG8_WAIT_V(8); PG8_WAIT_L(0); PG8_BAR; PG8_MMA(0, 0, At, B0); PG8_MMA(0, 1, At, B1); PG8_BAR; PG8_SCHED;
	v_mfma_f32_16x16x32_bf16 v[78:81], v[66:69], v[202:205], v[78:81]
	v_mfma_f32_16x16x32_bf16 v[70:73], v[82:85], v[202:205], v[70:73]
	v_mfma_f32_16x16x32_bf16 v[46:49], v[66:69], v[210:213], v[46:49]
	v_mfma_f32_16x16x32_bf16 v[42:45], v[82:85], v[210:213], v[42:45]
	v_mfma_f32_16x16x32_bf16 v[30:33], v[66:69], v[228:231], v[30:33]
	v_mfma_f32_16x16x32_bf16 v[26:29], v[82:85], v[228:231], v[26:29]
	v_mfma_f32_16x16x32_bf16 v[14:17], v[66:69], v[236:239], v[14:17]
	v_mfma_f32_16x16x32_bf16 v[10:13], v[82:85], v[236:239], v[10:13]
	v_mfma_f32_16x16x32_bf16 v[78:81], v[74:77], v[206:209], v[78:81]
	v_mfma_f32_16x16x32_bf16 v[70:73], v[86:89], v[206:209], v[70:73]
	v_mfma_f32_16x16x32_bf16 v[46:49], v[74:77], v[214:217], v[46:49]
	v_mfma_f32_16x16x32_bf16 v[42:45], v[86:89], v[214:217], v[42:45]
	v_mfma_f32_16x16x32_bf16 v[30:33], v[74:77], v[232:235], v[30:33]
	v_mfma_f32_16x16x32_bf16 v[26:29], v[86:89], v[232:235], v[26:29]
	v_mfma_f32_16x16x32_bf16 v[14:17], v[74:77], v[240:243], v[14:17]
	v_mfma_f32_16x16x32_bf16 v[10:13], v[86:89], v[240:243], v[10:13]
	v_mfma_f32_16x16x32_bf16 v[60:63], v[154:157], v[202:205], v[62:65]
	v_mfma_f32_16x16x32_bf16 v[54:57], v[174:177], v[202:205], v[54:57]
	v_mfma_f32_16x16x32_bf16 v[38:41], v[154:157], v[210:213], v[38:41]
	v_mfma_f32_16x16x32_bf16 v[34:37], v[174:177], v[210:213], v[34:37]
	v_mfma_f32_16x16x32_bf16 v[22:25], v[154:157], v[228:231], v[22:25]
	v_mfma_f32_16x16x32_bf16 v[18:21], v[174:177], v[228:231], v[18:21]
	v_mfma_f32_16x16x32_bf16 v[6:9], v[154:157], v[236:239], v[6:9]
	v_mfma_f32_16x16x32_bf16 v[2:5], v[174:177], v[236:239], v[2:5]
	v_mfma_f32_16x16x32_bf16 v[60:63], v[158:161], v[206:209], v[60:63]
	v_mfma_f32_16x16x32_bf16 v[54:57], v[178:181], v[206:209], v[54:57]
	v_mfma_f32_16x16x32_bf16 v[38:41], v[158:161], v[214:217], v[38:41]
	v_mfma_f32_16x16x32_bf16 v[34:37], v[178:181], v[214:217], v[34:37]
	v_mfma_f32_16x16x32_bf16 v[22:25], v[158:161], v[232:235], v[22:25]
	v_mfma_f32_16x16x32_bf16 v[18:21], v[178:181], v[232:235], v[18:21]
	v_mfma_f32_16x16x32_bf16 v[6:9], v[158:161], v[240:243], v[6:9]
	v_mfma_f32_16x16x32_bf16 v[2:5], v[178:181], v[240:243], v[2:5]
	s_barrier
	s_add_i32 s68, 0, 0x18000
	v_add_u32_e32 v59, s68, v185
	s_add_i32 s69, 0, 0x1c000
	ds_read_b128 v[64:67], v59
	ds_read_b128 v[74:77], v59 offset:1024
	ds_read_b128 v[82:85], v59 offset:2048
	ds_read_b128 v[86:89], v59 offset:3072
	v_add_u32_e32 v59, s69, v185
	ds_read_b128 v[154:157], v59
	ds_read_b128 v[158:161], v59 offset:1024
	ds_read_b128 v[174:177], v59 offset:2048
	ds_read_b128 v[178:181], v59 offset:3072
	s_add_u32 s14, s14, 0x80000
	s_addc_u32 s15, s15, 0
	s_mov_b32 m0, s56
	ds_read_b128 v[202:205], v200 offset:32768
	ds_read_b128 v[206:209], v200 offset:33792
	ds_read_b128 v[210:213], v200 offset:34816
	ds_read_b128 v[214:217], v200 offset:35840
	ds_read_b128 v[228:231], v200 offset:36864
	ds_read_b128 v[232:235], v200 offset:37888
	ds_read_b128 v[236:239], v200 offset:38912
	ds_read_b128 v[240:243], v200 offset:39936
	global_load_lds_dwordx4 v162, s[14:15]
	s_mov_b32 m0, s57
	s_nop 0
	global_load_lds_dwordx4 v164, s[14:15]
	s_waitcnt vmcnt(8)
	s_waitcnt lgkmcnt(0)
	s_barrier
	v_mfma_f32_16x16x32_bf16 v[150:153], v[64:67], v[202:205], v[150:153]
	v_mfma_f32_16x16x32_bf16 v[146:149], v[82:85], v[202:205], v[146:149]
	v_mfma_f32_16x16x32_bf16 v[134:137], v[64:67], v[210:213], v[134:137]
	v_mfma_f32_16x16x32_bf16 v[130:133], v[82:85], v[210:213], v[130:133]
	v_mfma_f32_16x16x32_bf16 v[118:121], v[64:67], v[228:231], v[118:121]
	v_mfma_f32_16x16x32_bf16 v[114:117], v[82:85], v[228:231], v[114:117]
	v_mfma_f32_16x16x32_bf16 v[102:105], v[64:67], v[236:239], v[102:105]
	v_mfma_f32_16x16x32_bf16 v[98:101], v[82:85], v[236:239], v[98:101]
	v_mfma_f32_16x16x32_bf16 v[150:153], v[74:77], v[206:209], v[150:153]
	v_mfma_f32_16x16x32_bf16 v[146:149], v[86:89], v[206:209], v[146:149]
	v_mfma_f32_16x16x32_bf16 v[134:137], v[74:77], v[214:217], v[134:137]
	v_mfma_f32_16x16x32_bf16 v[130:133], v[86:89], v[214:217], v[130:133]
	v_mfma_f32_16x16x32_bf16 v[118:121], v[74:77], v[232:235], v[118:121]
	v_mfma_f32_16x16x32_bf16 v[114:117], v[86:89], v[232:235], v[114:117]
	v_mfma_f32_16x16x32_bf16 v[102:105], v[74:77], v[240:243], v[102:105]
	v_mfma_f32_16x16x32_bf16 v[98:101], v[86:89], v[240:243], v[98:101]
	v_mfma_f32_16x16x32_bf16 v[142:145], v[154:157], v[202:205], v[142:145]
	v_mfma_f32_16x16x32_bf16 v[138:141], v[174:177], v[202:205], v[138:141]
	v_mfma_f32_16x16x32_bf16 v[126:129], v[154:157], v[210:213], v[126:129]
	v_mfma_f32_16x16x32_bf16 v[122:125], v[174:177], v[210:213], v[122:125]
	v_mfma_f32_16x16x32_bf16 v[110:113], v[154:157], v[228:231], v[110:113]
	v_mfma_f32_16x16x32_bf16 v[106:109], v[174:177], v[228:231], v[106:109]
	v_mfma_f32_16x16x32_bf16 v[94:97], v[154:157], v[236:239], v[94:97]
	v_mfma_f32_16x16x32_bf16 v[90:93], v[174:177], v[236:239], v[90:93]
	v_mfma_f32_16x16x32_bf16 v[142:145], v[158:161], v[206:209], v[142:145]
	v_mfma_f32_16x16x32_bf16 v[138:141], v[178:181], v[206:209], v[138:141]
	v_mfma_f32_16x16x32_bf16 v[126:129], v[158:161], v[214:217], v[126:129]
	v_mfma_f32_16x16x32_bf16 v[122:125], v[178:181], v[214:217], v[122:125]
	v_mfma_f32_16x16x32_bf16 v[110:113], v[158:161], v[232:235], v[110:113]
	v_mfma_f32_16x16x32_bf16 v[106:109], v[178:181], v[232:235], v[106:109]
	v_mfma_f32_16x16x32_bf16 v[94:97], v[158:161], v[240:243], v[94:97]
	v_mfma_f32_16x16x32_bf16 v[90:93], v[178:181], v[240:243], v[90:93]
	s_barrier
; #define PG8_STAGE(bufoff, gbase, voff) do { _Pragma("unroll") for (int _i = 0; _i < 2; ++_i) \
;         __builtin_amdgcn_global_load_lds((const unsigned*)((const char*)(gbase) + (voff)[_i]), (PG8_LAS unsigned*)(lds + (bufoff) + ldsw + _i * 8192), 16, 0, 0); } while (0)
; #define PG8_LDA(dst, b, h) do { _Pragma("unroll") for (int m = 0; m < 4; ++m) _Pragma("unroll") for (int k = 0; k < 2; ++k) dst[m][k] = *(const PG8_LAS bf16x8*)(lds + PG8_SA(b, h) + aoff + m * 2048 + k * 1024); } while (0)
; #define PG8_MMA(ai, bj, At, Bt) do { __builtin_amdgcn_s_setprio(1); _Pragma("unroll") for (int m = 0; m < 4; ++m) _Pragma("unroll") for (int n = 0; n < 2; ++n) _Pragma("unroll") for (int k = 0; k < 2; ++k) \
;         acc[ai][bj][m][n] = __builtin_amdgcn_mfma_f32_16x16x32_bf16(Bt[n][k], At[m][k], acc[ai][bj][m][n], 0, 0, 0); __builtin_amdgcn_s_setprio(0); } while (0)
; #define PG8_WAIT_V(n) asm volatile("s_waitcnt vmcnt(" #n ")" ::: "memory")
; #define PG8_WAIT_L(n) asm volatile("s_waitcnt lgkmcnt(" #n ")" ::: "memory")
; #define PG8_BAR __builtin_amdgcn_s_barrier()
; #define PG8_SCHED __builtin_amdgcn_sched_barrier(0)
; template <class Epi, class Sched, bool ALIGN_EPI = false, bool SP2 = false>
; __device__ __forceinline__ void gemm_phase(PG8_LAS unsigned char* lds, const Gemm g, const Sched& S, const Epi& E, const int wv) {
;     ...
;             PG8_LDA(At, 1, 1); PG8_STAGE(PG8_SB(1, 0), b3, voffB); PG8_STAGE(PG8_SB(1, 1), b3 + hstepB, voffB); PG8_STAGE(PG8_SA(1, 0), a3, voffA);
;             PG8_WAIT_V(8); PG8_WAIT_L(0); PG8_BAR; PG8_MMA(1, 0, At, B0); PG8_MMA(1, 1, At, B1); PG8_BAR; PG8_SCHED;
	s_add_i32 s14, s68, s53
	s_add_i32 m0, s14, 0xffffff80
	ds_read_b128 v[202:205], v200 offset:49152
	ds_read_b128 v[206:209], v200 offset:50176
	ds_read_b128 v[210:213], v200 offset:51200
	ds_read_b128 v[214:217], v200 offset:52224
	ds_read_b128 v[228:231], v200 offset:53248
	ds_read_b128 v[232:235], v200 offset:54272
	ds_read_b128 v[236:239], v200 offset:55296
	ds_read_b128 v[240:243], v200 offset:56320
	global_load_lds_dwordx4 v[218:219], off offset:128
	s_add_i32 m0, s14, 0x1f80
	s_add_i32 s14, s69, s53
	global_load_lds_dwordx4 v[244:245], off offset:128
	s_add_i32 m0, s14, 0xffffff80
	s_nop 0
	global_load_lds_dwordx4 v[246:247], off offset:128
	s_add_i32 m0, s14, 0x1f80
	s_nop 0
	global_load_lds_dwordx4 v[248:249], off offset:128
	s_add_i32 m0, s58, 0xffffff80
	s_nop 0
	global_load_lds_dwordx4 v[250:251], off offset:128
	s_add_i32 m0, s59, 0xffffff80
	s_nop 0
	global_load_lds_dwordx4 v[252:253], off offset:128
	s_waitcnt vmcnt(8)
	s_waitcnt lgkmcnt(0)
	s_barrier
	v_mfma_f32_16x16x32_bf16 v[78:81], v[64:67], v[202:205], v[78:81]
	v_mfma_f32_16x16x32_bf16 v[68:71], v[82:85], v[202:205], v[70:73]
	v_mfma_f32_16x16x32_bf16 v[46:49], v[64:67], v[210:213], v[46:49]
	v_mfma_f32_16x16x32_bf16 v[42:45], v[82:85], v[210:213], v[42:45]
	v_mfma_f32_16x16x32_bf16 v[30:33], v[64:67], v[228:231], v[30:33]
	v_mfma_f32_16x16x32_bf16 v[26:29], v[82:85], v[228:231], v[26:29]
	v_mfma_f32_16x16x32_bf16 v[14:17], v[64:67], v[236:239], v[14:17]
	v_mfma_f32_16x16x32_bf16 v[10:13], v[82:85], v[236:239], v[10:13]
	v_mfma_f32_16x16x32_bf16 v[78:81], v[74:77], v[206:209], v[78:81]
	v_mfma_f32_16x16x32_bf16 v[70:73], v[86:89], v[206:209], v[68:71]
	v_mfma_f32_16x16x32_bf16 v[46:49], v[74:77], v[214:217], v[46:49]
	v_mfma_f32_16x16x32_bf16 v[42:45], v[86:89], v[214:217], v[42:45]
	v_mfma_f32_16x16x32_bf16 v[30:33], v[74:77], v[232:235], v[30:33]
	v_mfma_f32_16x16x32_bf16 v[26:29], v[86:89], v[232:235], v[26:29]
	v_mfma_f32_16x16x32_bf16 v[14:17], v[74:77], v[240:243], v[14:17]
	v_mfma_f32_16x16x32_bf16 v[10:13], v[86:89], v[240:243], v[10:13]
	v_mfma_f32_16x16x32_bf16 v[60:63], v[154:157], v[202:205], v[60:63]
	v_mfma_f32_16x16x32_bf16 v[54:57], v[174:177], v[202:205], v[54:57]
	v_mfma_f32_16x16x32_bf16 v[38:41], v[154:157], v[210:213], v[38:41]
	v_mfma_f32_16x16x32_bf16 v[34:37], v[174:177], v[210:213], v[34:37]
	v_mfma_f32_16x16x32_bf16 v[22:25], v[154:157], v[228:231], v[22:25]
	v_mfma_f32_16x16x32_bf16 v[18:21], v[174:177], v[228:231], v[18:21]
	v_mfma_f32_16x16x32_bf16 v[6:9], v[154:157], v[236:239], v[6:9]
	v_mfma_f32_16x16x32_bf16 v[2:5], v[174:177], v[236:239], v[2:5]
	v_mfma_f32_16x16x32_bf16 v[62:65], v[158:161], v[206:209], v[60:63]
	v_mfma_f32_16x16x32_bf16 v[54:57], v[178:181], v[206:209], v[54:57]
	v_mfma_f32_16x16x32_bf16 v[38:41], v[158:161], v[214:217], v[38:41]
	v_mfma_f32_16x16x32_bf16 v[34:37], v[178:181], v[214:217], v[34:37]
	v_mfma_f32_16x16x32_bf16 v[22:25], v[158:161], v[232:235], v[22:25]
	v_mfma_f32_16x16x32_bf16 v[18:21], v[178:181], v[232:235], v[18:21]
	v_mfma_f32_16x16x32_bf16 v[6:9], v[158:161], v[240:243], v[6:9]
	v_mfma_f32_16x16x32_bf16 v[2:5], v[178:181], v[240:243], v[2:5]
	s_barrier
	s_add_u32 s12, s12, 0x100
	s_addc_u32 s13, s13, 0
	s_add_u32 s42, s42, 0x100
	s_addc_u32 s43, s43, 0
	s_cmp_ge_i32 s67, s60
	s_mov_b32 s14, s67
	s_cbranch_scc0 .LBB0_176
	s_movk_i32 s68, 0x4000
	s_movk_i32 s69, 0x6000
	s_mov_b32 s70, 0x18000
	s_mov_b32 s71, 0x3f317217

; #define PG8_STAGE(bufoff, gbase, voff) do { _Pragma("unroll") for (int _i = 0; _i < 2; ++_i) \
;         __builtin_amdgcn_global_load_lds((const unsigned*)((const char*)(gbase) + (voff)[_i]), (PG8_LAS unsigned*)(lds + (bufoff) + ldsw + _i * 8192), 16, 0, 0); } while (0)
; #define PG8_LDA(dst, b, h) do { _Pragma("unroll") for (int m = 0; m < 4; ++m) _Pragma("unroll") for (int k = 0; k < 2; ++k) dst[m][k] = *(const PG8_LAS bf16x8*)(lds + PG8_SA(b, h) + aoff + m * 2048 + k * 1024); } while (0)
; #define PG8_LDB(dst, b, h) do { _Pragma("unroll") for (int n = 0; n < 2; ++n) _Pragma("unroll") for (int k = 0; k < 2; ++k) dst[n][k] = *(const PG8_LAS bf16x8*)(lds + PG8_SB(b, h) + boff + n * 2048 + k * 1024); } while (0)
; #define PG8_MMA(ai, bj, At, Bt) do { __builtin_amdgcn_s_setprio(1); _Pragma("unroll") for (int m = 0; m < 4; ++m) _Pragma("unroll") for (int n = 0; n < 2; ++n) _Pragma("unroll") for (int k = 0; k < 2; ++k) \
;         acc[ai][bj][m][n] = __builtin_amdgcn_mfma_f32_16x16x32_bf16(Bt[n][k], At[m][k], acc[ai][bj][m][n], 0, 0, 0); __builtin_amdgcn_s_setprio(0); } while (0)
; #define PG8_WAIT_V(n) asm volatile("s_waitcnt vmcnt(" #n ")" ::: "memory")
; #define PG8_BAR __builtin_amdgcn_s_barrier()
; template <class Epi, class Sched, bool ALIGN_EPI = false, bool SP2 = false>
; __device__ __forceinline__ void gemm_phase(PG8_LAS unsigned char* lds, const Gemm g, const Sched& S, const Epi& E, const int wv) {
;     ...
;         for (int t = 0; t < nt; t += 2) {
;             const bool last = (t == nt - 2);
;             const char* a1 = cA + (size_t)(t + 1) * kstep;
;             const char* a2 = last ? nA : cA + (size_t)(t + 2) * kstep; const char* b2 = last ? nB : cB + (size_t)(t + 2) * kstep;
;             const char* a3 = a2 + kstep; const char* b3 = b2 + kstep;
;             if (last && has_next) S.a_ready(nxt);
;             if constexpr (SP2) {
;             PG8_LDB(B0, 0, 0); PG8_LDB(B1, 0, 1); PG8_SCHED; PG8_LDA(At, 0, 0); PG8_STAGE(PG8_SA(1, 1), a1 + hstepA, voffA);
;             PG8_WAIT_V(8); PG8_WAIT_L(0); PG8_BAR; PG8_MMA(0, 0, At, B0); PG8_MMA(0, 1, At, B1); PG8_BAR; PG8_SCHED;
;             PG8_LDA(At, 0, 1); PG8_STAGE(PG8_SB(0, 0), b2, voffB); PG8_STAGE(PG8_SB(0, 1), b2 + hstepB, voffB); PG8_STAGE(PG8_SA(0, 0), a2, voffA);
;             PG8_WAIT_V(8); PG8_WAIT_L(0); PG8_BAR; PG8_MMA(1, 0, At, B0); PG8_MMA(1, 1, At, B1); PG8_BAR; PG8_SCHED;
.LBB0_336:
	s_add_i32 s40, s14, 2
	s_add_u32 s41, s12, 0xfff80080
	s_addc_u32 s15, s13, -1
	s_add_i32 s65, 0, 0x10000
	s_cmp_eq_u32 s62, s14
	s_cselect_b32 s15, s93, s15
	s_cselect_b32 s14, s92, s41
	s_cselect_b32 s45, s25, s17
	s_cselect_b32 s44, s24, s11
	s_add_i32 s41, 0, 0x14000
	v_add_u32_e32 v46, s65, v197
	v_add_u32_e32 v158, s41, v197
	ds_read_b128 v[26:29], v46
	ds_read_b128 v[30:33], v46 offset:1024
	ds_read_b128 v[42:45], v46 offset:2048
	ds_read_b128 v[46:49], v46 offset:3072
	ds_read_b128 v[146:149], v158
	ds_read_b128 v[150:153], v158 offset:1024
	ds_read_b128 v[154:157], v158 offset:2048
	ds_read_b128 v[158:161], v158 offset:3072
	s_add_i32 m0, s55, 0xc000
	ds_read_b128 v[172:175], v199
	ds_read_b128 v[176:179], v199 offset:1024
	ds_read_b128 v[180:183], v199 offset:2048
	ds_read_b128 v[200:203], v199 offset:3072
	ds_read_b128 v[204:207], v199 offset:4096
	ds_read_b128 v[208:211], v199 offset:5120
	ds_read_b128 v[212:215], v199 offset:6144
	ds_read_b128 v[216:219], v199 offset:7168
	global_load_lds_dwordx4 v168, s[12:13]
	s_add_i32 m0, s55, 0xe000
	s_nop 0
	global_load_lds_dwordx4 v170, s[12:13]
	s_waitcnt vmcnt(8)
	s_waitcnt lgkmcnt(0)
	s_barrier
	v_mfma_f32_16x16x32_bf16 v[138:141], v[26:29], v[172:175], v[138:141]
	v_mfma_f32_16x16x32_bf16 v[142:145], v[42:45], v[172:175], v[142:145]
	v_mfma_f32_16x16x32_bf16 v[126:129], v[26:29], v[180:183], v[126:129]
	v_mfma_f32_16x16x32_bf16 v[122:125], v[42:45], v[180:183], v[122:125]
	v_mfma_f32_16x16x32_bf16 v[110:113], v[26:29], v[204:207], v[110:113]
	v_mfma_f32_16x16x32_bf16 v[106:109], v[42:45], v[204:207], v[106:109]
	v_mfma_f32_16x16x32_bf16 v[94:97], v[26:29], v[212:215], v[94:97]
	v_mfma_f32_16x16x32_bf16 v[90:93], v[42:45], v[212:215], v[90:93]
	v_mfma_f32_16x16x32_bf16 v[138:141], v[30:33], v[176:179], v[138:141]
	v_mfma_f32_16x16x32_bf16 v[142:145], v[46:49], v[176:179], v[142:145]
	v_mfma_f32_16x16x32_bf16 v[126:129], v[30:33], v[200:203], v[126:129]
	v_mfma_f32_16x16x32_bf16 v[122:125], v[46:49], v[200:203], v[122:125]
	v_mfma_f32_16x16x32_bf16 v[110:113], v[30:33], v[208:211], v[110:113]
	v_mfma_f32_16x16x32_bf16 v[106:109], v[46:49], v[208:211], v[106:109]
	v_mfma_f32_16x16x32_bf16 v[94:97], v[30:33], v[216:219], v[94:97]
	v_mfma_f32_16x16x32_bf16 v[90:93], v[46:49], v[216:219], v[90:93]
	v_mfma_f32_16x16x32_bf16 v[134:137], v[146:149], v[172:175], v[134:137]
	v_mfma_f32_16x16x32_bf16 v[130:133], v[154:157], v[172:175], v[130:133]
	v_mfma_f32_16x16x32_bf16 v[118:121], v[146:149], v[180:183], v[118:121]
	v_mfma_f32_16x16x32_bf16 v[114:117], v[154:157], v[180:183], v[114:117]
	v_mfma_f32_16x16x32_bf16 v[102:105], v[146:149], v[204:207], v[102:105]
	v_mfma_f32_16x16x32_bf16 v[98:101], v[154:157], v[204:207], v[98:101]
	v_mfma_f32_16x16x32_bf16 v[86:89], v[146:149], v[212:215], v[86:89]
	v_mfma_f32_16x16x32_bf16 v[82:85], v[154:157], v[212:215], v[82:85]
	v_mfma_f32_16x16x32_bf16 v[134:137], v[150:153], v[176:179], v[134:137]
	v_mfma_f32_16x16x32_bf16 v[130:133], v[158:161], v[176:179], v[130:133]
	v_mfma_f32_16x16x32_bf16 v[118:121], v[150:153], v[200:203], v[118:121]
	v_mfma_f32_16x16x32_bf16 v[114:117], v[158:161], v[200:203], v[114:117]
	v_mfma_f32_16x16x32_bf16 v[102:105], v[150:153], v[208:211], v[102:105]
	v_mfma_f32_16x16x32_bf16 v[98:101], v[158:161], v[208:211], v[98:101]
	v_mfma_f32_16x16x32_bf16 v[86:89], v[150:153], v[216:219], v[86:89]
	v_mfma_f32_16x16x32_bf16 v[82:85], v[158:161], v[216:219], v[82:85]
	s_barrier
	s_add_i32 s65, s65, s54
	v_lshl_add_u64 v[184:185], s[44:45], 0, v[0:1]
	s_mov_b32 m0, s65
	ds_read_b128 v[172:175], v199 offset:16384
	ds_read_b128 v[176:179], v199 offset:17408
	ds_read_b128 v[180:183], v199 offset:18432
	ds_read_b128 v[200:203], v199 offset:19456
	ds_read_b128 v[204:207], v199 offset:20480
	ds_read_b128 v[208:211], v199 offset:21504
	ds_read_b128 v[212:215], v199 offset:22528
	ds_read_b128 v[216:219], v199 offset:23552
	global_load_lds_dwordx4 v[184:185], off
	s_add_i32 m0, s65, 0x2000
	v_lshl_add_u64 v[194:195], s[44:45], 0, v[162:163]
	s_add_u32 s44, s44, s28
	s_addc_u32 s45, s45, s29
	s_add_i32 s41, s41, s54
	global_load_lds_dwordx4 v[194:195], off
	v_lshl_add_u64 v[228:229], s[44:45], 0, v[0:1]
	s_mov_b32 m0, s41
	v_lshl_add_u64 v[230:231], s[44:45], 0, v[162:163]
	global_load_lds_dwordx4 v[228:229], off
	s_add_i32 m0, s41, 0x2000
	v_lshl_add_u64 v[232:233], s[14:15], 0, v[166:167]
	global_load_lds_dwordx4 v[230:231], off
	s_mov_b32 m0, s55
	v_lshl_add_u64 v[234:235], s[14:15], 0, v[164:165]
	global_load_lds_dwordx4 v[232:233], off
	s_mov_b32 m0, s56
	s_nop 0
	global_load_lds_dwordx4 v[234:235], off
	s_waitcnt vmcnt(8)
	s_waitcnt lgkmcnt(0)
	s_barrier
; #define PG8_STAGE(bufoff, gbase, voff) do { _Pragma("unroll") for (int _i = 0; _i < 2; ++_i) \
;         __builtin_amdgcn_global_load_lds((const unsigned*)((const char*)(gbase) + (voff)[_i]), (PG8_LAS unsigned*)(lds + (bufoff) + ldsw + _i * 8192), 16, 0, 0); } while (0)
; #define PG8_LDA(dst, b, h) do { _Pragma("unroll") for (int m = 0; m < 4; ++m) _Pragma("unroll") for (int k = 0; k < 2; ++k) dst[m][k] = *(const PG8_LAS bf16x8*)(lds + PG8_SA(b, h) + aoff + m * 2048 + k * 1024); } while (0)
; #define PG8_LDB(dst, b, h) do { _Pragma("unroll") for (int n = 0; n < 2; ++n) _Pragma("unroll") for (int k = 0; k < 2; ++k) dst[n][k] = *(const PG8_LAS bf16x8*)(lds + PG8_SB(b, h) + boff + n * 2048 + k * 1024); } while (0)
; #define PG8_MMA(ai, bj, At, Bt) do { __builtin_amdgcn_s_setprio(1); _Pragma("unroll") for (int m = 0; m < 4; ++m) _Pragma("unroll") for (int n = 0; n < 2; ++n) _Pragma("unroll") for (int k = 0; k < 2; ++k) \
;         acc[ai][bj][m][n] = __builtin_amdgcn_mfma_f32_16x16x32_bf16(Bt[n][k], At[m][k], acc[ai][bj][m][n], 0, 0, 0); __builtin_amdgcn_s_setprio(0); } while (0)
; #define PG8_WAIT_V(n) asm volatile("s_waitcnt vmcnt(" #n ")" ::: "memory")
; #define PG8_WAIT_L(n) asm volatile("s_waitcnt lgkmcnt(" #n ")" ::: "memory")
; #define PG8_BAR __builtin_amdgcn_s_barrier()
; #define PG8_SCHED __builtin_amdgcn_sched_barrier(0)
; template <class Epi, class Sched, bool ALIGN_EPI = false, bool SP2 = false>
; __device__ __forceinline__ void gemm_phase(PG8_LAS unsigned char* lds, const Gemm g, const Sched& S, const Epi& E, const int wv) {
;     ...
;             PG8_WAIT_V(8); PG8_WAIT_L(0); PG8_BAR; PG8_MMA(1, 0, At, B0); PG8_MMA(1, 1, At, B1); PG8_BAR; PG8_SCHED;
;             PG8_LDB(B0, 1, 0); PG8_LDB(B1, 1, 1); PG8_SCHED; PG8_LDA(At, 1, 0); PG8_STAGE(PG8_SA(0, 1), a2 + hstepA, voffA);
;             PG8_WAIT_V(8); PG8_WAIT_L(0); PG8_BAR; PG8_MMA(0, 0, At, B0); PG8_MMA(0, 1, At, B1); PG8_BAR; PG8_SCHED;
	v_mfma_f32_16x16x32_bf16 v[78:81], v[26:29], v[172:175], v[78:81]
	v_mfma_f32_16x16x32_bf16 v[74:77], v[42:45], v[172:175], v[74:77]
	v_mfma_f32_16x16x32_bf16 v[62:65], v[26:29], v[180:183], v[62:65]
	v_mfma_f32_16x16x32_bf16 v[58:61], v[42:45], v[180:183], v[58:61]
	v_mfma_f32_16x16x32_bf16 v[38:41], v[26:29], v[204:207], v[38:41]
	v_mfma_f32_16x16x32_bf16 v[34:37], v[42:45], v[204:207], v[34:37]
	v_mfma_f32_16x16x32_bf16 v[14:17], v[26:29], v[212:215], v[14:17]
	v_mfma_f32_16x16x32_bf16 v[10:13], v[42:45], v[212:215], v[10:13]
	v_mfma_f32_16x16x32_bf16 v[78:81], v[30:33], v[176:179], v[78:81]
	v_mfma_f32_16x16x32_bf16 v[74:77], v[46:49], v[176:179], v[74:77]
	v_mfma_f32_16x16x32_bf16 v[62:65], v[30:33], v[200:203], v[62:65]
	v_mfma_f32_16x16x32_bf16 v[58:61], v[46:49], v[200:203], v[58:61]
	v_mfma_f32_16x16x32_bf16 v[38:41], v[30:33], v[208:211], v[38:41]
	v_mfma_f32_16x16x32_bf16 v[34:37], v[46:49], v[208:211], v[34:37]
	v_mfma_f32_16x16x32_bf16 v[14:17], v[30:33], v[216:219], v[14:17]
	v_mfma_f32_16x16x32_bf16 v[10:13], v[46:49], v[216:219], v[10:13]
	v_mfma_f32_16x16x32_bf16 v[22:25], v[146:149], v[204:207], v[22:25]
	v_mfma_f32_16x16x32_bf16 v[18:21], v[154:157], v[204:207], v[18:21]
	v_mfma_f32_16x16x32_bf16 v[6:9], v[146:149], v[212:215], v[6:9]
	v_mfma_f32_16x16x32_bf16 v[2:5], v[154:157], v[212:215], v[2:5]
	v_mfma_f32_16x16x32_bf16 v[26:29], v[146:149], v[172:175], v[70:73]
	v_mfma_f32_16x16x32_bf16 v[30:33], v[154:157], v[172:175], v[66:69]
	v_mfma_f32_16x16x32_bf16 v[42:45], v[146:149], v[180:183], v[54:57]
	v_mfma_f32_16x16x32_bf16 v[46:49], v[154:157], v[180:183], v[50:53]
	v_mfma_f32_16x16x32_bf16 v[22:25], v[150:153], v[208:211], v[22:25]
	v_mfma_f32_16x16x32_bf16 v[18:21], v[158:161], v[208:211], v[18:21]
	v_mfma_f32_16x16x32_bf16 v[6:9], v[150:153], v[216:219], v[6:9]
	v_mfma_f32_16x16x32_bf16 v[2:5], v[158:161], v[216:219], v[2:5]
	v_mfma_f32_16x16x32_bf16 v[26:29], v[150:153], v[176:179], v[26:29]
	v_mfma_f32_16x16x32_bf16 v[30:33], v[158:161], v[176:179], v[30:33]
	v_mfma_f32_16x16x32_bf16 v[42:45], v[150:153], v[200:203], v[42:45]
	v_mfma_f32_16x16x32_bf16 v[46:49], v[158:161], v[200:203], v[46:49]
	s_barrier
	s_add_i32 s41, 0, 0x18000
	s_add_i32 s44, 0, 0x1c000
	v_add_u32_e32 v70, s41, v197
	v_add_u32_e32 v158, s44, v197
	ds_read_b128 v[50:53], v70
	ds_read_b128 v[54:57], v70 offset:1024
	ds_read_b128 v[66:69], v70 offset:2048
	ds_read_b128 v[70:73], v70 offset:3072
	ds_read_b128 v[146:149], v158
	ds_read_b128 v[150:153], v158 offset:1024
	ds_read_b128 v[154:157], v158 offset:2048
	ds_read_b128 v[158:161], v158 offset:3072
	s_add_u32 s14, s14, 0x80000
	s_addc_u32 s15, s15, 0
	s_mov_b32 m0, s57
	ds_read_b128 v[172:175], v199 offset:32768
	ds_read_b128 v[176:179], v199 offset:33792
	ds_read_b128 v[180:183], v199 offset:34816
	ds_read_b128 v[200:203], v199 offset:35840
	ds_read_b128 v[204:207], v199 offset:36864
	ds_read_b128 v[208:211], v199 offset:37888
	ds_read_b128 v[212:215], v199 offset:38912
	ds_read_b128 v[216:219], v199 offset:39936
	global_load_lds_dwordx4 v166, s[14:15]
	s_mov_b32 m0, s58
	s_nop 0
	global_load_lds_dwordx4 v164, s[14:15]
	s_waitcnt vmcnt(8)
	s_waitcnt lgkmcnt(0)
	s_barrier
	v_mfma_f32_16x16x32_bf16 v[138:141], v[50:53], v[172:175], v[138:141]
	v_mfma_f32_16x16x32_bf16 v[142:145], v[66:69], v[172:175], v[142:145]
	v_mfma_f32_16x16x32_bf16 v[126:129], v[50:53], v[180:183], v[126:129]
	v_mfma_f32_16x16x32_bf16 v[122:125], v[66:69], v[180:183], v[122:125]
	v_mfma_f32_16x16x32_bf16 v[110:113], v[50:53], v[204:207], v[110:113]
	v_mfma_f32_16x16x32_bf16 v[106:109], v[66:69], v[204:207], v[106:109]
	v_mfma_f32_16x16x32_bf16 v[94:97], v[50:53], v[212:215], v[94:97]
	v_mfma_f32_16x16x32_bf16 v[90:93], v[66:69], v[212:215], v[90:93]
	v_mfma_f32_16x16x32_bf16 v[138:141], v[54:57], v[176:179], v[138:141]
	v_mfma_f32_16x16x32_bf16 v[142:145], v[70:73], v[176:179], v[142:145]
	v_mfma_f32_16x16x32_bf16 v[126:129], v[54:57], v[200:203], v[126:129]
	v_mfma_f32_16x16x32_bf16 v[122:125], v[70:73], v[200:203], v[122:125]
	v_mfma_f32_16x16x32_bf16 v[110:113], v[54:57], v[208:211], v[110:113]
	v_mfma_f32_16x16x32_bf16 v[106:109], v[70:73], v[208:211], v[106:109]
	v_mfma_f32_16x16x32_bf16 v[94:97], v[54:57], v[216:219], v[94:97]
	v_mfma_f32_16x16x32_bf16 v[90:93], v[70:73], v[216:219], v[90:93]
	v_mfma_f32_16x16x32_bf16 v[134:137], v[146:149], v[172:175], v[134:137]
	v_mfma_f32_16x16x32_bf16 v[130:133], v[154:157], v[172:175], v[130:133]
	v_mfma_f32_16x16x32_bf16 v[118:121], v[146:149], v[180:183], v[118:121]
	v_mfma_f32_16x16x32_bf16 v[114:117], v[154:157], v[180:183], v[114:117]
	v_mfma_f32_16x16x32_bf16 v[102:105], v[146:149], v[204:207], v[102:105]
	v_mfma_f32_16x16x32_bf16 v[98:101], v[154:157], v[204:207], v[98:101]
	v_mfma_f32_16x16x32_bf16 v[86:89], v[146:149], v[212:215], v[86:89]
	v_mfma_f32_16x16x32_bf16 v[82:85], v[154:157], v[212:215], v[82:85]
	v_mfma_f32_16x16x32_bf16 v[134:137], v[150:153], v[176:179], v[134:137]
	v_mfma_f32_16x16x32_bf16 v[130:133], v[158:161], v[176:179], v[130:133]
	v_mfma_f32_16x16x32_bf16 v[118:121], v[150:153], v[200:203], v[118:121]
	v_mfma_f32_16x16x32_bf16 v[114:117], v[158:161], v[200:203], v[114:117]
	v_mfma_f32_16x16x32_bf16 v[102:105], v[150:153], v[208:211], v[102:105]
	v_mfma_f32_16x16x32_bf16 v[98:101], v[158:161], v[208:211], v[98:101]
	v_mfma_f32_16x16x32_bf16 v[86:89], v[150:153], v[216:219], v[86:89]
	v_mfma_f32_16x16x32_bf16 v[82:85], v[158:161], v[216:219], v[82:85]
	s_barrier
; #define PG8_STAGE(bufoff, gbase, voff) do { _Pragma("unroll") for (int _i = 0; _i < 2; ++_i) \
;         __builtin_amdgcn_global_load_lds((const unsigned*)((const char*)(gbase) + (voff)[_i]), (PG8_LAS unsigned*)(lds + (bufoff) + ldsw + _i * 8192), 16, 0, 0); } while (0)
; #define PG8_LDA(dst, b, h) do { _Pragma("unroll") for (int m = 0; m < 4; ++m) _Pragma("unroll") for (int k = 0; k < 2; ++k) dst[m][k] = *(const PG8_LAS bf16x8*)(lds + PG8_SA(b, h) + aoff + m * 2048 + k * 1024); } while (0)
; #define PG8_MMA(ai, bj, At, Bt) do { __builtin_amdgcn_s_setprio(1); _Pragma("unroll") for (int m = 0; m < 4; ++m) _Pragma("unroll") for (int n = 0; n < 2; ++n) _Pragma("unroll") for (int k = 0; k < 2; ++k) \
;         acc[ai][bj][m][n] = __builtin_amdgcn_mfma_f32_16x16x32_bf16(Bt[n][k], At[m][k], acc[ai][bj][m][n], 0, 0, 0); __builtin_amdgcn_s_setprio(0); } while (0)
; #define PG8_WAIT_V(n) asm volatile("s_waitcnt vmcnt(" #n ")" ::: "memory")
; #define PG8_WAIT_L(n) asm volatile("s_waitcnt lgkmcnt(" #n ")" ::: "memory")
; #define PG8_BAR __builtin_amdgcn_s_barrier()
; #define PG8_SCHED __builtin_amdgcn_sched_barrier(0)
; template <class Epi, class Sched, bool ALIGN_EPI = false, bool SP2 = false>
; __device__ __forceinline__ void gemm_phase(PG8_LAS unsigned char* lds, const Gemm g, const Sched& S, const Epi& E, const int wv) {
;     ...
;             PG8_LDA(At, 1, 1); PG8_STAGE(PG8_SB(1, 0), b3, voffB); PG8_STAGE(PG8_SB(1, 1), b3 + hstepB, voffB); PG8_STAGE(PG8_SA(1, 0), a3, voffA);
;             PG8_WAIT_V(8); PG8_WAIT_L(0); PG8_BAR; PG8_MMA(1, 0, At, B0); PG8_MMA(1, 1, At, B1); PG8_BAR; PG8_SCHED;
	s_add_i32 s14, s41, s54
	s_add_i32 m0, s14, 0xffffff80
	ds_read_b128 v[172:175], v199 offset:49152
	ds_read_b128 v[176:179], v199 offset:50176
	ds_read_b128 v[180:183], v199 offset:51200
	ds_read_b128 v[200:203], v199 offset:52224
	ds_read_b128 v[204:207], v199 offset:53248
	ds_read_b128 v[208:211], v199 offset:54272
	ds_read_b128 v[212:215], v199 offset:55296
	ds_read_b128 v[216:219], v199 offset:56320
	global_load_lds_dwordx4 v[184:185], off offset:128
	s_add_i32 m0, s14, 0x1f80
	s_add_i32 s14, s44, s54
	global_load_lds_dwordx4 v[194:195], off offset:128
	s_add_i32 m0, s14, 0xffffff80
	s_nop 0
	global_load_lds_dwordx4 v[228:229], off offset:128
	s_add_i32 m0, s14, 0x1f80
	s_nop 0
	global_load_lds_dwordx4 v[230:231], off offset:128
	s_add_i32 m0, s60, 0xffffff80
	s_nop 0
	global_load_lds_dwordx4 v[232:233], off offset:128
	s_add_i32 m0, s61, 0xffffff80
	s_nop 0
	global_load_lds_dwordx4 v[234:235], off offset:128
	s_waitcnt vmcnt(8)
	s_waitcnt lgkmcnt(0)
	s_barrier
	v_mfma_f32_16x16x32_bf16 v[78:81], v[50:53], v[172:175], v[78:81]
	v_mfma_f32_16x16x32_bf16 v[74:77], v[66:69], v[172:175], v[74:77]
	v_mfma_f32_16x16x32_bf16 v[62:65], v[50:53], v[180:183], v[62:65]
	v_mfma_f32_16x16x32_bf16 v[58:61], v[66:69], v[180:183], v[58:61]
	v_mfma_f32_16x16x32_bf16 v[38:41], v[50:53], v[204:207], v[38:41]
	v_mfma_f32_16x16x32_bf16 v[34:37], v[66:69], v[204:207], v[34:37]
	v_mfma_f32_16x16x32_bf16 v[14:17], v[50:53], v[212:215], v[14:17]
	v_mfma_f32_16x16x32_bf16 v[10:13], v[66:69], v[212:215], v[10:13]
	v_mfma_f32_16x16x32_bf16 v[78:81], v[54:57], v[176:179], v[78:81]
	v_mfma_f32_16x16x32_bf16 v[74:77], v[70:73], v[176:179], v[74:77]
	v_mfma_f32_16x16x32_bf16 v[62:65], v[54:57], v[200:203], v[62:65]
	v_mfma_f32_16x16x32_bf16 v[58:61], v[70:73], v[200:203], v[58:61]
	v_mfma_f32_16x16x32_bf16 v[38:41], v[54:57], v[208:211], v[38:41]
	v_mfma_f32_16x16x32_bf16 v[34:37], v[70:73], v[208:211], v[34:37]
	v_mfma_f32_16x16x32_bf16 v[14:17], v[54:57], v[216:219], v[14:17]
	v_mfma_f32_16x16x32_bf16 v[10:13], v[70:73], v[216:219], v[10:13]
	v_mfma_f32_16x16x32_bf16 v[26:29], v[146:149], v[172:175], v[26:29]
	v_mfma_f32_16x16x32_bf16 v[70:73], v[150:153], v[176:179], v[26:29]
	v_mfma_f32_16x16x32_bf16 v[26:29], v[154:157], v[172:175], v[30:33]
	v_mfma_f32_16x16x32_bf16 v[66:69], v[158:161], v[176:179], v[26:29]
	v_mfma_f32_16x16x32_bf16 v[26:29], v[146:149], v[180:183], v[42:45]
	v_mfma_f32_16x16x32_bf16 v[54:57], v[150:153], v[200:203], v[26:29]
	v_mfma_f32_16x16x32_bf16 v[26:29], v[154:157], v[180:183], v[46:49]
	v_mfma_f32_16x16x32_bf16 v[22:25], v[146:149], v[204:207], v[22:25]
	v_mfma_f32_16x16x32_bf16 v[18:21], v[154:157], v[204:207], v[18:21]
	v_mfma_f32_16x16x32_bf16 v[6:9], v[146:149], v[212:215], v[6:9]
	v_mfma_f32_16x16x32_bf16 v[2:5], v[154:157], v[212:215], v[2:5]
	v_mfma_f32_16x16x32_bf16 v[50:53], v[158:161], v[200:203], v[26:29]
	v_mfma_f32_16x16x32_bf16 v[22:25], v[150:153], v[208:211], v[22:25]
	v_mfma_f32_16x16x32_bf16 v[18:21], v[158:161], v[208:211], v[18:21]
	v_mfma_f32_16x16x32_bf16 v[6:9], v[150:153], v[216:219], v[6:9]
	v_mfma_f32_16x16x32_bf16 v[2:5], v[158:161], v[216:219], v[2:5]
	s_barrier
	s_add_u32 s12, s12, 0x100
	s_addc_u32 s13, s13, 0
	s_add_u32 s11, s11, 0x100
	s_addc_u32 s17, s17, 0
	s_cmp_ge_i32 s40, s59
	s_mov_b32 s14, s40
	s_cbranch_scc0 .LBB0_336

; #define PG8_STAGE(bufoff, gbase, voff) do { _Pragma("unroll") for (int _i = 0; _i < 2; ++_i) \
;         __builtin_amdgcn_global_load_lds((const unsigned*)((const char*)(gbase) + (voff)[_i]), (PG8_LAS unsigned*)(lds + (bufoff) + ldsw + _i * 8192), 16, 0, 0); } while (0)
; #define PG8_LDA(dst, b, h) do { _Pragma("unroll") for (int m = 0; m < 4; ++m) _Pragma("unroll") for (int k = 0; k < 2; ++k) dst[m][k] = *(const PG8_LAS bf16x8*)(lds + PG8_SA(b, h) + aoff + m * 2048 + k * 1024); } while (0)
; #define PG8_LDB(dst, b, h) do { _Pragma("unroll") for (int n = 0; n < 2; ++n) _Pragma("unroll") for (int k = 0; k < 2; ++k) dst[n][k] = *(const PG8_LAS bf16x8*)(lds + PG8_SB(b, h) + boff + n * 2048 + k * 1024); } while (0)
; #define PG8_MMA(ai, bj, At, Bt) do { __builtin_amdgcn_s_setprio(1); _Pragma("unroll") for (int m = 0; m < 4; ++m) _Pragma("unroll") for (int n = 0; n < 2; ++n) _Pragma("unroll") for (int k = 0; k < 2; ++k) \
;         acc[ai][bj][m][n] = __builtin_amdgcn_mfma_f32_16x16x32_bf16(Bt[n][k], At[m][k], acc[ai][bj][m][n], 0, 0, 0); __builtin_amdgcn_s_setprio(0); } while (0)
; #define PG8_WAIT_V(n) asm volatile("s_waitcnt vmcnt(" #n ")" ::: "memory")
; #define PG8_BAR __builtin_amdgcn_s_barrier()
; template <class Epi, class Sched, bool ALIGN_EPI = false, bool SP2 = false>
; __device__ __forceinline__ void gemm_phase(PG8_LAS unsigned char* lds, const Gemm g, const Sched& S, const Epi& E, const int wv) {
;     ...
;         for (int t = 0; t < nt; t += 2) {
;             const bool last = (t == nt - 2);
;             const char* a1 = cA + (size_t)(t + 1) * kstep;
;             const char* a2 = last ? nA : cA + (size_t)(t + 2) * kstep; const char* b2 = last ? nB : cB + (size_t)(t + 2) * kstep;
;             const char* a3 = a2 + kstep; const char* b3 = b2 + kstep;
;             if (last && has_next) S.a_ready(nxt);
;             if constexpr (SP2) {
;             PG8_LDB(B0, 0, 0); PG8_LDB(B1, 0, 1); PG8_SCHED; PG8_LDA(At, 0, 0); PG8_STAGE(PG8_SA(1, 1), a1 + hstepA, voffA);
;             PG8_WAIT_V(8); PG8_WAIT_L(0); PG8_BAR; PG8_MMA(0, 0, At, B0); PG8_MMA(0, 1, At, B1); PG8_BAR; PG8_SCHED;
;             PG8_LDA(At, 0, 1); PG8_STAGE(PG8_SB(0, 0), b2, voffB); PG8_STAGE(PG8_SB(0, 1), b2 + hstepB, voffB); PG8_STAGE(PG8_SA(0, 0), a2, voffA);
;             PG8_WAIT_V(8); PG8_WAIT_L(0); PG8_BAR; PG8_MMA(1, 0, At, B0); PG8_MMA(1, 1, At, B1); PG8_BAR; PG8_SCHED;
.LBB0_699:
	s_add_i32 s72, s54, 2
	s_add_u32 s73, s44, 0xfff80080
	s_addc_u32 s55, s45, -1
	s_add_i32 s76, 0, 0x10000
	s_cmp_eq_u32 s66, s54
	s_cselect_b32 s55, s31, s55
	s_cselect_b32 s54, s71, s73
	v_add_u32_e32 v115, s76, v230
	s_cselect_b32 s75, s13, s57
	s_cselect_b32 s74, s12, s56
	s_add_i32 s73, 0, 0x14000
	ds_read_b128 v[126:129], v115
	ds_read_b128 v[138:141], v115 offset:1024
	ds_read_b128 v[142:145], v115 offset:2048
	ds_read_b128 v[146:149], v115 offset:3072
	v_add_u32_e32 v115, s73, v230
	ds_read_b128 v[150:153], v115
	ds_read_b128 v[154:157], v115 offset:1024
	ds_read_b128 v[158:161], v115 offset:2048
	ds_read_b128 v[162:165], v115 offset:3072
	s_add_i32 m0, s59, 0xc000
	ds_read_b128 v[166:169], v235
	ds_read_b128 v[170:173], v235 offset:1024
	ds_read_b128 v[174:177], v235 offset:2048
	ds_read_b128 v[178:181], v235 offset:3072
	ds_read_b128 v[182:185], v235 offset:4096
	ds_read_b128 v[204:207], v235 offset:5120
	ds_read_b128 v[208:211], v235 offset:6144
	ds_read_b128 v[212:215], v235 offset:7168
	global_load_lds_dwordx4 v200, s[44:45]
	s_add_i32 m0, s59, 0xe000
	s_nop 0
	global_load_lds_dwordx4 v202, s[44:45]
	s_waitcnt vmcnt(8)
	s_waitcnt lgkmcnt(0)
	s_barrier
	v_mfma_f32_16x16x32_bf16 v[134:137], v[126:129], v[166:169], v[134:137]
	v_mfma_f32_16x16x32_bf16 v[130:133], v[142:145], v[166:169], v[130:133]
	v_mfma_f32_16x16x32_bf16 v[110:113], v[126:129], v[174:177], v[110:113]
	v_mfma_f32_16x16x32_bf16 v[106:109], v[142:145], v[174:177], v[106:109]
	v_mfma_f32_16x16x32_bf16 v[94:97], v[126:129], v[182:185], v[94:97]
	v_mfma_f32_16x16x32_bf16 v[90:93], v[142:145], v[182:185], v[90:93]
	v_mfma_f32_16x16x32_bf16 v[78:81], v[126:129], v[208:211], v[78:81]
	v_mfma_f32_16x16x32_bf16 v[74:77], v[142:145], v[208:211], v[74:77]
	v_mfma_f32_16x16x32_bf16 v[134:137], v[138:141], v[170:173], v[134:137]
	v_mfma_f32_16x16x32_bf16 v[130:133], v[146:149], v[170:173], v[130:133]
	v_mfma_f32_16x16x32_bf16 v[110:113], v[138:141], v[178:181], v[110:113]
	v_mfma_f32_16x16x32_bf16 v[106:109], v[146:149], v[178:181], v[106:109]
	v_mfma_f32_16x16x32_bf16 v[94:97], v[138:141], v[204:207], v[94:97]
	v_mfma_f32_16x16x32_bf16 v[90:93], v[146:149], v[204:207], v[90:93]
	v_mfma_f32_16x16x32_bf16 v[78:81], v[138:141], v[212:215], v[78:81]
	v_mfma_f32_16x16x32_bf16 v[74:77], v[146:149], v[212:215], v[74:77]
	v_mfma_f32_16x16x32_bf16 v[122:125], v[150:153], v[166:169], v[122:125]
	v_mfma_f32_16x16x32_bf16 v[116:119], v[158:161], v[166:169], v[118:121]
	v_mfma_f32_16x16x32_bf16 v[102:105], v[150:153], v[174:177], v[102:105]
	v_mfma_f32_16x16x32_bf16 v[98:101], v[158:161], v[174:177], v[98:101]
	v_mfma_f32_16x16x32_bf16 v[86:89], v[150:153], v[182:185], v[86:89]
	v_mfma_f32_16x16x32_bf16 v[82:85], v[158:161], v[182:185], v[82:85]
	v_mfma_f32_16x16x32_bf16 v[70:73], v[150:153], v[208:211], v[70:73]
	v_mfma_f32_16x16x32_bf16 v[66:69], v[158:161], v[208:211], v[66:69]
	v_mfma_f32_16x16x32_bf16 v[122:125], v[154:157], v[170:173], v[122:125]
	v_mfma_f32_16x16x32_bf16 v[116:119], v[162:165], v[170:173], v[116:119]
	v_mfma_f32_16x16x32_bf16 v[102:105], v[154:157], v[178:181], v[102:105]
	v_mfma_f32_16x16x32_bf16 v[98:101], v[162:165], v[178:181], v[98:101]
	v_mfma_f32_16x16x32_bf16 v[86:89], v[154:157], v[204:207], v[86:89]
	v_mfma_f32_16x16x32_bf16 v[82:85], v[162:165], v[204:207], v[82:85]
	v_mfma_f32_16x16x32_bf16 v[70:73], v[154:157], v[212:215], v[70:73]
	v_mfma_f32_16x16x32_bf16 v[66:69], v[162:165], v[212:215], v[66:69]
	s_barrier
	s_add_i32 s76, s76, s53
	v_lshl_add_u64 v[216:217], s[74:75], 0, v[0:1]
	s_mov_b32 m0, s76
	ds_read_b128 v[166:169], v235 offset:16384
	ds_read_b128 v[170:173], v235 offset:17408
	ds_read_b128 v[174:177], v235 offset:18432
	ds_read_b128 v[178:181], v235 offset:19456
	ds_read_b128 v[182:185], v235 offset:20480
	ds_read_b128 v[204:207], v235 offset:21504
	ds_read_b128 v[208:211], v235 offset:22528
	ds_read_b128 v[212:215], v235 offset:23552
	global_load_lds_dwordx4 v[216:217], off
	s_add_i32 m0, s76, 0x2000
	v_lshl_add_u64 v[218:219], s[74:75], 0, v[198:199]
	s_add_u32 s74, s74, s34
	s_addc_u32 s75, s75, s35
	s_add_i32 s73, s73, s53
	global_load_lds_dwordx4 v[218:219], off
	v_lshl_add_u64 v[236:237], s[74:75], 0, v[0:1]
	s_mov_b32 m0, s73
	v_lshl_add_u64 v[238:239], s[74:75], 0, v[198:199]
	global_load_lds_dwordx4 v[236:237], off
	s_add_i32 m0, s73, 0x2000
	v_lshl_add_u64 v[240:241], s[54:55], 0, v[194:195]
	global_load_lds_dwordx4 v[238:239], off
	s_mov_b32 m0, s59
	v_lshl_add_u64 v[242:243], s[54:55], 0, v[196:197]
	global_load_lds_dwordx4 v[240:241], off
	s_mov_b32 m0, s60
	s_nop 0
	global_load_lds_dwordx4 v[242:243], off
	s_waitcnt vmcnt(8)
	s_waitcnt lgkmcnt(0)
	s_barrier
; #define PG8_STAGE(bufoff, gbase, voff) do { _Pragma("unroll") for (int _i = 0; _i < 2; ++_i) \
;         __builtin_amdgcn_global_load_lds((const unsigned*)((const char*)(gbase) + (voff)[_i]), (PG8_LAS unsigned*)(lds + (bufoff) + ldsw + _i * 8192), 16, 0, 0); } while (0)
; #define PG8_LDA(dst, b, h) do { _Pragma("unroll") for (int m = 0; m < 4; ++m) _Pragma("unroll") for (int k = 0; k < 2; ++k) dst[m][k] = *(const PG8_LAS bf16x8*)(lds + PG8_SA(b, h) + aoff + m * 2048 + k * 1024); } while (0)
; #define PG8_LDB(dst, b, h) do { _Pragma("unroll") for (int n = 0; n < 2; ++n) _Pragma("unroll") for (int k = 0; k < 2; ++k) dst[n][k] = *(const PG8_LAS bf16x8*)(lds + PG8_SB(b, h) + boff + n * 2048 + k * 1024); } while (0)
; #define PG8_MMA(ai, bj, At, Bt) do { __builtin_amdgcn_s_setprio(1); _Pragma("unroll") for (int m = 0; m < 4; ++m) _Pragma("unroll") for (int n = 0; n < 2; ++n) _Pragma("unroll") for (int k = 0; k < 2; ++k) \
;         acc[ai][bj][m][n] = __builtin_amdgcn_mfma_f32_16x16x32_bf16(Bt[n][k], At[m][k], acc[ai][bj][m][n], 0, 0, 0); __builtin_amdgcn_s_setprio(0); } while (0)
; #define PG8_WAIT_V(n) asm volatile("s_waitcnt vmcnt(" #n ")" ::: "memory")
; #define PG8_WAIT_L(n) asm volatile("s_waitcnt lgkmcnt(" #n ")" ::: "memory")
; #define PG8_BAR __builtin_amdgcn_s_barrier()
; #define PG8_SCHED __builtin_amdgcn_sched_barrier(0)
; template <class Epi, class Sched, bool ALIGN_EPI = false, bool SP2 = false>
; __device__ __forceinline__ void gemm_phase(PG8_LAS unsigned char* lds, const Gemm g, const Sched& S, const Epi& E, const int wv) {
;     ...
;             PG8_WAIT_V(8); PG8_WAIT_L(0); PG8_BAR; PG8_MMA(1, 0, At, B0); PG8_MMA(1, 1, At, B1); PG8_BAR; PG8_SCHED;
;             PG8_LDB(B0, 1, 0); PG8_LDB(B1, 1, 1); PG8_SCHED; PG8_LDA(At, 1, 0); PG8_STAGE(PG8_SA(0, 1), a2 + hstepA, voffA);
;             PG8_WAIT_V(8); PG8_WAIT_L(0); PG8_BAR; PG8_MMA(0, 0, At, B0); PG8_MMA(0, 1, At, B1); PG8_BAR; PG8_SCHED;
	v_mfma_f32_16x16x32_bf16 v[62:65], v[126:129], v[166:169], v[62:65]
	v_mfma_f32_16x16x32_bf16 v[58:61], v[142:145], v[166:169], v[58:61]
	v_mfma_f32_16x16x32_bf16 v[46:49], v[126:129], v[174:177], v[46:49]
	v_mfma_f32_16x16x32_bf16 v[42:45], v[142:145], v[174:177], v[42:45]
	v_mfma_f32_16x16x32_bf16 v[30:33], v[126:129], v[182:185], v[30:33]
	v_mfma_f32_16x16x32_bf16 v[26:29], v[142:145], v[182:185], v[26:29]
	v_mfma_f32_16x16x32_bf16 v[14:17], v[126:129], v[208:211], v[14:17]
	v_mfma_f32_16x16x32_bf16 v[10:13], v[142:145], v[208:211], v[10:13]
	v_mfma_f32_16x16x32_bf16 v[62:65], v[138:141], v[170:173], v[62:65]
	v_mfma_f32_16x16x32_bf16 v[58:61], v[146:149], v[170:173], v[58:61]
	v_mfma_f32_16x16x32_bf16 v[46:49], v[138:141], v[178:181], v[46:49]
	v_mfma_f32_16x16x32_bf16 v[42:45], v[146:149], v[178:181], v[42:45]
	v_mfma_f32_16x16x32_bf16 v[30:33], v[138:141], v[204:207], v[30:33]
	v_mfma_f32_16x16x32_bf16 v[26:29], v[146:149], v[204:207], v[26:29]
	v_mfma_f32_16x16x32_bf16 v[14:17], v[138:141], v[212:215], v[14:17]
	v_mfma_f32_16x16x32_bf16 v[10:13], v[146:149], v[212:215], v[10:13]
	v_mfma_f32_16x16x32_bf16 v[54:57], v[150:153], v[166:169], v[54:57]
	v_mfma_f32_16x16x32_bf16 v[50:53], v[158:161], v[166:169], v[50:53]
	v_mfma_f32_16x16x32_bf16 v[38:41], v[150:153], v[174:177], v[38:41]
	v_mfma_f32_16x16x32_bf16 v[34:37], v[158:161], v[174:177], v[34:37]
	v_mfma_f32_16x16x32_bf16 v[22:25], v[150:153], v[182:185], v[22:25]
	v_mfma_f32_16x16x32_bf16 v[18:21], v[158:161], v[182:185], v[18:21]
	v_mfma_f32_16x16x32_bf16 v[6:9], v[150:153], v[208:211], v[6:9]
	v_mfma_f32_16x16x32_bf16 v[2:5], v[158:161], v[208:211], v[2:5]
	v_mfma_f32_16x16x32_bf16 v[54:57], v[154:157], v[170:173], v[54:57]
	v_mfma_f32_16x16x32_bf16 v[50:53], v[162:165], v[170:173], v[50:53]
	v_mfma_f32_16x16x32_bf16 v[38:41], v[154:157], v[178:181], v[38:41]
	v_mfma_f32_16x16x32_bf16 v[34:37], v[162:165], v[178:181], v[34:37]
	v_mfma_f32_16x16x32_bf16 v[22:25], v[154:157], v[204:207], v[22:25]
	v_mfma_f32_16x16x32_bf16 v[18:21], v[162:165], v[204:207], v[18:21]
	v_mfma_f32_16x16x32_bf16 v[6:9], v[154:157], v[212:215], v[6:9]
	v_mfma_f32_16x16x32_bf16 v[2:5], v[162:165], v[212:215], v[2:5]
	s_barrier
	s_add_i32 s73, 0, 0x18000
	v_add_u32_e32 v115, s73, v230
	s_add_i32 s74, 0, 0x1c000
	ds_read_b128 v[126:129], v115
	ds_read_b128 v[138:141], v115 offset:1024
	ds_read_b128 v[142:145], v115 offset:2048
	ds_read_b128 v[146:149], v115 offset:3072
	v_add_u32_e32 v115, s74, v230
	ds_read_b128 v[150:153], v115
	ds_read_b128 v[154:157], v115 offset:1024
	ds_read_b128 v[158:161], v115 offset:2048
	ds_read_b128 v[162:165], v115 offset:3072
	s_add_u32 s54, s54, 0x80000
	s_addc_u32 s55, s55, 0
	s_mov_b32 m0, s61
	ds_read_b128 v[166:169], v235 offset:32768
	ds_read_b128 v[170:173], v235 offset:33792
	ds_read_b128 v[174:177], v235 offset:34816
	ds_read_b128 v[178:181], v235 offset:35840
	ds_read_b128 v[182:185], v235 offset:36864
	ds_read_b128 v[204:207], v235 offset:37888
	ds_read_b128 v[208:211], v235 offset:38912
	ds_read_b128 v[212:215], v235 offset:39936
	global_load_lds_dwordx4 v194, s[54:55]
	s_mov_b32 m0, s62
	s_nop 0
	global_load_lds_dwordx4 v196, s[54:55]
	s_waitcnt vmcnt(8)
	s_waitcnt lgkmcnt(0)
	s_barrier
	v_mfma_f32_16x16x32_bf16 v[134:137], v[126:129], v[166:169], v[134:137]
	v_mfma_f32_16x16x32_bf16 v[130:133], v[142:145], v[166:169], v[130:133]
	v_mfma_f32_16x16x32_bf16 v[110:113], v[126:129], v[174:177], v[110:113]
	v_mfma_f32_16x16x32_bf16 v[106:109], v[142:145], v[174:177], v[106:109]
	v_mfma_f32_16x16x32_bf16 v[94:97], v[126:129], v[182:185], v[94:97]
	v_mfma_f32_16x16x32_bf16 v[90:93], v[142:145], v[182:185], v[90:93]
	v_mfma_f32_16x16x32_bf16 v[78:81], v[126:129], v[208:211], v[78:81]
	v_mfma_f32_16x16x32_bf16 v[74:77], v[142:145], v[208:211], v[74:77]
	v_mfma_f32_16x16x32_bf16 v[134:137], v[138:141], v[170:173], v[134:137]
	v_mfma_f32_16x16x32_bf16 v[130:133], v[146:149], v[170:173], v[130:133]
	v_mfma_f32_16x16x32_bf16 v[110:113], v[138:141], v[178:181], v[110:113]
	v_mfma_f32_16x16x32_bf16 v[106:109], v[146:149], v[178:181], v[106:109]
	v_mfma_f32_16x16x32_bf16 v[94:97], v[138:141], v[204:207], v[94:97]
	v_mfma_f32_16x16x32_bf16 v[90:93], v[146:149], v[204:207], v[90:93]
	v_mfma_f32_16x16x32_bf16 v[78:81], v[138:141], v[212:215], v[78:81]
	v_mfma_f32_16x16x32_bf16 v[74:77], v[146:149], v[212:215], v[74:77]
	v_mfma_f32_16x16x32_bf16 v[120:123], v[150:153], v[166:169], v[122:125]
	v_mfma_f32_16x16x32_bf16 v[116:119], v[158:161], v[166:169], v[116:119]
	v_mfma_f32_16x16x32_bf16 v[102:105], v[150:153], v[174:177], v[102:105]
	v_mfma_f32_16x16x32_bf16 v[98:101], v[158:161], v[174:177], v[98:101]
	v_mfma_f32_16x16x32_bf16 v[86:89], v[150:153], v[182:185], v[86:89]
	v_mfma_f32_16x16x32_bf16 v[82:85], v[158:161], v[182:185], v[82:85]
	v_mfma_f32_16x16x32_bf16 v[70:73], v[150:153], v[208:211], v[70:73]
	v_mfma_f32_16x16x32_bf16 v[66:69], v[158:161], v[208:211], v[66:69]
	v_mfma_f32_16x16x32_bf16 v[122:125], v[154:157], v[170:173], v[120:123]
	v_mfma_f32_16x16x32_bf16 v[118:121], v[162:165], v[170:173], v[116:119]
	v_mfma_f32_16x16x32_bf16 v[102:105], v[154:157], v[178:181], v[102:105]
	v_mfma_f32_16x16x32_bf16 v[98:101], v[162:165], v[178:181], v[98:101]
	v_mfma_f32_16x16x32_bf16 v[86:89], v[154:157], v[204:207], v[86:89]
	v_mfma_f32_16x16x32_bf16 v[82:85], v[162:165], v[204:207], v[82:85]
	v_mfma_f32_16x16x32_bf16 v[70:73], v[154:157], v[212:215], v[70:73]
	v_mfma_f32_16x16x32_bf16 v[66:69], v[162:165], v[212:215], v[66:69]
	s_barrier
; #define PG8_STAGE(bufoff, gbase, voff) do { _Pragma("unroll") for (int _i = 0; _i < 2; ++_i) \
;         __builtin_amdgcn_global_load_lds((const unsigned*)((const char*)(gbase) + (voff)[_i]), (PG8_LAS unsigned*)(lds + (bufoff) + ldsw + _i * 8192), 16, 0, 0); } while (0)
; #define PG8_LDA(dst, b, h) do { _Pragma("unroll") for (int m = 0; m < 4; ++m) _Pragma("unroll") for (int k = 0; k < 2; ++k) dst[m][k] = *(const PG8_LAS bf16x8*)(lds + PG8_SA(b, h) + aoff + m * 2048 + k * 1024); } while (0)
; #define PG8_MMA(ai, bj, At, Bt) do { __builtin_amdgcn_s_setprio(1); _Pragma("unroll") for (int m = 0; m < 4; ++m) _Pragma("unroll") for (int n = 0; n < 2; ++n) _Pragma("unroll") for (int k = 0; k < 2; ++k) \
;         acc[ai][bj][m][n] = __builtin_amdgcn_mfma_f32_16x16x32_bf16(Bt[n][k], At[m][k], acc[ai][bj][m][n], 0, 0, 0); __builtin_amdgcn_s_setprio(0); } while (0)
; #define PG8_WAIT_V(n) asm volatile("s_waitcnt vmcnt(" #n ")" ::: "memory")
; #define PG8_WAIT_L(n) asm volatile("s_waitcnt lgkmcnt(" #n ")" ::: "memory")
; #define PG8_BAR __builtin_amdgcn_s_barrier()
; #define PG8_SCHED __builtin_amdgcn_sched_barrier(0)
; template <class Epi, class Sched, bool ALIGN_EPI = false, bool SP2 = false>
; __device__ __forceinline__ void gemm_phase(PG8_LAS unsigned char* lds, const Gemm g, const Sched& S, const Epi& E, const int wv) {
;     ...
;             PG8_LDA(At, 1, 1); PG8_STAGE(PG8_SB(1, 0), b3, voffB); PG8_STAGE(PG8_SB(1, 1), b3 + hstepB, voffB); PG8_STAGE(PG8_SA(1, 0), a3, voffA);
;             PG8_WAIT_V(8); PG8_WAIT_L(0); PG8_BAR; PG8_MMA(1, 0, At, B0); PG8_MMA(1, 1, At, B1); PG8_BAR; PG8_SCHED;
	s_add_i32 s54, s73, s53
	s_add_i32 m0, s54, 0xffffff80
	ds_read_b128 v[166:169], v235 offset:49152
	ds_read_b128 v[170:173], v235 offset:50176
	ds_read_b128 v[174:177], v235 offset:51200
	ds_read_b128 v[178:181], v235 offset:52224
	ds_read_b128 v[182:185], v235 offset:53248
	ds_read_b128 v[204:207], v235 offset:54272
	ds_read_b128 v[208:211], v235 offset:55296
	ds_read_b128 v[212:215], v235 offset:56320
	global_load_lds_dwordx4 v[216:217], off offset:128
	s_add_i32 m0, s54, 0x1f80
	s_add_i32 s54, s74, s53
	global_load_lds_dwordx4 v[218:219], off offset:128
	s_add_i32 m0, s54, 0xffffff80
	s_nop 0
	global_load_lds_dwordx4 v[236:237], off offset:128
	s_add_i32 m0, s54, 0x1f80
	s_nop 0
	global_load_lds_dwordx4 v[238:239], off offset:128
	s_add_i32 m0, s64, 0xffffff80
	s_nop 0
	global_load_lds_dwordx4 v[240:241], off offset:128
	s_add_i32 m0, s65, 0xffffff80
	s_nop 0
	global_load_lds_dwordx4 v[242:243], off offset:128
	s_waitcnt vmcnt(8)
	s_waitcnt lgkmcnt(0)
	s_barrier
	v_mfma_f32_16x16x32_bf16 v[62:65], v[126:129], v[166:169], v[62:65]
	v_mfma_f32_16x16x32_bf16 v[58:61], v[142:145], v[166:169], v[58:61]
	v_mfma_f32_16x16x32_bf16 v[46:49], v[126:129], v[174:177], v[46:49]
	v_mfma_f32_16x16x32_bf16 v[42:45], v[142:145], v[174:177], v[42:45]
	v_mfma_f32_16x16x32_bf16 v[30:33], v[126:129], v[182:185], v[30:33]
	v_mfma_f32_16x16x32_bf16 v[26:29], v[142:145], v[182:185], v[26:29]
	v_mfma_f32_16x16x32_bf16 v[14:17], v[126:129], v[208:211], v[14:17]
	v_mfma_f32_16x16x32_bf16 v[10:13], v[142:145], v[208:211], v[10:13]
	v_mfma_f32_16x16x32_bf16 v[62:65], v[138:141], v[170:173], v[62:65]
	v_mfma_f32_16x16x32_bf16 v[58:61], v[146:149], v[170:173], v[58:61]
	v_mfma_f32_16x16x32_bf16 v[46:49], v[138:141], v[178:181], v[46:49]
	v_mfma_f32_16x16x32_bf16 v[42:45], v[146:149], v[178:181], v[42:45]
	v_mfma_f32_16x16x32_bf16 v[30:33], v[138:141], v[204:207], v[30:33]
	v_mfma_f32_16x16x32_bf16 v[26:29], v[146:149], v[204:207], v[26:29]
	v_mfma_f32_16x16x32_bf16 v[14:17], v[138:141], v[212:215], v[14:17]
	v_mfma_f32_16x16x32_bf16 v[10:13], v[146:149], v[212:215], v[10:13]
	v_mfma_f32_16x16x32_bf16 v[54:57], v[150:153], v[166:169], v[54:57]
	v_mfma_f32_16x16x32_bf16 v[50:53], v[158:161], v[166:169], v[50:53]
	v_mfma_f32_16x16x32_bf16 v[38:41], v[150:153], v[174:177], v[38:41]
	v_mfma_f32_16x16x32_bf16 v[34:37], v[158:161], v[174:177], v[34:37]
	v_mfma_f32_16x16x32_bf16 v[22:25], v[150:153], v[182:185], v[22:25]
	v_mfma_f32_16x16x32_bf16 v[18:21], v[158:161], v[182:185], v[18:21]
	v_mfma_f32_16x16x32_bf16 v[6:9], v[150:153], v[208:211], v[6:9]
	v_mfma_f32_16x16x32_bf16 v[2:5], v[158:161], v[208:211], v[2:5]
	v_mfma_f32_16x16x32_bf16 v[54:57], v[154:157], v[170:173], v[54:57]
	v_mfma_f32_16x16x32_bf16 v[50:53], v[162:165], v[170:173], v[50:53]
	v_mfma_f32_16x16x32_bf16 v[38:41], v[154:157], v[178:181], v[38:41]
	v_mfma_f32_16x16x32_bf16 v[34:37], v[162:165], v[178:181], v[34:37]
	v_mfma_f32_16x16x32_bf16 v[22:25], v[154:157], v[204:207], v[22:25]
	v_mfma_f32_16x16x32_bf16 v[18:21], v[162:165], v[204:207], v[18:21]
	v_mfma_f32_16x16x32_bf16 v[6:9], v[154:157], v[212:215], v[6:9]
	v_mfma_f32_16x16x32_bf16 v[2:5], v[162:165], v[212:215], v[2:5]
	s_barrier
	s_add_u32 s44, s44, 0x100
	s_addc_u32 s45, s45, 0
	s_add_u32 s56, s56, 0x100
	s_addc_u32 s57, s57, 0
	s_cmp_ge_i32 s72, s63
	s_mov_b32 s54, s72
	s_cbranch_scc0 .LBB0_699
	s_movk_i32 s75, 0x2000
	s_mov_b32 s72, 0x10000
	s_mov_b32 s73, 0x12000
	s_mov_b32 s74, 0x14000
	s_mov_b32 s71, 0x3f317217
	s_and_b64 vcc, exec, s[48:49]
	s_cbranch_vccz .LBB0_673

; #define PG8_STAGE(bufoff, gbase, voff) do { _Pragma("unroll") for (int _i = 0; _i < 2; ++_i) \
;         __builtin_amdgcn_global_load_lds((const unsigned*)((const char*)(gbase) + (voff)[_i]), (PG8_LAS unsigned*)(lds + (bufoff) + ldsw + _i * 8192), 16, 0, 0); } while (0)
; #define PG8_LDA(dst, b, h) do { _Pragma("unroll") for (int m = 0; m < 4; ++m) _Pragma("unroll") for (int k = 0; k < 2; ++k) dst[m][k] = *(const PG8_LAS bf16x8*)(lds + PG8_SA(b, h) + aoff + m * 2048 + k * 1024); } while (0)
; #define PG8_LDB(dst, b, h) do { _Pragma("unroll") for (int n = 0; n < 2; ++n) _Pragma("unroll") for (int k = 0; k < 2; ++k) dst[n][k] = *(const PG8_LAS bf16x8*)(lds + PG8_SB(b, h) + boff + n * 2048 + k * 1024); } while (0)
; #define PG8_MMA(ai, bj, At, Bt) do { __builtin_amdgcn_s_setprio(1); _Pragma("unroll") for (int m = 0; m < 4; ++m) _Pragma("unroll") for (int n = 0; n < 2; ++n) _Pragma("unroll") for (int k = 0; k < 2; ++k) \
;         acc[ai][bj][m][n] = __builtin_amdgcn_mfma_f32_16x16x32_bf16(Bt[n][k], At[m][k], acc[ai][bj][m][n], 0, 0, 0); __builtin_amdgcn_s_setprio(0); } while (0)
; #define PG8_WAIT_V(n) asm volatile("s_waitcnt vmcnt(" #n ")" ::: "memory")
; #define PG8_BAR __builtin_amdgcn_s_barrier()
; template <class Epi, class Sched, bool ALIGN_EPI = false, bool SP2 = false>
; __device__ __forceinline__ void gemm_phase(PG8_LAS unsigned char* lds, const Gemm g, const Sched& S, const Epi& E, const int wv) {
;     ...
;         for (int t = 0; t < nt; t += 2) {
;             const bool last = (t == nt - 2);
;             const char* a1 = cA + (size_t)(t + 1) * kstep;
;             const char* a2 = last ? nA : cA + (size_t)(t + 2) * kstep; const char* b2 = last ? nB : cB + (size_t)(t + 2) * kstep;
;             const char* a3 = a2 + kstep; const char* b3 = b2 + kstep;
;             if (last && has_next) S.a_ready(nxt);
;             if constexpr (SP2) {
;             PG8_LDB(B0, 0, 0); PG8_LDB(B1, 0, 1); PG8_SCHED; PG8_LDA(At, 0, 0); PG8_STAGE(PG8_SA(1, 1), a1 + hstepA, voffA);
;             PG8_WAIT_V(8); PG8_WAIT_L(0); PG8_BAR; PG8_MMA(0, 0, At, B0); PG8_MMA(0, 1, At, B1); PG8_BAR; PG8_SCHED;
;             PG8_LDA(At, 0, 1); PG8_STAGE(PG8_SB(0, 0), b2, voffB); PG8_STAGE(PG8_SB(0, 1), b2 + hstepB, voffB); PG8_STAGE(PG8_SA(0, 0), a2, voffA);
;             PG8_WAIT_V(8); PG8_WAIT_L(0); PG8_BAR; PG8_MMA(1, 0, At, B0); PG8_MMA(1, 1, At, B1); PG8_BAR; PG8_SCHED;
.LBB0_809:
	s_add_i32 s52, s46, 2
	s_add_u32 s14, s48, 0x100
	s_addc_u32 s15, s49, 0
	s_add_i32 s53, 0, 0x10000
	s_cmp_eq_u32 s71, s46
	s_cselect_b32 s47, s11, s15
	s_cselect_b32 s46, s13, s14
	s_cselect_b32 s77, s87, s51
	s_cselect_b32 s76, s86, s35
	s_add_i32 s75, 0, 0x14000
	v_add_u32_e32 v150, s53, v208
	v_add_u32_e32 v166, s75, v208
	ds_read_b128 v[138:141], v150
	ds_read_b128 v[142:145], v150 offset:1024
	ds_read_b128 v[146:149], v150 offset:2048
	ds_read_b128 v[150:153], v150 offset:3072
	ds_read_b128 v[154:157], v166
	ds_read_b128 v[158:161], v166 offset:1024
	ds_read_b128 v[162:165], v166 offset:2048
	ds_read_b128 v[166:169], v166 offset:3072
	v_lshl_add_u64 v[190:191], s[48:49], 0, v[182:183]
	s_add_i32 m0, s63, 0xc000
	ds_read_b128 v[194:197], v211
	ds_read_b128 v[198:201], v211 offset:1024
	ds_read_b128 v[202:205], v211 offset:2048
	ds_read_b128 v[214:217], v211 offset:3072
	ds_read_b128 v[228:231], v211 offset:4096
	ds_read_b128 v[232:235], v211 offset:5120
	ds_read_b128 v[236:239], v211 offset:6144
	ds_read_b128 v[240:243], v211 offset:7168
	global_load_lds_dwordx4 v[190:191], off
	v_lshl_add_u64 v[190:191], s[48:49], 0, v[184:185]
	s_add_i32 m0, s63, 0xe000
	s_nop 0
	global_load_lds_dwordx4 v[190:191], off
	s_waitcnt vmcnt(8)
	s_waitcnt lgkmcnt(0)
	s_barrier
	v_mfma_f32_16x16x32_bf16 v[118:121], v[138:141], v[194:197], v[118:121]
	v_mfma_f32_16x16x32_bf16 v[46:49], v[146:149], v[194:197], v[46:49]
	v_mfma_f32_16x16x32_bf16 v[110:113], v[138:141], v[202:205], v[110:113]
	v_mfma_f32_16x16x32_bf16 v[38:41], v[146:149], v[202:205], v[38:41]
	v_mfma_f32_16x16x32_bf16 v[134:137], v[138:141], v[228:231], v[134:137]
	v_mfma_f32_16x16x32_bf16 v[62:65], v[146:149], v[228:231], v[62:65]
	v_mfma_f32_16x16x32_bf16 v[130:133], v[138:141], v[236:239], v[130:133]
	v_mfma_f32_16x16x32_bf16 v[58:61], v[146:149], v[236:239], v[58:61]
	v_mfma_f32_16x16x32_bf16 v[118:121], v[142:145], v[198:201], v[118:121]
	v_mfma_f32_16x16x32_bf16 v[46:49], v[150:153], v[198:201], v[46:49]
	v_mfma_f32_16x16x32_bf16 v[110:113], v[142:145], v[214:217], v[110:113]
	v_mfma_f32_16x16x32_bf16 v[38:41], v[150:153], v[214:217], v[38:41]
	v_mfma_f32_16x16x32_bf16 v[134:137], v[142:145], v[232:235], v[134:137]
	v_mfma_f32_16x16x32_bf16 v[62:65], v[150:153], v[232:235], v[62:65]
	v_mfma_f32_16x16x32_bf16 v[130:133], v[142:145], v[240:243], v[130:133]
	v_mfma_f32_16x16x32_bf16 v[58:61], v[150:153], v[240:243], v[58:61]
	v_mfma_f32_16x16x32_bf16 v[114:117], v[154:157], v[194:197], v[114:117]
	v_mfma_f32_16x16x32_bf16 v[42:45], v[162:165], v[194:197], v[42:45]
	v_mfma_f32_16x16x32_bf16 v[106:109], v[154:157], v[202:205], v[106:109]
	v_mfma_f32_16x16x32_bf16 v[34:37], v[162:165], v[202:205], v[34:37]
	v_mfma_f32_16x16x32_bf16 v[126:129], v[154:157], v[228:231], v[126:129]
	v_mfma_f32_16x16x32_bf16 v[54:57], v[162:165], v[228:231], v[54:57]
	v_mfma_f32_16x16x32_bf16 v[122:125], v[154:157], v[236:239], v[122:125]
	v_mfma_f32_16x16x32_bf16 v[50:53], v[162:165], v[236:239], v[50:53]
	v_mfma_f32_16x16x32_bf16 v[114:117], v[158:161], v[198:201], v[114:117]
	v_mfma_f32_16x16x32_bf16 v[42:45], v[166:169], v[198:201], v[42:45]
	v_mfma_f32_16x16x32_bf16 v[106:109], v[158:161], v[214:217], v[106:109]
	v_mfma_f32_16x16x32_bf16 v[34:37], v[166:169], v[214:217], v[34:37]
	v_mfma_f32_16x16x32_bf16 v[126:129], v[158:161], v[232:235], v[126:129]
	v_mfma_f32_16x16x32_bf16 v[54:57], v[166:169], v[232:235], v[54:57]
	v_mfma_f32_16x16x32_bf16 v[122:125], v[158:161], v[240:243], v[122:125]
	v_mfma_f32_16x16x32_bf16 v[50:53], v[166:169], v[240:243], v[50:53]
	s_barrier
	s_add_i32 s48, s53, s62
	s_mov_b32 m0, s48
	ds_read_b128 v[194:197], v211 offset:16384
	ds_read_b128 v[198:201], v211 offset:17408
	ds_read_b128 v[202:205], v211 offset:18432
	ds_read_b128 v[214:217], v211 offset:19456
	ds_read_b128 v[228:231], v211 offset:20480
	ds_read_b128 v[232:235], v211 offset:21504
	ds_read_b128 v[236:239], v211 offset:22528
	ds_read_b128 v[240:243], v211 offset:23552
	global_load_lds_dwordx4 v0, s[76:77]
	s_add_i32 m0, s48, 0x2000
	s_add_u32 s48, s76, s16
	s_addc_u32 s49, s77, s17
	s_add_i32 s53, s75, s62
	global_load_lds_dwordx4 v174, s[76:77]
	v_lshl_add_u64 v[218:219], s[48:49], 0, v[0:1]
	s_mov_b32 m0, s53
	v_lshl_add_u64 v[244:245], s[48:49], 0, v[174:175]
	global_load_lds_dwordx4 v[218:219], off
	s_add_i32 m0, s53, 0x2000
	v_lshl_add_u64 v[246:247], s[46:47], 0, v[170:171]
	global_load_lds_dwordx4 v[244:245], off
	s_mov_b32 m0, s63
	v_lshl_add_u64 v[248:249], s[46:47], 0, v[172:173]
	global_load_lds_dwordx4 v[246:247], off
	s_mov_b32 m0, s64
	s_nop 0
	global_load_lds_dwordx4 v[248:249], off
	s_waitcnt vmcnt(8)
	s_waitcnt lgkmcnt(0)
	s_barrier
; #define PG8_STAGE(bufoff, gbase, voff) do { _Pragma("unroll") for (int _i = 0; _i < 2; ++_i) \
;         __builtin_amdgcn_global_load_lds((const unsigned*)((const char*)(gbase) + (voff)[_i]), (PG8_LAS unsigned*)(lds + (bufoff) + ldsw + _i * 8192), 16, 0, 0); } while (0)
; #define PG8_LDA(dst, b, h) do { _Pragma("unroll") for (int m = 0; m < 4; ++m) _Pragma("unroll") for (int k = 0; k < 2; ++k) dst[m][k] = *(const PG8_LAS bf16x8*)(lds + PG8_SA(b, h) + aoff + m * 2048 + k * 1024); } while (0)
; #define PG8_LDB(dst, b, h) do { _Pragma("unroll") for (int n = 0; n < 2; ++n) _Pragma("unroll") for (int k = 0; k < 2; ++k) dst[n][k] = *(const PG8_LAS bf16x8*)(lds + PG8_SB(b, h) + boff + n * 2048 + k * 1024); } while (0)
; #define PG8_MMA(ai, bj, At, Bt) do { __builtin_amdgcn_s_setprio(1); _Pragma("unroll") for (int m = 0; m < 4; ++m) _Pragma("unroll") for (int n = 0; n < 2; ++n) _Pragma("unroll") for (int k = 0; k < 2; ++k) \
;         acc[ai][bj][m][n] = __builtin_amdgcn_mfma_f32_16x16x32_bf16(Bt[n][k], At[m][k], acc[ai][bj][m][n], 0, 0, 0); __builtin_amdgcn_s_setprio(0); } while (0)
; #define PG8_WAIT_V(n) asm volatile("s_waitcnt vmcnt(" #n ")" ::: "memory")
; #define PG8_WAIT_L(n) asm volatile("s_waitcnt lgkmcnt(" #n ")" ::: "memory")
; #define PG8_BAR __builtin_amdgcn_s_barrier()
; #define PG8_SCHED __builtin_amdgcn_sched_barrier(0)
; template <class Epi, class Sched, bool ALIGN_EPI = false, bool SP2 = false>
; __device__ __forceinline__ void gemm_phase(PG8_LAS unsigned char* lds, const Gemm g, const Sched& S, const Epi& E, const int wv) {
;     ...
;             PG8_WAIT_V(8); PG8_WAIT_L(0); PG8_BAR; PG8_MMA(1, 0, At, B0); PG8_MMA(1, 1, At, B1); PG8_BAR; PG8_SCHED;
;             PG8_LDB(B0, 1, 0); PG8_LDB(B1, 1, 1); PG8_SCHED; PG8_LDA(At, 1, 0); PG8_STAGE(PG8_SA(0, 1), a2 + hstepA, voffA);
;             PG8_WAIT_V(8); PG8_WAIT_L(0); PG8_BAR; PG8_MMA(0, 0, At, B0); PG8_MMA(0, 1, At, B1); PG8_BAR; PG8_SCHED;
	v_mfma_f32_16x16x32_bf16 v[86:89], v[138:141], v[194:197], v[86:89]
	v_mfma_f32_16x16x32_bf16 v[14:17], v[146:149], v[194:197], v[14:17]
	v_mfma_f32_16x16x32_bf16 v[70:73], v[138:141], v[202:205], v[70:73]
	v_mfma_f32_16x16x32_bf16 v[6:9], v[146:149], v[202:205], v[6:9]
	v_mfma_f32_16x16x32_bf16 v[102:105], v[138:141], v[228:231], v[102:105]
	v_mfma_f32_16x16x32_bf16 v[30:33], v[146:149], v[228:231], v[30:33]
	v_mfma_f32_16x16x32_bf16 v[98:101], v[138:141], v[236:239], v[98:101]
	v_mfma_f32_16x16x32_bf16 v[26:29], v[146:149], v[236:239], v[26:29]
	v_mfma_f32_16x16x32_bf16 v[86:89], v[142:145], v[198:201], v[86:89]
	v_mfma_f32_16x16x32_bf16 v[14:17], v[150:153], v[198:201], v[14:17]
	v_mfma_f32_16x16x32_bf16 v[70:73], v[142:145], v[214:217], v[70:73]
	v_mfma_f32_16x16x32_bf16 v[6:9], v[150:153], v[214:217], v[6:9]
	v_mfma_f32_16x16x32_bf16 v[102:105], v[142:145], v[232:235], v[102:105]
	v_mfma_f32_16x16x32_bf16 v[30:33], v[150:153], v[232:235], v[30:33]
	v_mfma_f32_16x16x32_bf16 v[98:101], v[142:145], v[240:243], v[98:101]
	v_mfma_f32_16x16x32_bf16 v[26:29], v[150:153], v[240:243], v[26:29]
	v_mfma_f32_16x16x32_bf16 v[82:85], v[154:157], v[194:197], v[82:85]
	v_mfma_f32_16x16x32_bf16 v[10:13], v[162:165], v[194:197], v[10:13]
	v_mfma_f32_16x16x32_bf16 v[66:69], v[154:157], v[202:205], v[66:69]
	v_mfma_f32_16x16x32_bf16 v[2:5], v[162:165], v[202:205], v[2:5]
	v_mfma_f32_16x16x32_bf16 v[94:97], v[154:157], v[228:231], v[94:97]
	v_mfma_f32_16x16x32_bf16 v[22:25], v[162:165], v[228:231], v[22:25]
	v_mfma_f32_16x16x32_bf16 v[90:93], v[154:157], v[236:239], v[90:93]
	v_mfma_f32_16x16x32_bf16 v[18:21], v[162:165], v[236:239], v[18:21]
	v_mfma_f32_16x16x32_bf16 v[82:85], v[158:161], v[198:201], v[82:85]
	v_mfma_f32_16x16x32_bf16 v[10:13], v[166:169], v[198:201], v[10:13]
	v_mfma_f32_16x16x32_bf16 v[66:69], v[158:161], v[214:217], v[66:69]
	v_mfma_f32_16x16x32_bf16 v[2:5], v[166:169], v[214:217], v[2:5]
	v_mfma_f32_16x16x32_bf16 v[94:97], v[158:161], v[232:235], v[94:97]
	v_mfma_f32_16x16x32_bf16 v[22:25], v[166:169], v[232:235], v[22:25]
	v_mfma_f32_16x16x32_bf16 v[90:93], v[158:161], v[240:243], v[90:93]
	v_mfma_f32_16x16x32_bf16 v[18:21], v[166:169], v[240:243], v[18:21]
	s_barrier
	s_add_i32 s48, 0, 0x18000
	s_add_i32 s49, 0, 0x1c000
	v_add_u32_e32 v150, s48, v208
	v_add_u32_e32 v166, s49, v208
	ds_read_b128 v[138:141], v150
	ds_read_b128 v[142:145], v150 offset:1024
	ds_read_b128 v[146:149], v150 offset:2048
	ds_read_b128 v[150:153], v150 offset:3072
	ds_read_b128 v[154:157], v166
	ds_read_b128 v[158:161], v166 offset:1024
	ds_read_b128 v[162:165], v166 offset:2048
	ds_read_b128 v[166:169], v166 offset:3072
	s_add_u32 s46, s46, 0x80000
	s_addc_u32 s47, s47, 0
	s_mov_b32 m0, s65
	ds_read_b128 v[194:197], v211 offset:32768
	ds_read_b128 v[198:201], v211 offset:33792
	ds_read_b128 v[202:205], v211 offset:34816
	ds_read_b128 v[214:217], v211 offset:35840
	ds_read_b128 v[228:231], v211 offset:36864
	ds_read_b128 v[232:235], v211 offset:37888
	ds_read_b128 v[236:239], v211 offset:38912
	ds_read_b128 v[240:243], v211 offset:39936
	global_load_lds_dwordx4 v170, s[46:47]
	s_mov_b32 m0, s66
	s_nop 0
	global_load_lds_dwordx4 v172, s[46:47]
	s_waitcnt vmcnt(8)
	s_waitcnt lgkmcnt(0)
	s_barrier
	v_mfma_f32_16x16x32_bf16 v[118:121], v[138:141], v[194:197], v[118:121]
	v_mfma_f32_16x16x32_bf16 v[46:49], v[146:149], v[194:197], v[46:49]
	v_mfma_f32_16x16x32_bf16 v[110:113], v[138:141], v[202:205], v[110:113]
	v_mfma_f32_16x16x32_bf16 v[38:41], v[146:149], v[202:205], v[38:41]
	v_mfma_f32_16x16x32_bf16 v[134:137], v[138:141], v[228:231], v[134:137]
	v_mfma_f32_16x16x32_bf16 v[62:65], v[146:149], v[228:231], v[62:65]
	v_mfma_f32_16x16x32_bf16 v[130:133], v[138:141], v[236:239], v[130:133]
	v_mfma_f32_16x16x32_bf16 v[58:61], v[146:149], v[236:239], v[58:61]
	v_mfma_f32_16x16x32_bf16 v[118:121], v[142:145], v[198:201], v[118:121]
	v_mfma_f32_16x16x32_bf16 v[46:49], v[150:153], v[198:201], v[46:49]
	v_mfma_f32_16x16x32_bf16 v[110:113], v[142:145], v[214:217], v[110:113]
	v_mfma_f32_16x16x32_bf16 v[38:41], v[150:153], v[214:217], v[38:41]
	v_mfma_f32_16x16x32_bf16 v[134:137], v[142:145], v[232:235], v[134:137]
	v_mfma_f32_16x16x32_bf16 v[62:65], v[150:153], v[232:235], v[62:65]
	v_mfma_f32_16x16x32_bf16 v[130:133], v[142:145], v[240:243], v[130:133]
	v_mfma_f32_16x16x32_bf16 v[58:61], v[150:153], v[240:243], v[58:61]
	v_mfma_f32_16x16x32_bf16 v[114:117], v[154:157], v[194:197], v[114:117]
	v_mfma_f32_16x16x32_bf16 v[42:45], v[162:165], v[194:197], v[42:45]
	v_mfma_f32_16x16x32_bf16 v[106:109], v[154:157], v[202:205], v[106:109]
	v_mfma_f32_16x16x32_bf16 v[34:37], v[162:165], v[202:205], v[34:37]
	v_mfma_f32_16x16x32_bf16 v[126:129], v[154:157], v[228:231], v[126:129]
	v_mfma_f32_16x16x32_bf16 v[54:57], v[162:165], v[228:231], v[54:57]
	v_mfma_f32_16x16x32_bf16 v[122:125], v[154:157], v[236:239], v[122:125]
	v_mfma_f32_16x16x32_bf16 v[50:53], v[162:165], v[236:239], v[50:53]
	v_mfma_f32_16x16x32_bf16 v[114:117], v[158:161], v[198:201], v[114:117]
	v_mfma_f32_16x16x32_bf16 v[42:45], v[166:169], v[198:201], v[42:45]
	v_mfma_f32_16x16x32_bf16 v[106:109], v[158:161], v[214:217], v[106:109]
	v_mfma_f32_16x16x32_bf16 v[34:37], v[166:169], v[214:217], v[34:37]
	v_mfma_f32_16x16x32_bf16 v[126:129], v[158:161], v[232:235], v[126:129]
	v_mfma_f32_16x16x32_bf16 v[54:57], v[166:169], v[232:235], v[54:57]
	v_mfma_f32_16x16x32_bf16 v[122:125], v[158:161], v[240:243], v[122:125]
	v_mfma_f32_16x16x32_bf16 v[50:53], v[166:169], v[240:243], v[50:53]
	s_barrier
; #define PG8_STAGE(bufoff, gbase, voff) do { _Pragma("unroll") for (int _i = 0; _i < 2; ++_i) \
;         __builtin_amdgcn_global_load_lds((const unsigned*)((const char*)(gbase) + (voff)[_i]), (PG8_LAS unsigned*)(lds + (bufoff) + ldsw + _i * 8192), 16, 0, 0); } while (0)
; #define PG8_LDA(dst, b, h) do { _Pragma("unroll") for (int m = 0; m < 4; ++m) _Pragma("unroll") for (int k = 0; k < 2; ++k) dst[m][k] = *(const PG8_LAS bf16x8*)(lds + PG8_SA(b, h) + aoff + m * 2048 + k * 1024); } while (0)
; #define PG8_MMA(ai, bj, At, Bt) do { __builtin_amdgcn_s_setprio(1); _Pragma("unroll") for (int m = 0; m < 4; ++m) _Pragma("unroll") for (int n = 0; n < 2; ++n) _Pragma("unroll") for (int k = 0; k < 2; ++k) \
;         acc[ai][bj][m][n] = __builtin_amdgcn_mfma_f32_16x16x32_bf16(Bt[n][k], At[m][k], acc[ai][bj][m][n], 0, 0, 0); __builtin_amdgcn_s_setprio(0); } while (0)
; #define PG8_WAIT_V(n) asm volatile("s_waitcnt vmcnt(" #n ")" ::: "memory")
; #define PG8_WAIT_L(n) asm volatile("s_waitcnt lgkmcnt(" #n ")" ::: "memory")
; #define PG8_BAR __builtin_amdgcn_s_barrier()
; #define PG8_SCHED __builtin_amdgcn_sched_barrier(0)
; template <class Epi, class Sched, bool ALIGN_EPI = false, bool SP2 = false>
; __device__ __forceinline__ void gemm_phase(PG8_LAS unsigned char* lds, const Gemm g, const Sched& S, const Epi& E, const int wv) {
;     ...
;             PG8_LDA(At, 1, 1); PG8_STAGE(PG8_SB(1, 0), b3, voffB); PG8_STAGE(PG8_SB(1, 1), b3 + hstepB, voffB); PG8_STAGE(PG8_SA(1, 0), a3, voffA);
;             PG8_WAIT_V(8); PG8_WAIT_L(0); PG8_BAR; PG8_MMA(1, 0, At, B0); PG8_MMA(1, 1, At, B1); PG8_BAR; PG8_SCHED;
	s_add_i32 s46, s48, s62
	s_add_i32 m0, s46, 0xffffff80
	ds_read_b128 v[194:197], v211 offset:49152
	ds_read_b128 v[198:201], v211 offset:50176
	ds_read_b128 v[202:205], v211 offset:51200
	ds_read_b128 v[214:217], v211 offset:52224
	ds_read_b128 v[228:231], v211 offset:53248
	ds_read_b128 v[232:235], v211 offset:54272
	ds_read_b128 v[236:239], v211 offset:55296
	ds_read_b128 v[240:243], v211 offset:56320
	global_load_lds_dwordx4 v0, s[76:77] offset:128
	s_add_i32 m0, s46, 0x1f80
	s_add_i32 s46, s49, s62
	global_load_lds_dwordx4 v174, s[76:77] offset:128
	s_add_i32 m0, s46, 0xffffff80
	s_nop 0
	global_load_lds_dwordx4 v[218:219], off offset:128
	s_add_i32 m0, s46, 0x1f80
	s_nop 0
	global_load_lds_dwordx4 v[244:245], off offset:128
	s_add_i32 m0, s69, 0xffffff80
	s_nop 0
	global_load_lds_dwordx4 v[246:247], off offset:128
	s_add_i32 m0, s70, 0xffffff80
	s_nop 0
	global_load_lds_dwordx4 v[248:249], off offset:128
	s_waitcnt vmcnt(8)
	s_waitcnt lgkmcnt(0)
	s_barrier
	v_mfma_f32_16x16x32_bf16 v[86:89], v[138:141], v[194:197], v[86:89]
	v_mfma_f32_16x16x32_bf16 v[14:17], v[146:149], v[194:197], v[14:17]
	v_mfma_f32_16x16x32_bf16 v[70:73], v[138:141], v[202:205], v[70:73]
	v_mfma_f32_16x16x32_bf16 v[6:9], v[146:149], v[202:205], v[6:9]
	v_mfma_f32_16x16x32_bf16 v[102:105], v[138:141], v[228:231], v[102:105]
	v_mfma_f32_16x16x32_bf16 v[30:33], v[146:149], v[228:231], v[30:33]
	v_mfma_f32_16x16x32_bf16 v[98:101], v[138:141], v[236:239], v[98:101]
	v_mfma_f32_16x16x32_bf16 v[26:29], v[146:149], v[236:239], v[26:29]
	v_mfma_f32_16x16x32_bf16 v[86:89], v[142:145], v[198:201], v[86:89]
	v_mfma_f32_16x16x32_bf16 v[14:17], v[150:153], v[198:201], v[14:17]
	v_mfma_f32_16x16x32_bf16 v[70:73], v[142:145], v[214:217], v[70:73]
	v_mfma_f32_16x16x32_bf16 v[6:9], v[150:153], v[214:217], v[6:9]
	v_mfma_f32_16x16x32_bf16 v[102:105], v[142:145], v[232:235], v[102:105]
	v_mfma_f32_16x16x32_bf16 v[30:33], v[150:153], v[232:235], v[30:33]
	v_mfma_f32_16x16x32_bf16 v[98:101], v[142:145], v[240:243], v[98:101]
	v_mfma_f32_16x16x32_bf16 v[26:29], v[150:153], v[240:243], v[26:29]
	v_mfma_f32_16x16x32_bf16 v[82:85], v[154:157], v[194:197], v[82:85]
	v_mfma_f32_16x16x32_bf16 v[10:13], v[162:165], v[194:197], v[10:13]
	v_mfma_f32_16x16x32_bf16 v[66:69], v[154:157], v[202:205], v[66:69]
	v_mfma_f32_16x16x32_bf16 v[2:5], v[162:165], v[202:205], v[2:5]
	v_mfma_f32_16x16x32_bf16 v[94:97], v[154:157], v[228:231], v[94:97]
	v_mfma_f32_16x16x32_bf16 v[22:25], v[162:165], v[228:231], v[22:25]
	v_mfma_f32_16x16x32_bf16 v[90:93], v[154:157], v[236:239], v[90:93]
	v_mfma_f32_16x16x32_bf16 v[18:21], v[162:165], v[236:239], v[18:21]
	v_mfma_f32_16x16x32_bf16 v[82:85], v[158:161], v[198:201], v[82:85]
	v_mfma_f32_16x16x32_bf16 v[10:13], v[166:169], v[198:201], v[10:13]
	v_mfma_f32_16x16x32_bf16 v[66:69], v[158:161], v[214:217], v[66:69]
	v_mfma_f32_16x16x32_bf16 v[2:5], v[166:169], v[214:217], v[2:5]
	v_mfma_f32_16x16x32_bf16 v[94:97], v[158:161], v[232:235], v[94:97]
	v_mfma_f32_16x16x32_bf16 v[22:25], v[166:169], v[232:235], v[22:25]
	v_mfma_f32_16x16x32_bf16 v[90:93], v[158:161], v[240:243], v[90:93]
	v_mfma_f32_16x16x32_bf16 v[18:21], v[166:169], v[240:243], v[18:21]
	s_barrier
	s_add_u32 s35, s35, 0x100
	s_addc_u32 s51, s51, 0
	s_cmp_ge_i32 s52, s67
	s_mov_b64 s[48:49], s[14:15]
	s_mov_b32 s46, s52
	s_cbranch_scc0 .LBB0_809
	s_movk_i32 s75, 0x2000
	s_movk_i32 s76, 0x3000
	s_and_b64 vcc, exec, s[30:31]
	s_cbranch_vccz .LBB0_784

; #define PG8_STAGE(bufoff, gbase, voff) do { _Pragma("unroll") for (int _i = 0; _i < 2; ++_i) \
;         __builtin_amdgcn_global_load_lds((const unsigned*)((const char*)(gbase) + (voff)[_i]), (PG8_LAS unsigned*)(lds + (bufoff) + ldsw + _i * 8192), 16, 0, 0); } while (0)
; #define PG8_LDA(dst, b, h) do { _Pragma("unroll") for (int m = 0; m < 4; ++m) _Pragma("unroll") for (int k = 0; k < 2; ++k) dst[m][k] = *(const PG8_LAS bf16x8*)(lds + PG8_SA(b, h) + aoff + m * 2048 + k * 1024); } while (0)
; #define PG8_LDB(dst, b, h) do { _Pragma("unroll") for (int n = 0; n < 2; ++n) _Pragma("unroll") for (int k = 0; k < 2; ++k) dst[n][k] = *(const PG8_LAS bf16x8*)(lds + PG8_SB(b, h) + boff + n * 2048 + k * 1024); } while (0)
; #define PG8_MMA(ai, bj, At, Bt) do { __builtin_amdgcn_s_setprio(1); _Pragma("unroll") for (int m = 0; m < 4; ++m) _Pragma("unroll") for (int n = 0; n < 2; ++n) _Pragma("unroll") for (int k = 0; k < 2; ++k) \
;         acc[ai][bj][m][n] = __builtin_amdgcn_mfma_f32_16x16x32_bf16(Bt[n][k], At[m][k], acc[ai][bj][m][n], 0, 0, 0); __builtin_amdgcn_s_setprio(0); } while (0)
; #define PG8_WAIT_V(n) asm volatile("s_waitcnt vmcnt(" #n ")" ::: "memory")
; #define PG8_WAIT_L(n) asm volatile("s_waitcnt lgkmcnt(" #n ")" ::: "memory")
; template <class Epi, class Sched, bool ALIGN_EPI = false, bool SP2 = false>
; __device__ __forceinline__ void gemm_phase(PG8_LAS unsigned char* lds, const Gemm g, const Sched& S, const Epi& E, const int wv) {
;     ...
;             const bool last = (t == nt - 2);
;             const char* a1 = cA + (size_t)(t + 1) * kstep;
;             const char* a2 = last ? nA : cA + (size_t)(t + 2) * kstep; const char* b2 = last ? nB : cB + (size_t)(t + 2) * kstep;
;             const char* a3 = a2 + kstep; const char* b3 = b2 + kstep;
;             if (last && has_next) S.a_ready(nxt);
;             if constexpr (SP2) {
;             PG8_LDB(B0, 0, 0); PG8_LDB(B1, 0, 1); PG8_SCHED; PG8_LDA(At, 0, 0); PG8_STAGE(PG8_SA(1, 1), a1 + hstepA, voffA);
;             PG8_WAIT_V(8); PG8_WAIT_L(0); PG8_BAR; PG8_MMA(0, 0, At, B0); PG8_MMA(0, 1, At, B1); PG8_BAR; PG8_SCHED;
;             PG8_LDA(At, 0, 1); PG8_STAGE(PG8_SB(0, 0), b2, voffB); PG8_STAGE(PG8_SB(0, 1), b2 + hstepB, voffB); PG8_STAGE(PG8_SA(0, 0), a2, voffA);
;             PG8_WAIT_V(8); PG8_WAIT_L(0); PG8_BAR; PG8_MMA(1, 0, At, B0); PG8_MMA(1, 1, At, B1); PG8_BAR; PG8_SCHED;
.LBB0_990:
	s_add_i32 s67, s44, 2
	s_add_u32 s34, s30, 0x100
	s_addc_u32 s35, s31, 0
	s_add_i32 s70, 0, 0x10000
	s_cmp_eq_u32 s59, s44
	s_cselect_b32 s45, s13, s35
	s_cselect_b32 s44, s12, s34
	s_cselect_b32 s69, s15, s66
	s_cselect_b32 s68, s14, s65
	s_add_i32 s71, 0, 0x14000
	v_add_u32_e32 v142, s70, v230
	v_add_u32_e32 v158, s71, v230
	ds_read_b128 v[114:117], v142
	ds_read_b128 v[126:129], v142 offset:1024
	ds_read_b128 v[138:141], v142 offset:2048
	ds_read_b128 v[142:145], v142 offset:3072
	ds_read_b128 v[146:149], v158
	ds_read_b128 v[150:153], v158 offset:1024
	ds_read_b128 v[154:157], v158 offset:2048
	ds_read_b128 v[158:161], v158 offset:3072
	v_lshl_add_u64 v[190:191], s[30:31], 0, v[200:201]
	s_add_i32 m0, s52, 0xc000
	ds_read_b128 v[162:165], v235
	ds_read_b128 v[166:169], v235 offset:1024
	ds_read_b128 v[170:173], v235 offset:2048
	ds_read_b128 v[174:177], v235 offset:3072
	ds_read_b128 v[178:181], v235 offset:4096
	ds_read_b128 v[182:185], v235 offset:5120
	ds_read_b128 v[204:207], v235 offset:6144
	ds_read_b128 v[208:211], v235 offset:7168
	global_load_lds_dwordx4 v[190:191], off
	v_lshl_add_u64 v[190:191], s[30:31], 0, v[202:203]
	s_add_i32 m0, s52, 0xe000
	s_nop 0
	global_load_lds_dwordx4 v[190:191], off
	s_waitcnt vmcnt(8)
	s_waitcnt lgkmcnt(0)
	s_barrier
	v_mfma_f32_16x16x32_bf16 v[134:137], v[114:117], v[162:165], v[134:137]
	v_mfma_f32_16x16x32_bf16 v[130:133], v[138:141], v[162:165], v[130:133]
	v_mfma_f32_16x16x32_bf16 v[110:113], v[114:117], v[170:173], v[110:113]
	v_mfma_f32_16x16x32_bf16 v[106:109], v[138:141], v[170:173], v[106:109]
	v_mfma_f32_16x16x32_bf16 v[94:97], v[114:117], v[178:181], v[94:97]
	v_mfma_f32_16x16x32_bf16 v[90:93], v[138:141], v[178:181], v[90:93]
	v_mfma_f32_16x16x32_bf16 v[78:81], v[114:117], v[204:207], v[78:81]
	v_mfma_f32_16x16x32_bf16 v[74:77], v[138:141], v[204:207], v[74:77]
	v_mfma_f32_16x16x32_bf16 v[134:137], v[126:129], v[166:169], v[134:137]
	v_mfma_f32_16x16x32_bf16 v[130:133], v[142:145], v[166:169], v[130:133]
	v_mfma_f32_16x16x32_bf16 v[110:113], v[126:129], v[174:177], v[110:113]
	v_mfma_f32_16x16x32_bf16 v[106:109], v[142:145], v[174:177], v[106:109]
	v_mfma_f32_16x16x32_bf16 v[94:97], v[126:129], v[182:185], v[94:97]
	v_mfma_f32_16x16x32_bf16 v[90:93], v[142:145], v[182:185], v[90:93]
	v_mfma_f32_16x16x32_bf16 v[78:81], v[126:129], v[208:211], v[78:81]
	v_mfma_f32_16x16x32_bf16 v[74:77], v[142:145], v[208:211], v[74:77]
	v_mfma_f32_16x16x32_bf16 v[122:125], v[146:149], v[162:165], v[122:125]
	v_mfma_f32_16x16x32_bf16 v[118:121], v[154:157], v[162:165], v[118:121]
	v_mfma_f32_16x16x32_bf16 v[102:105], v[146:149], v[170:173], v[102:105]
	v_mfma_f32_16x16x32_bf16 v[98:101], v[154:157], v[170:173], v[98:101]
	v_mfma_f32_16x16x32_bf16 v[86:89], v[146:149], v[178:181], v[86:89]
	v_mfma_f32_16x16x32_bf16 v[82:85], v[154:157], v[178:181], v[82:85]
	v_mfma_f32_16x16x32_bf16 v[70:73], v[146:149], v[204:207], v[70:73]
	v_mfma_f32_16x16x32_bf16 v[66:69], v[154:157], v[204:207], v[66:69]
	v_mfma_f32_16x16x32_bf16 v[122:125], v[150:153], v[166:169], v[122:125]
	v_mfma_f32_16x16x32_bf16 v[118:121], v[158:161], v[166:169], v[118:121]
	v_mfma_f32_16x16x32_bf16 v[102:105], v[150:153], v[174:177], v[102:105]
	v_mfma_f32_16x16x32_bf16 v[98:101], v[158:161], v[174:177], v[98:101]
	v_mfma_f32_16x16x32_bf16 v[86:89], v[150:153], v[182:185], v[86:89]
	v_mfma_f32_16x16x32_bf16 v[82:85], v[158:161], v[182:185], v[82:85]
	v_mfma_f32_16x16x32_bf16 v[70:73], v[150:153], v[208:211], v[70:73]
	v_mfma_f32_16x16x32_bf16 v[66:69], v[158:161], v[208:211], v[66:69]
	s_barrier
	s_add_i32 s30, s70, s47
	v_lshl_add_u64 v[190:191], s[68:69], 0, v[0:1]
	s_mov_b32 m0, s30
	ds_read_b128 v[162:165], v235 offset:16384
	ds_read_b128 v[166:169], v235 offset:17408
	ds_read_b128 v[170:173], v235 offset:18432
	ds_read_b128 v[174:177], v235 offset:19456
	ds_read_b128 v[178:181], v235 offset:20480
	ds_read_b128 v[182:185], v235 offset:21504
	ds_read_b128 v[204:207], v235 offset:22528
	ds_read_b128 v[208:211], v235 offset:23552
	global_load_lds_dwordx4 v[190:191], off
	s_add_i32 m0, s30, 0x2000
	s_add_u32 s30, s68, s2
	v_lshl_add_u64 v[192:193], s[68:69], 0, v[198:199]
	s_addc_u32 s31, s69, s3
	s_add_i32 s68, s71, s47
	global_load_lds_dwordx4 v[192:193], off
	v_lshl_add_u64 v[212:213], s[30:31], 0, v[0:1]
	s_mov_b32 m0, s68
	v_lshl_add_u64 v[214:215], s[30:31], 0, v[198:199]
	global_load_lds_dwordx4 v[212:213], off
	s_add_i32 m0, s68, 0x2000
	global_load_lds_dwordx4 v[214:215], off
	s_mov_b32 m0, s52
	global_load_lds_dwordx4 v194, s[44:45]
	s_mov_b32 m0, s53
	s_nop 0
	global_load_lds_dwordx4 v196, s[44:45]
	s_waitcnt vmcnt(8)
	s_waitcnt lgkmcnt(0)
	s_barrier
; #define PG8_STAGE(bufoff, gbase, voff) do { _Pragma("unroll") for (int _i = 0; _i < 2; ++_i) \
;         __builtin_amdgcn_global_load_lds((const unsigned*)((const char*)(gbase) + (voff)[_i]), (PG8_LAS unsigned*)(lds + (bufoff) + ldsw + _i * 8192), 16, 0, 0); } while (0)
; #define PG8_LDA(dst, b, h) do { _Pragma("unroll") for (int m = 0; m < 4; ++m) _Pragma("unroll") for (int k = 0; k < 2; ++k) dst[m][k] = *(const PG8_LAS bf16x8*)(lds + PG8_SA(b, h) + aoff + m * 2048 + k * 1024); } while (0)
; #define PG8_LDB(dst, b, h) do { _Pragma("unroll") for (int n = 0; n < 2; ++n) _Pragma("unroll") for (int k = 0; k < 2; ++k) dst[n][k] = *(const PG8_LAS bf16x8*)(lds + PG8_SB(b, h) + boff + n * 2048 + k * 1024); } while (0)
; #define PG8_MMA(ai, bj, At, Bt) do { __builtin_amdgcn_s_setprio(1); _Pragma("unroll") for (int m = 0; m < 4; ++m) _Pragma("unroll") for (int n = 0; n < 2; ++n) _Pragma("unroll") for (int k = 0; k < 2; ++k) \
;         acc[ai][bj][m][n] = __builtin_amdgcn_mfma_f32_16x16x32_bf16(Bt[n][k], At[m][k], acc[ai][bj][m][n], 0, 0, 0); __builtin_amdgcn_s_setprio(0); } while (0)
; #define PG8_WAIT_V(n) asm volatile("s_waitcnt vmcnt(" #n ")" ::: "memory")
; #define PG8_WAIT_L(n) asm volatile("s_waitcnt lgkmcnt(" #n ")" ::: "memory")
; #define PG8_BAR __builtin_amdgcn_s_barrier()
; #define PG8_SCHED __builtin_amdgcn_sched_barrier(0)
; template <class Epi, class Sched, bool ALIGN_EPI = false, bool SP2 = false>
; __device__ __forceinline__ void gemm_phase(PG8_LAS unsigned char* lds, const Gemm g, const Sched& S, const Epi& E, const int wv) {
;     ...
;             PG8_WAIT_V(8); PG8_WAIT_L(0); PG8_BAR; PG8_MMA(1, 0, At, B0); PG8_MMA(1, 1, At, B1); PG8_BAR; PG8_SCHED;
;             PG8_LDB(B0, 1, 0); PG8_LDB(B1, 1, 1); PG8_SCHED; PG8_LDA(At, 1, 0); PG8_STAGE(PG8_SA(0, 1), a2 + hstepA, voffA);
;             PG8_WAIT_V(8); PG8_WAIT_L(0); PG8_BAR; PG8_MMA(0, 0, At, B0); PG8_MMA(0, 1, At, B1); PG8_BAR; PG8_SCHED;
	v_mfma_f32_16x16x32_bf16 v[62:65], v[114:117], v[162:165], v[62:65]
	v_mfma_f32_16x16x32_bf16 v[58:61], v[138:141], v[162:165], v[58:61]
	v_mfma_f32_16x16x32_bf16 v[46:49], v[114:117], v[170:173], v[46:49]
	v_mfma_f32_16x16x32_bf16 v[42:45], v[138:141], v[170:173], v[42:45]
	v_mfma_f32_16x16x32_bf16 v[30:33], v[114:117], v[178:181], v[30:33]
	v_mfma_f32_16x16x32_bf16 v[26:29], v[138:141], v[178:181], v[26:29]
	v_mfma_f32_16x16x32_bf16 v[14:17], v[114:117], v[204:207], v[14:17]
	v_mfma_f32_16x16x32_bf16 v[10:13], v[138:141], v[204:207], v[10:13]
	v_mfma_f32_16x16x32_bf16 v[62:65], v[126:129], v[166:169], v[62:65]
	v_mfma_f32_16x16x32_bf16 v[58:61], v[142:145], v[166:169], v[58:61]
	v_mfma_f32_16x16x32_bf16 v[46:49], v[126:129], v[174:177], v[46:49]
	v_mfma_f32_16x16x32_bf16 v[42:45], v[142:145], v[174:177], v[42:45]
	v_mfma_f32_16x16x32_bf16 v[30:33], v[126:129], v[182:185], v[30:33]
	v_mfma_f32_16x16x32_bf16 v[26:29], v[142:145], v[182:185], v[26:29]
	v_mfma_f32_16x16x32_bf16 v[14:17], v[126:129], v[208:211], v[14:17]
	v_mfma_f32_16x16x32_bf16 v[10:13], v[142:145], v[208:211], v[10:13]
	v_mfma_f32_16x16x32_bf16 v[54:57], v[146:149], v[162:165], v[54:57]
	v_mfma_f32_16x16x32_bf16 v[50:53], v[154:157], v[162:165], v[50:53]
	v_mfma_f32_16x16x32_bf16 v[38:41], v[146:149], v[170:173], v[38:41]
	v_mfma_f32_16x16x32_bf16 v[34:37], v[154:157], v[170:173], v[34:37]
	v_mfma_f32_16x16x32_bf16 v[22:25], v[146:149], v[178:181], v[22:25]
	v_mfma_f32_16x16x32_bf16 v[18:21], v[154:157], v[178:181], v[18:21]
	v_mfma_f32_16x16x32_bf16 v[6:9], v[146:149], v[204:207], v[6:9]
	v_mfma_f32_16x16x32_bf16 v[2:5], v[154:157], v[204:207], v[2:5]
	v_mfma_f32_16x16x32_bf16 v[54:57], v[150:153], v[166:169], v[54:57]
	v_mfma_f32_16x16x32_bf16 v[50:53], v[158:161], v[166:169], v[50:53]
	v_mfma_f32_16x16x32_bf16 v[38:41], v[150:153], v[174:177], v[38:41]
	v_mfma_f32_16x16x32_bf16 v[34:37], v[158:161], v[174:177], v[34:37]
	v_mfma_f32_16x16x32_bf16 v[22:25], v[150:153], v[182:185], v[22:25]
	v_mfma_f32_16x16x32_bf16 v[18:21], v[158:161], v[182:185], v[18:21]
	v_mfma_f32_16x16x32_bf16 v[6:9], v[150:153], v[208:211], v[6:9]
	v_mfma_f32_16x16x32_bf16 v[2:5], v[158:161], v[208:211], v[2:5]
	s_barrier
	s_add_i32 s68, 0, 0x18000
	s_add_i32 s69, 0, 0x1c000
	v_add_u32_e32 v142, s68, v230
	v_add_u32_e32 v158, s69, v230
	ds_read_b128 v[114:117], v142
	ds_read_b128 v[126:129], v142 offset:1024
	ds_read_b128 v[138:141], v142 offset:2048
	ds_read_b128 v[142:145], v142 offset:3072
	ds_read_b128 v[146:149], v158
	ds_read_b128 v[150:153], v158 offset:1024
	ds_read_b128 v[154:157], v158 offset:2048
	ds_read_b128 v[158:161], v158 offset:3072
	s_add_u32 s30, s44, 0x180000
	s_addc_u32 s31, s45, 0
	s_mov_b32 m0, s54
	ds_read_b128 v[162:165], v235 offset:32768
	ds_read_b128 v[166:169], v235 offset:33792
	ds_read_b128 v[170:173], v235 offset:34816
	ds_read_b128 v[174:177], v235 offset:35840
	ds_read_b128 v[178:181], v235 offset:36864
	ds_read_b128 v[182:185], v235 offset:37888
	ds_read_b128 v[204:207], v235 offset:38912
	ds_read_b128 v[208:211], v235 offset:39936
	global_load_lds_dwordx4 v194, s[30:31]
	s_mov_b32 m0, s55
	s_nop 0
	global_load_lds_dwordx4 v196, s[30:31]
	s_waitcnt vmcnt(8)
	s_waitcnt lgkmcnt(0)
	s_barrier
	v_mfma_f32_16x16x32_bf16 v[134:137], v[114:117], v[162:165], v[134:137]
	v_mfma_f32_16x16x32_bf16 v[130:133], v[138:141], v[162:165], v[130:133]
	v_mfma_f32_16x16x32_bf16 v[110:113], v[114:117], v[170:173], v[110:113]
	v_mfma_f32_16x16x32_bf16 v[106:109], v[138:141], v[170:173], v[106:109]
	v_mfma_f32_16x16x32_bf16 v[94:97], v[114:117], v[178:181], v[94:97]
	v_mfma_f32_16x16x32_bf16 v[90:93], v[138:141], v[178:181], v[90:93]
	v_mfma_f32_16x16x32_bf16 v[78:81], v[114:117], v[204:207], v[78:81]
	v_mfma_f32_16x16x32_bf16 v[74:77], v[138:141], v[204:207], v[74:77]
	v_mfma_f32_16x16x32_bf16 v[134:137], v[126:129], v[166:169], v[134:137]
	v_mfma_f32_16x16x32_bf16 v[130:133], v[142:145], v[166:169], v[130:133]
	v_mfma_f32_16x16x32_bf16 v[110:113], v[126:129], v[174:177], v[110:113]
	v_mfma_f32_16x16x32_bf16 v[106:109], v[142:145], v[174:177], v[106:109]
	v_mfma_f32_16x16x32_bf16 v[94:97], v[126:129], v[182:185], v[94:97]
	v_mfma_f32_16x16x32_bf16 v[90:93], v[142:145], v[182:185], v[90:93]
	v_mfma_f32_16x16x32_bf16 v[78:81], v[126:129], v[208:211], v[78:81]
	v_mfma_f32_16x16x32_bf16 v[74:77], v[142:145], v[208:211], v[74:77]
	v_mfma_f32_16x16x32_bf16 v[122:125], v[146:149], v[162:165], v[122:125]
	v_mfma_f32_16x16x32_bf16 v[118:121], v[154:157], v[162:165], v[118:121]
	v_mfma_f32_16x16x32_bf16 v[102:105], v[146:149], v[170:173], v[102:105]
	v_mfma_f32_16x16x32_bf16 v[98:101], v[154:157], v[170:173], v[98:101]
	v_mfma_f32_16x16x32_bf16 v[86:89], v[146:149], v[178:181], v[86:89]
	v_mfma_f32_16x16x32_bf16 v[82:85], v[154:157], v[178:181], v[82:85]
	v_mfma_f32_16x16x32_bf16 v[70:73], v[146:149], v[204:207], v[70:73]
	v_mfma_f32_16x16x32_bf16 v[66:69], v[154:157], v[204:207], v[66:69]
	v_mfma_f32_16x16x32_bf16 v[122:125], v[150:153], v[166:169], v[122:125]
	v_mfma_f32_16x16x32_bf16 v[118:121], v[158:161], v[166:169], v[118:121]
	v_mfma_f32_16x16x32_bf16 v[102:105], v[150:153], v[174:177], v[102:105]
	v_mfma_f32_16x16x32_bf16 v[98:101], v[158:161], v[174:177], v[98:101]
	v_mfma_f32_16x16x32_bf16 v[86:89], v[150:153], v[182:185], v[86:89]
	v_mfma_f32_16x16x32_bf16 v[82:85], v[158:161], v[182:185], v[82:85]
	v_mfma_f32_16x16x32_bf16 v[70:73], v[150:153], v[208:211], v[70:73]
	v_mfma_f32_16x16x32_bf16 v[66:69], v[158:161], v[208:211], v[66:69]
	s_barrier
; #define PG8_STAGE(bufoff, gbase, voff) do { _Pragma("unroll") for (int _i = 0; _i < 2; ++_i) \
;         __builtin_amdgcn_global_load_lds((const unsigned*)((const char*)(gbase) + (voff)[_i]), (PG8_LAS unsigned*)(lds + (bufoff) + ldsw + _i * 8192), 16, 0, 0); } while (0)
; #define PG8_LDA(dst, b, h) do { _Pragma("unroll") for (int m = 0; m < 4; ++m) _Pragma("unroll") for (int k = 0; k < 2; ++k) dst[m][k] = *(const PG8_LAS bf16x8*)(lds + PG8_SA(b, h) + aoff + m * 2048 + k * 1024); } while (0)
; #define PG8_MMA(ai, bj, At, Bt) do { __builtin_amdgcn_s_setprio(1); _Pragma("unroll") for (int m = 0; m < 4; ++m) _Pragma("unroll") for (int n = 0; n < 2; ++n) _Pragma("unroll") for (int k = 0; k < 2; ++k) \
;         acc[ai][bj][m][n] = __builtin_amdgcn_mfma_f32_16x16x32_bf16(Bt[n][k], At[m][k], acc[ai][bj][m][n], 0, 0, 0); __builtin_amdgcn_s_setprio(0); } while (0)
; #define PG8_WAIT_V(n) asm volatile("s_waitcnt vmcnt(" #n ")" ::: "memory")
; #define PG8_WAIT_L(n) asm volatile("s_waitcnt lgkmcnt(" #n ")" ::: "memory")
; #define PG8_BAR __builtin_amdgcn_s_barrier()
; #define PG8_SCHED __builtin_amdgcn_sched_barrier(0)
; template <class Epi, class Sched, bool ALIGN_EPI = false, bool SP2 = false>
; __device__ __forceinline__ void gemm_phase(PG8_LAS unsigned char* lds, const Gemm g, const Sched& S, const Epi& E, const int wv) {
;     ...
;             PG8_LDA(At, 1, 1); PG8_STAGE(PG8_SB(1, 0), b3, voffB); PG8_STAGE(PG8_SB(1, 1), b3 + hstepB, voffB); PG8_STAGE(PG8_SA(1, 0), a3, voffA);
;             PG8_WAIT_V(8); PG8_WAIT_L(0); PG8_BAR; PG8_MMA(1, 0, At, B0); PG8_MMA(1, 1, At, B1); PG8_BAR; PG8_SCHED;
	s_add_i32 s30, s68, s47
	s_add_i32 m0, s30, 0xffffff80
	ds_read_b128 v[162:165], v235 offset:49152
	ds_read_b128 v[166:169], v235 offset:50176
	ds_read_b128 v[170:173], v235 offset:51200
	ds_read_b128 v[174:177], v235 offset:52224
	ds_read_b128 v[178:181], v235 offset:53248
	ds_read_b128 v[182:185], v235 offset:54272
	ds_read_b128 v[204:207], v235 offset:55296
	ds_read_b128 v[208:211], v235 offset:56320
	global_load_lds_dwordx4 v[190:191], off offset:128
	s_add_i32 m0, s30, 0x1f80
	s_add_i32 s30, s69, s47
	global_load_lds_dwordx4 v[192:193], off offset:128
	s_add_i32 m0, s30, 0xffffff80
	s_nop 0
	global_load_lds_dwordx4 v[212:213], off offset:128
	s_add_i32 m0, s30, 0x1f80
	s_nop 0
	global_load_lds_dwordx4 v[214:215], off offset:128
	s_add_i32 m0, s57, 0xffffff80
	s_nop 0
	global_load_lds_dwordx4 v194, s[44:45] offset:128
	s_add_i32 m0, s58, 0xffffff80
	s_nop 0
	global_load_lds_dwordx4 v196, s[44:45] offset:128
	s_waitcnt vmcnt(8)
	s_waitcnt lgkmcnt(0)
	s_barrier
	v_mfma_f32_16x16x32_bf16 v[62:65], v[114:117], v[162:165], v[62:65]
	v_mfma_f32_16x16x32_bf16 v[58:61], v[138:141], v[162:165], v[58:61]
	v_mfma_f32_16x16x32_bf16 v[46:49], v[114:117], v[170:173], v[46:49]
	v_mfma_f32_16x16x32_bf16 v[42:45], v[138:141], v[170:173], v[42:45]
	v_mfma_f32_16x16x32_bf16 v[30:33], v[114:117], v[178:181], v[30:33]
	v_mfma_f32_16x16x32_bf16 v[26:29], v[138:141], v[178:181], v[26:29]
	v_mfma_f32_16x16x32_bf16 v[14:17], v[114:117], v[204:207], v[14:17]
	v_mfma_f32_16x16x32_bf16 v[10:13], v[138:141], v[204:207], v[10:13]
	v_mfma_f32_16x16x32_bf16 v[62:65], v[126:129], v[166:169], v[62:65]
	v_mfma_f32_16x16x32_bf16 v[58:61], v[142:145], v[166:169], v[58:61]
	v_mfma_f32_16x16x32_bf16 v[46:49], v[126:129], v[174:177], v[46:49]
	v_mfma_f32_16x16x32_bf16 v[42:45], v[142:145], v[174:177], v[42:45]
	v_mfma_f32_16x16x32_bf16 v[30:33], v[126:129], v[182:185], v[30:33]
	v_mfma_f32_16x16x32_bf16 v[26:29], v[142:145], v[182:185], v[26:29]
	v_mfma_f32_16x16x32_bf16 v[14:17], v[126:129], v[208:211], v[14:17]
	v_mfma_f32_16x16x32_bf16 v[10:13], v[142:145], v[208:211], v[10:13]
	v_mfma_f32_16x16x32_bf16 v[54:57], v[146:149], v[162:165], v[54:57]
	v_mfma_f32_16x16x32_bf16 v[50:53], v[154:157], v[162:165], v[50:53]
	v_mfma_f32_16x16x32_bf16 v[38:41], v[146:149], v[170:173], v[38:41]
	v_mfma_f32_16x16x32_bf16 v[34:37], v[154:157], v[170:173], v[34:37]
	v_mfma_f32_16x16x32_bf16 v[22:25], v[146:149], v[178:181], v[22:25]
	v_mfma_f32_16x16x32_bf16 v[18:21], v[154:157], v[178:181], v[18:21]
	v_mfma_f32_16x16x32_bf16 v[6:9], v[146:149], v[204:207], v[6:9]
	v_mfma_f32_16x16x32_bf16 v[2:5], v[154:157], v[204:207], v[2:5]
	v_mfma_f32_16x16x32_bf16 v[54:57], v[150:153], v[166:169], v[54:57]
	v_mfma_f32_16x16x32_bf16 v[50:53], v[158:161], v[166:169], v[50:53]
	v_mfma_f32_16x16x32_bf16 v[38:41], v[150:153], v[174:177], v[38:41]
	v_mfma_f32_16x16x32_bf16 v[34:37], v[158:161], v[174:177], v[34:37]
	v_mfma_f32_16x16x32_bf16 v[22:25], v[150:153], v[182:185], v[22:25]
	v_mfma_f32_16x16x32_bf16 v[18:21], v[158:161], v[182:185], v[18:21]
	v_mfma_f32_16x16x32_bf16 v[6:9], v[150:153], v[208:211], v[6:9]
	v_mfma_f32_16x16x32_bf16 v[2:5], v[158:161], v[208:211], v[2:5]
	s_barrier
	s_add_u32 s65, s65, 0x100
	s_addc_u32 s66, s66, 0
	s_cmp_ge_i32 s67, s56
	s_mov_b64 s[30:31], s[34:35]
	s_mov_b32 s44, s67
	s_cbranch_scc0 .LBB0_990
	s_movk_i32 s68, 0x4000
	s_movk_i32 s69, 0x6000
	s_mov_b32 s70, 0x18000
	s_mov_b32 s71, 0x3f317217
	v_readlane_b32 s67, v255, 30
	s_and_b64 vcc, exec, s[28:29]
	s_cbranch_vccz .LBB0_966

; #define PG8_STAGE(bufoff, gbase, voff) do { _Pragma("unroll") for (int _i = 0; _i < 2; ++_i) \
;         __builtin_amdgcn_global_load_lds((const unsigned*)((const char*)(gbase) + (voff)[_i]), (PG8_LAS unsigned*)(lds + (bufoff) + ldsw + _i * 8192), 16, 0, 0); } while (0)
; #define PG8_LDA(dst, b, h) do { _Pragma("unroll") for (int m = 0; m < 4; ++m) _Pragma("unroll") for (int k = 0; k < 2; ++k) dst[m][k] = *(const PG8_LAS bf16x8*)(lds + PG8_SA(b, h) + aoff + m * 2048 + k * 1024); } while (0)
; #define PG8_LDB(dst, b, h) do { _Pragma("unroll") for (int n = 0; n < 2; ++n) _Pragma("unroll") for (int k = 0; k < 2; ++k) dst[n][k] = *(const PG8_LAS bf16x8*)(lds + PG8_SB(b, h) + boff + n * 2048 + k * 1024); } while (0)
; #define PG8_MMA(ai, bj, At, Bt) do { __builtin_amdgcn_s_setprio(1); _Pragma("unroll") for (int m = 0; m < 4; ++m) _Pragma("unroll") for (int n = 0; n < 2; ++n) _Pragma("unroll") for (int k = 0; k < 2; ++k) \
;         acc[ai][bj][m][n] = __builtin_amdgcn_mfma_f32_16x16x32_bf16(Bt[n][k], At[m][k], acc[ai][bj][m][n], 0, 0, 0); __builtin_amdgcn_s_setprio(0); } while (0)
; #define PG8_WAIT_V(n) asm volatile("s_waitcnt vmcnt(" #n ")" ::: "memory")
; #define PG8_WAIT_L(n) asm volatile("s_waitcnt lgkmcnt(" #n ")" ::: "memory")
; template <class Epi, class Sched, bool ALIGN_EPI = false, bool SP2 = false>
; __device__ __forceinline__ void gemm_phase(PG8_LAS unsigned char* lds, const Gemm g, const Sched& S, const Epi& E, const int wv) {
;     ...
;             const bool last = (t == nt - 2);
;             const char* a1 = cA + (size_t)(t + 1) * kstep;
;             const char* a2 = last ? nA : cA + (size_t)(t + 2) * kstep; const char* b2 = last ? nB : cB + (size_t)(t + 2) * kstep;
;             const char* a3 = a2 + kstep; const char* b3 = b2 + kstep;
;             if (last && has_next) S.a_ready(nxt);
;             if constexpr (SP2) {
;             PG8_LDB(B0, 0, 0); PG8_LDB(B1, 0, 1); PG8_SCHED; PG8_LDA(At, 0, 0); PG8_STAGE(PG8_SA(1, 1), a1 + hstepA, voffA);
;             PG8_WAIT_V(8); PG8_WAIT_L(0); PG8_BAR; PG8_MMA(0, 0, At, B0); PG8_MMA(0, 1, At, B1); PG8_BAR; PG8_SCHED;
;             PG8_LDA(At, 0, 1); PG8_STAGE(PG8_SB(0, 0), b2, voffB); PG8_STAGE(PG8_SB(0, 1), b2 + hstepB, voffB); PG8_STAGE(PG8_SA(0, 0), a2, voffA);
;             PG8_WAIT_V(8); PG8_WAIT_L(0); PG8_BAR; PG8_MMA(1, 0, At, B0); PG8_MMA(1, 1, At, B1); PG8_BAR; PG8_SCHED;
.LBB0_1074:
	s_add_i32 s63, s30, 2
	s_add_u32 s64, s28, 0xfff80080
	s_addc_u32 s31, s29, -1
	s_add_i32 s66, 0, 0x10000
	s_cmp_eq_u32 s57, s30
	s_cselect_b32 s31, s17, s31
	s_cselect_b32 s30, s40, s64
	v_add_u32_e32 v0, s66, v157
	s_cselect_b32 s65, s19, s62
	s_cselect_b32 s64, s18, s41
	s_add_i32 s67, 0, 0x14000
	ds_read_b128 v[164:167], v0
	ds_read_b128 v[168:171], v0 offset:1024
	ds_read_b128 v[172:175], v0 offset:2048
	ds_read_b128 v[176:179], v0 offset:3072
	v_add_u32_e32 v0, s67, v157
	ds_read_b128 v[180:183], v0
	ds_read_b128 v[194:197], v0 offset:1024
	ds_read_b128 v[198:201], v0 offset:2048
	ds_read_b128 v[202:205], v0 offset:3072
	s_add_i32 m0, s47, 0xc000
	ds_read_b128 v[206:209], v163
	ds_read_b128 v[210:213], v163 offset:1024
	ds_read_b128 v[214:217], v163 offset:2048
	ds_read_b128 v[228:231], v163 offset:3072
	ds_read_b128 v[232:235], v163 offset:4096
	ds_read_b128 v[236:239], v163 offset:5120
	ds_read_b128 v[240:243], v163 offset:6144
	ds_read_b128 v[244:247], v163 offset:7168
	global_load_lds_dwordx4 v146, s[28:29]
	s_add_i32 m0, s47, 0xe000
	s_nop 0
	global_load_lds_dwordx4 v148, s[28:29]
	s_waitcnt vmcnt(8)
	s_waitcnt lgkmcnt(0)
	s_barrier
	v_mfma_f32_16x16x32_bf16 v[130:133], v[164:167], v[206:209], v[130:133]
	v_mfma_f32_16x16x32_bf16 v[126:129], v[172:175], v[206:209], v[126:129]
	v_mfma_f32_16x16x32_bf16 v[114:117], v[164:167], v[214:217], v[114:117]
	v_mfma_f32_16x16x32_bf16 v[110:113], v[172:175], v[214:217], v[110:113]
	v_mfma_f32_16x16x32_bf16 v[98:101], v[164:167], v[232:235], v[98:101]
	v_mfma_f32_16x16x32_bf16 v[94:97], v[172:175], v[232:235], v[94:97]
	v_mfma_f32_16x16x32_bf16 v[82:85], v[164:167], v[240:243], v[82:85]
	v_mfma_f32_16x16x32_bf16 v[78:81], v[172:175], v[240:243], v[78:81]
	v_mfma_f32_16x16x32_bf16 v[130:133], v[168:171], v[210:213], v[130:133]
	v_mfma_f32_16x16x32_bf16 v[126:129], v[176:179], v[210:213], v[126:129]
	v_mfma_f32_16x16x32_bf16 v[114:117], v[168:171], v[228:231], v[114:117]
	v_mfma_f32_16x16x32_bf16 v[110:113], v[176:179], v[228:231], v[110:113]
	v_mfma_f32_16x16x32_bf16 v[98:101], v[168:171], v[236:239], v[98:101]
	v_mfma_f32_16x16x32_bf16 v[94:97], v[176:179], v[236:239], v[94:97]
	v_mfma_f32_16x16x32_bf16 v[82:85], v[168:171], v[244:247], v[82:85]
	v_mfma_f32_16x16x32_bf16 v[78:81], v[176:179], v[244:247], v[78:81]
	v_mfma_f32_16x16x32_bf16 v[122:125], v[180:183], v[206:209], v[122:125]
	v_mfma_f32_16x16x32_bf16 v[118:121], v[198:201], v[206:209], v[118:121]
	v_mfma_f32_16x16x32_bf16 v[106:109], v[180:183], v[214:217], v[106:109]
	v_mfma_f32_16x16x32_bf16 v[102:105], v[198:201], v[214:217], v[102:105]
	v_mfma_f32_16x16x32_bf16 v[90:93], v[180:183], v[232:235], v[90:93]
	v_mfma_f32_16x16x32_bf16 v[86:89], v[198:201], v[232:235], v[86:89]
	v_mfma_f32_16x16x32_bf16 v[74:77], v[180:183], v[240:243], v[74:77]
	v_mfma_f32_16x16x32_bf16 v[70:73], v[198:201], v[240:243], v[70:73]
	v_mfma_f32_16x16x32_bf16 v[122:125], v[194:197], v[210:213], v[122:125]
	v_mfma_f32_16x16x32_bf16 v[118:121], v[202:205], v[210:213], v[118:121]
	v_mfma_f32_16x16x32_bf16 v[106:109], v[194:197], v[228:231], v[106:109]
	v_mfma_f32_16x16x32_bf16 v[102:105], v[202:205], v[228:231], v[102:105]
	v_mfma_f32_16x16x32_bf16 v[90:93], v[194:197], v[236:239], v[90:93]
	v_mfma_f32_16x16x32_bf16 v[86:89], v[202:205], v[236:239], v[86:89]
	v_mfma_f32_16x16x32_bf16 v[74:77], v[194:197], v[244:247], v[74:77]
	v_mfma_f32_16x16x32_bf16 v[70:73], v[202:205], v[244:247], v[70:73]
	s_barrier
	s_add_i32 s66, s66, s45
	v_lshl_add_u64 v[150:151], s[64:65], 0, v[138:139]
	s_mov_b32 m0, s66
	ds_read_b128 v[206:209], v163 offset:16384
	ds_read_b128 v[210:213], v163 offset:17408
	ds_read_b128 v[214:217], v163 offset:18432
	ds_read_b128 v[228:231], v163 offset:19456
	ds_read_b128 v[232:235], v163 offset:20480
	ds_read_b128 v[236:239], v163 offset:21504
	ds_read_b128 v[240:243], v163 offset:22528
	ds_read_b128 v[244:247], v163 offset:23552
	global_load_lds_dwordx4 v[150:151], off
	s_add_i32 m0, s66, 0x2000
	v_lshl_add_u64 v[184:185], s[64:65], 0, v[134:135]
	s_add_u32 s64, s64, s0
	s_addc_u32 s65, s65, s1
	s_add_i32 s66, s67, s45
	global_load_lds_dwordx4 v[184:185], off
	v_lshl_add_u64 v[190:191], s[64:65], 0, v[138:139]
	s_mov_b32 m0, s66
	v_lshl_add_u64 v[192:193], s[64:65], 0, v[134:135]
	global_load_lds_dwordx4 v[190:191], off
	s_add_i32 m0, s66, 0x2000
	v_lshl_add_u64 v[218:219], s[30:31], 0, v[140:141]
	global_load_lds_dwordx4 v[192:193], off
	s_mov_b32 m0, s47
	v_lshl_add_u64 v[248:249], s[30:31], 0, v[136:137]
	global_load_lds_dwordx4 v[218:219], off
	s_mov_b32 m0, s48
	s_nop 0
	global_load_lds_dwordx4 v[248:249], off
	s_waitcnt vmcnt(8)
	s_waitcnt lgkmcnt(0)
	s_barrier
; #define PG8_STAGE(bufoff, gbase, voff) do { _Pragma("unroll") for (int _i = 0; _i < 2; ++_i) \
;         __builtin_amdgcn_global_load_lds((const unsigned*)((const char*)(gbase) + (voff)[_i]), (PG8_LAS unsigned*)(lds + (bufoff) + ldsw + _i * 8192), 16, 0, 0); } while (0)
; #define PG8_LDA(dst, b, h) do { _Pragma("unroll") for (int m = 0; m < 4; ++m) _Pragma("unroll") for (int k = 0; k < 2; ++k) dst[m][k] = *(const PG8_LAS bf16x8*)(lds + PG8_SA(b, h) + aoff + m * 2048 + k * 1024); } while (0)
; #define PG8_LDB(dst, b, h) do { _Pragma("unroll") for (int n = 0; n < 2; ++n) _Pragma("unroll") for (int k = 0; k < 2; ++k) dst[n][k] = *(const PG8_LAS bf16x8*)(lds + PG8_SB(b, h) + boff + n * 2048 + k * 1024); } while (0)
; #define PG8_MMA(ai, bj, At, Bt) do { __builtin_amdgcn_s_setprio(1); _Pragma("unroll") for (int m = 0; m < 4; ++m) _Pragma("unroll") for (int n = 0; n < 2; ++n) _Pragma("unroll") for (int k = 0; k < 2; ++k) \
;         acc[ai][bj][m][n] = __builtin_amdgcn_mfma_f32_16x16x32_bf16(Bt[n][k], At[m][k], acc[ai][bj][m][n], 0, 0, 0); __builtin_amdgcn_s_setprio(0); } while (0)
; #define PG8_WAIT_V(n) asm volatile("s_waitcnt vmcnt(" #n ")" ::: "memory")
; #define PG8_WAIT_L(n) asm volatile("s_waitcnt lgkmcnt(" #n ")" ::: "memory")
; #define PG8_BAR __builtin_amdgcn_s_barrier()
; #define PG8_SCHED __builtin_amdgcn_sched_barrier(0)
; template <class Epi, class Sched, bool ALIGN_EPI = false, bool SP2 = false>
; __device__ __forceinline__ void gemm_phase(PG8_LAS unsigned char* lds, const Gemm g, const Sched& S, const Epi& E, const int wv) {
;     ...
;             PG8_WAIT_V(8); PG8_WAIT_L(0); PG8_BAR; PG8_MMA(1, 0, At, B0); PG8_MMA(1, 1, At, B1); PG8_BAR; PG8_SCHED;
;             PG8_LDB(B0, 1, 0); PG8_LDB(B1, 1, 1); PG8_SCHED; PG8_LDA(At, 1, 0); PG8_STAGE(PG8_SA(0, 1), a2 + hstepA, voffA);
;             PG8_WAIT_V(8); PG8_WAIT_L(0); PG8_BAR; PG8_MMA(0, 0, At, B0); PG8_MMA(0, 1, At, B1); PG8_BAR; PG8_SCHED;
	v_mfma_f32_16x16x32_bf16 v[66:69], v[164:167], v[206:209], v[66:69]
	v_mfma_f32_16x16x32_bf16 v[62:65], v[172:175], v[206:209], v[62:65]
	v_mfma_f32_16x16x32_bf16 v[50:53], v[164:167], v[214:217], v[50:53]
	v_mfma_f32_16x16x32_bf16 v[46:49], v[172:175], v[214:217], v[46:49]
	v_mfma_f32_16x16x32_bf16 v[34:37], v[164:167], v[232:235], v[34:37]
	v_mfma_f32_16x16x32_bf16 v[30:33], v[172:175], v[232:235], v[30:33]
	v_mfma_f32_16x16x32_bf16 v[18:21], v[164:167], v[240:243], v[18:21]
	v_mfma_f32_16x16x32_bf16 v[14:17], v[172:175], v[240:243], v[14:17]
	v_mfma_f32_16x16x32_bf16 v[66:69], v[168:171], v[210:213], v[66:69]
	v_mfma_f32_16x16x32_bf16 v[62:65], v[176:179], v[210:213], v[62:65]
	v_mfma_f32_16x16x32_bf16 v[50:53], v[168:171], v[228:231], v[50:53]
	v_mfma_f32_16x16x32_bf16 v[46:49], v[176:179], v[228:231], v[46:49]
	v_mfma_f32_16x16x32_bf16 v[34:37], v[168:171], v[236:239], v[34:37]
	v_mfma_f32_16x16x32_bf16 v[30:33], v[176:179], v[236:239], v[30:33]
	v_mfma_f32_16x16x32_bf16 v[18:21], v[168:171], v[244:247], v[18:21]
	v_mfma_f32_16x16x32_bf16 v[14:17], v[176:179], v[244:247], v[14:17]
	v_mfma_f32_16x16x32_bf16 v[58:61], v[180:183], v[206:209], v[58:61]
	v_mfma_f32_16x16x32_bf16 v[54:57], v[198:201], v[206:209], v[54:57]
	v_mfma_f32_16x16x32_bf16 v[42:45], v[180:183], v[214:217], v[42:45]
	v_mfma_f32_16x16x32_bf16 v[38:41], v[198:201], v[214:217], v[38:41]
	v_mfma_f32_16x16x32_bf16 v[26:29], v[180:183], v[232:235], v[26:29]
	v_mfma_f32_16x16x32_bf16 v[22:25], v[198:201], v[232:235], v[22:25]
	v_mfma_f32_16x16x32_bf16 v[10:13], v[180:183], v[240:243], v[10:13]
	v_mfma_f32_16x16x32_bf16 v[6:9], v[198:201], v[240:243], v[6:9]
	v_mfma_f32_16x16x32_bf16 v[58:61], v[194:197], v[210:213], v[58:61]
	v_mfma_f32_16x16x32_bf16 v[54:57], v[202:205], v[210:213], v[54:57]
	v_mfma_f32_16x16x32_bf16 v[42:45], v[194:197], v[228:231], v[42:45]
	v_mfma_f32_16x16x32_bf16 v[38:41], v[202:205], v[228:231], v[38:41]
	v_mfma_f32_16x16x32_bf16 v[26:29], v[194:197], v[236:239], v[26:29]
	v_mfma_f32_16x16x32_bf16 v[22:25], v[202:205], v[236:239], v[22:25]
	v_mfma_f32_16x16x32_bf16 v[10:13], v[194:197], v[244:247], v[10:13]
	v_mfma_f32_16x16x32_bf16 v[6:9], v[202:205], v[244:247], v[6:9]
	s_barrier
	s_add_i32 s64, 0, 0x18000
	v_add_u32_e32 v0, s64, v157
	s_add_i32 s65, 0, 0x1c000
	ds_read_b128 v[164:167], v0
	ds_read_b128 v[168:171], v0 offset:1024
	ds_read_b128 v[172:175], v0 offset:2048
	ds_read_b128 v[176:179], v0 offset:3072
	v_add_u32_e32 v0, s65, v157
	ds_read_b128 v[180:183], v0
	ds_read_b128 v[194:197], v0 offset:1024
	ds_read_b128 v[198:201], v0 offset:2048
	ds_read_b128 v[202:205], v0 offset:3072
	s_add_u32 s30, s30, 0x80000
	s_addc_u32 s31, s31, 0
	s_mov_b32 m0, s49
	ds_read_b128 v[206:209], v163 offset:32768
	ds_read_b128 v[210:213], v163 offset:33792
	ds_read_b128 v[214:217], v163 offset:34816
	ds_read_b128 v[228:231], v163 offset:35840
	ds_read_b128 v[232:235], v163 offset:36864
	ds_read_b128 v[236:239], v163 offset:37888
	ds_read_b128 v[240:243], v163 offset:38912
	ds_read_b128 v[244:247], v163 offset:39936
	global_load_lds_dwordx4 v140, s[30:31]
	s_mov_b32 m0, s50
	s_nop 0
	global_load_lds_dwordx4 v136, s[30:31]
	s_waitcnt vmcnt(8)
	s_waitcnt lgkmcnt(0)
	s_barrier
	v_mfma_f32_16x16x32_bf16 v[130:133], v[164:167], v[206:209], v[130:133]
	v_mfma_f32_16x16x32_bf16 v[126:129], v[172:175], v[206:209], v[126:129]
	v_mfma_f32_16x16x32_bf16 v[114:117], v[164:167], v[214:217], v[114:117]
	v_mfma_f32_16x16x32_bf16 v[110:113], v[172:175], v[214:217], v[110:113]
	v_mfma_f32_16x16x32_bf16 v[98:101], v[164:167], v[232:235], v[98:101]
	v_mfma_f32_16x16x32_bf16 v[94:97], v[172:175], v[232:235], v[94:97]
	v_mfma_f32_16x16x32_bf16 v[82:85], v[164:167], v[240:243], v[82:85]
	v_mfma_f32_16x16x32_bf16 v[78:81], v[172:175], v[240:243], v[78:81]
	v_mfma_f32_16x16x32_bf16 v[130:133], v[168:171], v[210:213], v[130:133]
	v_mfma_f32_16x16x32_bf16 v[126:129], v[176:179], v[210:213], v[126:129]
	v_mfma_f32_16x16x32_bf16 v[114:117], v[168:171], v[228:231], v[114:117]
	v_mfma_f32_16x16x32_bf16 v[110:113], v[176:179], v[228:231], v[110:113]
	v_mfma_f32_16x16x32_bf16 v[98:101], v[168:171], v[236:239], v[98:101]
	v_mfma_f32_16x16x32_bf16 v[94:97], v[176:179], v[236:239], v[94:97]
	v_mfma_f32_16x16x32_bf16 v[82:85], v[168:171], v[244:247], v[82:85]
	v_mfma_f32_16x16x32_bf16 v[78:81], v[176:179], v[244:247], v[78:81]
	v_mfma_f32_16x16x32_bf16 v[122:125], v[180:183], v[206:209], v[122:125]
	v_mfma_f32_16x16x32_bf16 v[118:121], v[198:201], v[206:209], v[118:121]
	v_mfma_f32_16x16x32_bf16 v[106:109], v[180:183], v[214:217], v[106:109]
	v_mfma_f32_16x16x32_bf16 v[102:105], v[198:201], v[214:217], v[102:105]
	v_mfma_f32_16x16x32_bf16 v[90:93], v[180:183], v[232:235], v[90:93]
	v_mfma_f32_16x16x32_bf16 v[86:89], v[198:201], v[232:235], v[86:89]
	v_mfma_f32_16x16x32_bf16 v[74:77], v[180:183], v[240:243], v[74:77]
	v_mfma_f32_16x16x32_bf16 v[70:73], v[198:201], v[240:243], v[70:73]
	v_mfma_f32_16x16x32_bf16 v[122:125], v[194:197], v[210:213], v[122:125]
	v_mfma_f32_16x16x32_bf16 v[118:121], v[202:205], v[210:213], v[118:121]
	v_mfma_f32_16x16x32_bf16 v[106:109], v[194:197], v[228:231], v[106:109]
	v_mfma_f32_16x16x32_bf16 v[102:105], v[202:205], v[228:231], v[102:105]
	v_mfma_f32_16x16x32_bf16 v[90:93], v[194:197], v[236:239], v[90:93]
	v_mfma_f32_16x16x32_bf16 v[86:89], v[202:205], v[236:239], v[86:89]
	v_mfma_f32_16x16x32_bf16 v[74:77], v[194:197], v[244:247], v[74:77]
	v_mfma_f32_16x16x32_bf16 v[70:73], v[202:205], v[244:247], v[70:73]
	s_barrier
; #define PG8_STAGE(bufoff, gbase, voff) do { _Pragma("unroll") for (int _i = 0; _i < 2; ++_i) \
;         __builtin_amdgcn_global_load_lds((const unsigned*)((const char*)(gbase) + (voff)[_i]), (PG8_LAS unsigned*)(lds + (bufoff) + ldsw + _i * 8192), 16, 0, 0); } while (0)
; #define PG8_LDA(dst, b, h) do { _Pragma("unroll") for (int m = 0; m < 4; ++m) _Pragma("unroll") for (int k = 0; k < 2; ++k) dst[m][k] = *(const PG8_LAS bf16x8*)(lds + PG8_SA(b, h) + aoff + m * 2048 + k * 1024); } while (0)
; #define PG8_MMA(ai, bj, At, Bt) do { __builtin_amdgcn_s_setprio(1); _Pragma("unroll") for (int m = 0; m < 4; ++m) _Pragma("unroll") for (int n = 0; n < 2; ++n) _Pragma("unroll") for (int k = 0; k < 2; ++k) \
;         acc[ai][bj][m][n] = __builtin_amdgcn_mfma_f32_16x16x32_bf16(Bt[n][k], At[m][k], acc[ai][bj][m][n], 0, 0, 0); __builtin_amdgcn_s_setprio(0); } while (0)
; #define PG8_WAIT_V(n) asm volatile("s_waitcnt vmcnt(" #n ")" ::: "memory")
; #define PG8_WAIT_L(n) asm volatile("s_waitcnt lgkmcnt(" #n ")" ::: "memory")
; #define PG8_BAR __builtin_amdgcn_s_barrier()
; #define PG8_SCHED __builtin_amdgcn_sched_barrier(0)
; template <class Epi, class Sched, bool ALIGN_EPI = false, bool SP2 = false>
; __device__ __forceinline__ void gemm_phase(PG8_LAS unsigned char* lds, const Gemm g, const Sched& S, const Epi& E, const int wv) {
;     ...
;             PG8_LDA(At, 1, 1); PG8_STAGE(PG8_SB(1, 0), b3, voffB); PG8_STAGE(PG8_SB(1, 1), b3 + hstepB, voffB); PG8_STAGE(PG8_SA(1, 0), a3, voffA);
;             PG8_WAIT_V(8); PG8_WAIT_L(0); PG8_BAR; PG8_MMA(1, 0, At, B0); PG8_MMA(1, 1, At, B1); PG8_BAR; PG8_SCHED;
	s_add_i32 s30, s64, s45
	s_add_i32 m0, s30, 0xffffff80
	ds_read_b128 v[206:209], v163 offset:49152
	ds_read_b128 v[210:213], v163 offset:50176
	ds_read_b128 v[214:217], v163 offset:51200
	ds_read_b128 v[228:231], v163 offset:52224
	ds_read_b128 v[232:235], v163 offset:53248
	ds_read_b128 v[236:239], v163 offset:54272
	ds_read_b128 v[240:243], v163 offset:55296
	ds_read_b128 v[244:247], v163 offset:56320
	global_load_lds_dwordx4 v[150:151], off offset:128
	s_add_i32 m0, s30, 0x1f80
	s_add_i32 s30, s65, s45
	global_load_lds_dwordx4 v[184:185], off offset:128
	s_add_i32 m0, s30, 0xffffff80
	s_nop 0
	global_load_lds_dwordx4 v[190:191], off offset:128
	s_add_i32 m0, s30, 0x1f80
	s_nop 0
	global_load_lds_dwordx4 v[192:193], off offset:128
	s_add_i32 m0, s53, 0xffffff80
	s_nop 0
	global_load_lds_dwordx4 v[218:219], off offset:128
	s_add_i32 m0, s54, 0xffffff80
	s_nop 0
	global_load_lds_dwordx4 v[248:249], off offset:128
	s_waitcnt vmcnt(8)
	s_waitcnt lgkmcnt(0)
	s_barrier
	v_mfma_f32_16x16x32_bf16 v[66:69], v[164:167], v[206:209], v[66:69]
	v_mfma_f32_16x16x32_bf16 v[62:65], v[172:175], v[206:209], v[62:65]
	v_mfma_f32_16x16x32_bf16 v[50:53], v[164:167], v[214:217], v[50:53]
	v_mfma_f32_16x16x32_bf16 v[46:49], v[172:175], v[214:217], v[46:49]
	v_mfma_f32_16x16x32_bf16 v[34:37], v[164:167], v[232:235], v[34:37]
	v_mfma_f32_16x16x32_bf16 v[30:33], v[172:175], v[232:235], v[30:33]
	v_mfma_f32_16x16x32_bf16 v[18:21], v[164:167], v[240:243], v[18:21]
	v_mfma_f32_16x16x32_bf16 v[14:17], v[172:175], v[240:243], v[14:17]
	v_mfma_f32_16x16x32_bf16 v[66:69], v[168:171], v[210:213], v[66:69]
	v_mfma_f32_16x16x32_bf16 v[62:65], v[176:179], v[210:213], v[62:65]
	v_mfma_f32_16x16x32_bf16 v[50:53], v[168:171], v[228:231], v[50:53]
	v_mfma_f32_16x16x32_bf16 v[46:49], v[176:179], v[228:231], v[46:49]
	v_mfma_f32_16x16x32_bf16 v[34:37], v[168:171], v[236:239], v[34:37]
	v_mfma_f32_16x16x32_bf16 v[30:33], v[176:179], v[236:239], v[30:33]
	v_mfma_f32_16x16x32_bf16 v[18:21], v[168:171], v[244:247], v[18:21]
	v_mfma_f32_16x16x32_bf16 v[14:17], v[176:179], v[244:247], v[14:17]
	v_mfma_f32_16x16x32_bf16 v[58:61], v[180:183], v[206:209], v[58:61]
	v_mfma_f32_16x16x32_bf16 v[54:57], v[198:201], v[206:209], v[54:57]
	v_mfma_f32_16x16x32_bf16 v[42:45], v[180:183], v[214:217], v[42:45]
	v_mfma_f32_16x16x32_bf16 v[38:41], v[198:201], v[214:217], v[38:41]
	v_mfma_f32_16x16x32_bf16 v[26:29], v[180:183], v[232:235], v[26:29]
	v_mfma_f32_16x16x32_bf16 v[22:25], v[198:201], v[232:235], v[22:25]
	v_mfma_f32_16x16x32_bf16 v[10:13], v[180:183], v[240:243], v[10:13]
	v_mfma_f32_16x16x32_bf16 v[6:9], v[198:201], v[240:243], v[6:9]
	v_mfma_f32_16x16x32_bf16 v[58:61], v[194:197], v[210:213], v[58:61]
	v_mfma_f32_16x16x32_bf16 v[54:57], v[202:205], v[210:213], v[54:57]
	v_mfma_f32_16x16x32_bf16 v[42:45], v[194:197], v[228:231], v[42:45]
	v_mfma_f32_16x16x32_bf16 v[38:41], v[202:205], v[228:231], v[38:41]
	v_mfma_f32_16x16x32_bf16 v[26:29], v[194:197], v[236:239], v[26:29]
	v_mfma_f32_16x16x32_bf16 v[22:25], v[202:205], v[236:239], v[22:25]
	v_mfma_f32_16x16x32_bf16 v[10:13], v[194:197], v[244:247], v[10:13]
	v_mfma_f32_16x16x32_bf16 v[6:9], v[202:205], v[244:247], v[6:9]
	s_barrier
	s_add_u32 s28, s28, 0x100
	s_addc_u32 s29, s29, 0
	s_add_u32 s41, s41, 0x100
	s_addc_u32 s62, s62, 0
	s_cmp_ge_i32 s63, s55
	s_mov_b32 s30, s63
	s_cbranch_scc0 .LBB0_1074
	v_readlane_b32 s67, v255, 30

; #define PG8_STAGE(bufoff, gbase, voff) do { _Pragma("unroll") for (int _i = 0; _i < 2; ++_i) \
;         __builtin_amdgcn_global_load_lds((const unsigned*)((const char*)(gbase) + (voff)[_i]), (PG8_LAS unsigned*)(lds + (bufoff) + ldsw + _i * 8192), 16, 0, 0); } while (0)
; #define PG8_LDA(dst, b, h) do { _Pragma("unroll") for (int m = 0; m < 4; ++m) _Pragma("unroll") for (int k = 0; k < 2; ++k) dst[m][k] = *(const PG8_LAS bf16x8*)(lds + PG8_SA(b, h) + aoff + m * 2048 + k * 1024); } while (0)
; #define PG8_LDB(dst, b, h) do { _Pragma("unroll") for (int n = 0; n < 2; ++n) _Pragma("unroll") for (int k = 0; k < 2; ++k) dst[n][k] = *(const PG8_LAS bf16x8*)(lds + PG8_SB(b, h) + boff + n * 2048 + k * 1024); } while (0)
; #define PG8_MMA(ai, bj, At, Bt) do { __builtin_amdgcn_s_setprio(1); _Pragma("unroll") for (int m = 0; m < 4; ++m) _Pragma("unroll") for (int n = 0; n < 2; ++n) _Pragma("unroll") for (int k = 0; k < 2; ++k) \
;         acc[ai][bj][m][n] = __builtin_amdgcn_mfma_f32_16x16x32_bf16(Bt[n][k], At[m][k], acc[ai][bj][m][n], 0, 0, 0); __builtin_amdgcn_s_setprio(0); } while (0)
; #define PG8_WAIT_V(n) asm volatile("s_waitcnt vmcnt(" #n ")" ::: "memory")
; #define PG8_WAIT_L(n) asm volatile("s_waitcnt lgkmcnt(" #n ")" ::: "memory")
; template <class Epi, class Sched, bool ALIGN_EPI = false, bool SP2 = false>
; __device__ __forceinline__ void gemm_phase(PG8_LAS unsigned char* lds, const Gemm g, const Sched& S, const Epi& E, const int wv) {
;     ...
;             const bool last = (t == nt - 2);
;             const char* a1 = cA + (size_t)(t + 1) * kstep;
;             const char* a2 = last ? nA : cA + (size_t)(t + 2) * kstep; const char* b2 = last ? nB : cB + (size_t)(t + 2) * kstep;
;             const char* a3 = a2 + kstep; const char* b3 = b2 + kstep;
;             if (last && has_next) S.a_ready(nxt);
;             if constexpr (SP2) {
;             PG8_LDB(B0, 0, 0); PG8_LDB(B1, 0, 1); PG8_SCHED; PG8_LDA(At, 0, 0); PG8_STAGE(PG8_SA(1, 1), a1 + hstepA, voffA);
;             PG8_WAIT_V(8); PG8_WAIT_L(0); PG8_BAR; PG8_MMA(0, 0, At, B0); PG8_MMA(0, 1, At, B1); PG8_BAR; PG8_SCHED;
;             PG8_LDA(At, 0, 1); PG8_STAGE(PG8_SB(0, 0), b2, voffB); PG8_STAGE(PG8_SB(0, 1), b2 + hstepB, voffB); PG8_STAGE(PG8_SA(0, 0), a2, voffA);
;             PG8_WAIT_V(8); PG8_WAIT_L(0); PG8_BAR; PG8_MMA(1, 0, At, B0); PG8_MMA(1, 1, At, B1); PG8_BAR; PG8_SCHED;
.LBB0_1385:
	s_add_i32 s70, s52, 2
	s_add_u32 s71, s44, 0xfffc0080
	s_addc_u32 s53, s45, -1
	s_add_i32 s74, 0, 0x10000
	s_cmp_eq_u32 s65, s52
	s_cselect_b32 s53, s13, s53
	s_cselect_b32 s52, s19, s71
	s_cselect_b32 s73, s15, s55
	s_cselect_b32 s72, s14, s54
	s_add_i32 s71, 0, 0x14000
	v_add_u32_e32 v142, s74, v230
	v_add_u32_e32 v158, s71, v230
	ds_read_b128 v[114:117], v142
	ds_read_b128 v[126:129], v142 offset:1024
	ds_read_b128 v[138:141], v142 offset:2048
	ds_read_b128 v[142:145], v142 offset:3072
	ds_read_b128 v[146:149], v158
	ds_read_b128 v[150:153], v158 offset:1024
	ds_read_b128 v[154:157], v158 offset:2048
	ds_read_b128 v[158:161], v158 offset:3072
	s_add_i32 m0, s51, 0xc000
	ds_read_b128 v[162:165], v235
	ds_read_b128 v[166:169], v235 offset:1024
	ds_read_b128 v[170:173], v235 offset:2048
	ds_read_b128 v[174:177], v235 offset:3072
	ds_read_b128 v[178:181], v235 offset:4096
	ds_read_b128 v[182:185], v235 offset:5120
	ds_read_b128 v[204:207], v235 offset:6144
	ds_read_b128 v[208:211], v235 offset:7168
	global_load_lds_dwordx4 v200, s[44:45]
	s_add_i32 m0, s51, 0xe000
	s_nop 0
	global_load_lds_dwordx4 v202, s[44:45]
	s_waitcnt vmcnt(8)
	s_waitcnt lgkmcnt(0)
	s_barrier
	v_mfma_f32_16x16x32_bf16 v[134:137], v[114:117], v[162:165], v[134:137]
	v_mfma_f32_16x16x32_bf16 v[130:133], v[138:141], v[162:165], v[130:133]
	v_mfma_f32_16x16x32_bf16 v[110:113], v[114:117], v[170:173], v[110:113]
	v_mfma_f32_16x16x32_bf16 v[106:109], v[138:141], v[170:173], v[106:109]
	v_mfma_f32_16x16x32_bf16 v[94:97], v[114:117], v[178:181], v[94:97]
	v_mfma_f32_16x16x32_bf16 v[90:93], v[138:141], v[178:181], v[90:93]
	v_mfma_f32_16x16x32_bf16 v[78:81], v[114:117], v[204:207], v[78:81]
	v_mfma_f32_16x16x32_bf16 v[74:77], v[138:141], v[204:207], v[74:77]
	v_mfma_f32_16x16x32_bf16 v[134:137], v[126:129], v[166:169], v[134:137]
	v_mfma_f32_16x16x32_bf16 v[130:133], v[142:145], v[166:169], v[130:133]
	v_mfma_f32_16x16x32_bf16 v[110:113], v[126:129], v[174:177], v[110:113]
	v_mfma_f32_16x16x32_bf16 v[106:109], v[142:145], v[174:177], v[106:109]
	v_mfma_f32_16x16x32_bf16 v[94:97], v[126:129], v[182:185], v[94:97]
	v_mfma_f32_16x16x32_bf16 v[90:93], v[142:145], v[182:185], v[90:93]
	v_mfma_f32_16x16x32_bf16 v[78:81], v[126:129], v[208:211], v[78:81]
	v_mfma_f32_16x16x32_bf16 v[74:77], v[142:145], v[208:211], v[74:77]
	v_mfma_f32_16x16x32_bf16 v[122:125], v[146:149], v[162:165], v[122:125]
	v_mfma_f32_16x16x32_bf16 v[118:121], v[154:157], v[162:165], v[118:121]
	v_mfma_f32_16x16x32_bf16 v[102:105], v[146:149], v[170:173], v[102:105]
	v_mfma_f32_16x16x32_bf16 v[98:101], v[154:157], v[170:173], v[98:101]
	v_mfma_f32_16x16x32_bf16 v[86:89], v[146:149], v[178:181], v[86:89]
	v_mfma_f32_16x16x32_bf16 v[82:85], v[154:157], v[178:181], v[82:85]
	v_mfma_f32_16x16x32_bf16 v[70:73], v[146:149], v[204:207], v[70:73]
	v_mfma_f32_16x16x32_bf16 v[66:69], v[154:157], v[204:207], v[66:69]
	v_mfma_f32_16x16x32_bf16 v[122:125], v[150:153], v[166:169], v[122:125]
	v_mfma_f32_16x16x32_bf16 v[118:121], v[158:161], v[166:169], v[118:121]
	v_mfma_f32_16x16x32_bf16 v[102:105], v[150:153], v[174:177], v[102:105]
	v_mfma_f32_16x16x32_bf16 v[98:101], v[158:161], v[174:177], v[98:101]
	v_mfma_f32_16x16x32_bf16 v[86:89], v[150:153], v[182:185], v[86:89]
	v_mfma_f32_16x16x32_bf16 v[82:85], v[158:161], v[182:185], v[82:85]
	v_mfma_f32_16x16x32_bf16 v[70:73], v[150:153], v[208:211], v[70:73]
	v_mfma_f32_16x16x32_bf16 v[66:69], v[158:161], v[208:211], v[66:69]
	s_barrier
	s_add_i32 s74, s74, s3
	v_lshl_add_u64 v[190:191], s[72:73], 0, v[0:1]
	s_mov_b32 m0, s74
	ds_read_b128 v[162:165], v235 offset:16384
	ds_read_b128 v[166:169], v235 offset:17408
	ds_read_b128 v[170:173], v235 offset:18432
	ds_read_b128 v[174:177], v235 offset:19456
	ds_read_b128 v[178:181], v235 offset:20480
	ds_read_b128 v[182:185], v235 offset:21504
	ds_read_b128 v[204:207], v235 offset:22528
	ds_read_b128 v[208:211], v235 offset:23552
	global_load_lds_dwordx4 v[190:191], off
	s_add_i32 m0, s74, 0x2000
	v_lshl_add_u64 v[192:193], s[72:73], 0, v[198:199]
	s_add_u32 s72, s72, s24
	s_addc_u32 s73, s73, s25
	s_add_i32 s71, s71, s3
	global_load_lds_dwordx4 v[192:193], off
	v_lshl_add_u64 v[212:213], s[72:73], 0, v[0:1]
	s_mov_b32 m0, s71
	v_lshl_add_u64 v[214:215], s[72:73], 0, v[198:199]
	global_load_lds_dwordx4 v[212:213], off
	s_add_i32 m0, s71, 0x2000
	v_lshl_add_u64 v[216:217], s[52:53], 0, v[194:195]
	global_load_lds_dwordx4 v[214:215], off
	s_mov_b32 m0, s51
	v_lshl_add_u64 v[218:219], s[52:53], 0, v[196:197]
	global_load_lds_dwordx4 v[216:217], off
	s_mov_b32 m0, s59
	s_nop 0
	global_load_lds_dwordx4 v[218:219], off
	s_waitcnt vmcnt(8)
	s_waitcnt lgkmcnt(0)
	s_barrier
; #define PG8_STAGE(bufoff, gbase, voff) do { _Pragma("unroll") for (int _i = 0; _i < 2; ++_i) \
;         __builtin_amdgcn_global_load_lds((const unsigned*)((const char*)(gbase) + (voff)[_i]), (PG8_LAS unsigned*)(lds + (bufoff) + ldsw + _i * 8192), 16, 0, 0); } while (0)
; #define PG8_LDA(dst, b, h) do { _Pragma("unroll") for (int m = 0; m < 4; ++m) _Pragma("unroll") for (int k = 0; k < 2; ++k) dst[m][k] = *(const PG8_LAS bf16x8*)(lds + PG8_SA(b, h) + aoff + m * 2048 + k * 1024); } while (0)
; #define PG8_LDB(dst, b, h) do { _Pragma("unroll") for (int n = 0; n < 2; ++n) _Pragma("unroll") for (int k = 0; k < 2; ++k) dst[n][k] = *(const PG8_LAS bf16x8*)(lds + PG8_SB(b, h) + boff + n * 2048 + k * 1024); } while (0)
; #define PG8_MMA(ai, bj, At, Bt) do { __builtin_amdgcn_s_setprio(1); _Pragma("unroll") for (int m = 0; m < 4; ++m) _Pragma("unroll") for (int n = 0; n < 2; ++n) _Pragma("unroll") for (int k = 0; k < 2; ++k) \
;         acc[ai][bj][m][n] = __builtin_amdgcn_mfma_f32_16x16x32_bf16(Bt[n][k], At[m][k], acc[ai][bj][m][n], 0, 0, 0); __builtin_amdgcn_s_setprio(0); } while (0)
; #define PG8_WAIT_V(n) asm volatile("s_waitcnt vmcnt(" #n ")" ::: "memory")
; #define PG8_WAIT_L(n) asm volatile("s_waitcnt lgkmcnt(" #n ")" ::: "memory")
; #define PG8_BAR __builtin_amdgcn_s_barrier()
; #define PG8_SCHED __builtin_amdgcn_sched_barrier(0)
; template <class Epi, class Sched, bool ALIGN_EPI = false, bool SP2 = false>
; __device__ __forceinline__ void gemm_phase(PG8_LAS unsigned char* lds, const Gemm g, const Sched& S, const Epi& E, const int wv) {
;     ...
;             PG8_WAIT_V(8); PG8_WAIT_L(0); PG8_BAR; PG8_MMA(1, 0, At, B0); PG8_MMA(1, 1, At, B1); PG8_BAR; PG8_SCHED;
;             PG8_LDB(B0, 1, 0); PG8_LDB(B1, 1, 1); PG8_SCHED; PG8_LDA(At, 1, 0); PG8_STAGE(PG8_SA(0, 1), a2 + hstepA, voffA);
;             PG8_WAIT_V(8); PG8_WAIT_L(0); PG8_BAR; PG8_MMA(0, 0, At, B0); PG8_MMA(0, 1, At, B1); PG8_BAR; PG8_SCHED;
	v_mfma_f32_16x16x32_bf16 v[62:65], v[114:117], v[162:165], v[62:65]
	v_mfma_f32_16x16x32_bf16 v[58:61], v[138:141], v[162:165], v[58:61]
	v_mfma_f32_16x16x32_bf16 v[46:49], v[114:117], v[170:173], v[46:49]
	v_mfma_f32_16x16x32_bf16 v[42:45], v[138:141], v[170:173], v[42:45]
	v_mfma_f32_16x16x32_bf16 v[30:33], v[114:117], v[178:181], v[30:33]
	v_mfma_f32_16x16x32_bf16 v[26:29], v[138:141], v[178:181], v[26:29]
	v_mfma_f32_16x16x32_bf16 v[14:17], v[114:117], v[204:207], v[14:17]
	v_mfma_f32_16x16x32_bf16 v[10:13], v[138:141], v[204:207], v[10:13]
	v_mfma_f32_16x16x32_bf16 v[62:65], v[126:129], v[166:169], v[62:65]
	v_mfma_f32_16x16x32_bf16 v[58:61], v[142:145], v[166:169], v[58:61]
	v_mfma_f32_16x16x32_bf16 v[46:49], v[126:129], v[174:177], v[46:49]
	v_mfma_f32_16x16x32_bf16 v[42:45], v[142:145], v[174:177], v[42:45]
	v_mfma_f32_16x16x32_bf16 v[30:33], v[126:129], v[182:185], v[30:33]
	v_mfma_f32_16x16x32_bf16 v[26:29], v[142:145], v[182:185], v[26:29]
	v_mfma_f32_16x16x32_bf16 v[14:17], v[126:129], v[208:211], v[14:17]
	v_mfma_f32_16x16x32_bf16 v[10:13], v[142:145], v[208:211], v[10:13]
	v_mfma_f32_16x16x32_bf16 v[54:57], v[146:149], v[162:165], v[54:57]
	v_mfma_f32_16x16x32_bf16 v[50:53], v[154:157], v[162:165], v[50:53]
	v_mfma_f32_16x16x32_bf16 v[38:41], v[146:149], v[170:173], v[38:41]
	v_mfma_f32_16x16x32_bf16 v[34:37], v[154:157], v[170:173], v[34:37]
	v_mfma_f32_16x16x32_bf16 v[22:25], v[146:149], v[178:181], v[22:25]
	v_mfma_f32_16x16x32_bf16 v[18:21], v[154:157], v[178:181], v[18:21]
	v_mfma_f32_16x16x32_bf16 v[6:9], v[146:149], v[204:207], v[6:9]
	v_mfma_f32_16x16x32_bf16 v[2:5], v[154:157], v[204:207], v[2:5]
	v_mfma_f32_16x16x32_bf16 v[54:57], v[150:153], v[166:169], v[54:57]
	v_mfma_f32_16x16x32_bf16 v[50:53], v[158:161], v[166:169], v[50:53]
	v_mfma_f32_16x16x32_bf16 v[38:41], v[150:153], v[174:177], v[38:41]
	v_mfma_f32_16x16x32_bf16 v[34:37], v[158:161], v[174:177], v[34:37]
	v_mfma_f32_16x16x32_bf16 v[22:25], v[150:153], v[182:185], v[22:25]
	v_mfma_f32_16x16x32_bf16 v[18:21], v[158:161], v[182:185], v[18:21]
	v_mfma_f32_16x16x32_bf16 v[6:9], v[150:153], v[208:211], v[6:9]
	v_mfma_f32_16x16x32_bf16 v[2:5], v[158:161], v[208:211], v[2:5]
	s_barrier
	s_add_i32 s71, 0, 0x18000
	s_add_i32 s72, 0, 0x1c000
	v_add_u32_e32 v142, s71, v230
	v_add_u32_e32 v158, s72, v230
	ds_read_b128 v[114:117], v142
	ds_read_b128 v[126:129], v142 offset:1024
	ds_read_b128 v[138:141], v142 offset:2048
	ds_read_b128 v[142:145], v142 offset:3072
	ds_read_b128 v[146:149], v158
	ds_read_b128 v[150:153], v158 offset:1024
	ds_read_b128 v[154:157], v158 offset:2048
	ds_read_b128 v[158:161], v158 offset:3072
	s_add_u32 s52, s52, 0x40000
	s_addc_u32 s53, s53, 0
	s_mov_b32 m0, s60
	ds_read_b128 v[162:165], v235 offset:32768
	ds_read_b128 v[166:169], v235 offset:33792
	ds_read_b128 v[170:173], v235 offset:34816
	ds_read_b128 v[174:177], v235 offset:35840
	ds_read_b128 v[178:181], v235 offset:36864
	ds_read_b128 v[182:185], v235 offset:37888
	ds_read_b128 v[204:207], v235 offset:38912
	ds_read_b128 v[208:211], v235 offset:39936
	global_load_lds_dwordx4 v194, s[52:53]
	s_mov_b32 m0, s61
	s_nop 0
	global_load_lds_dwordx4 v196, s[52:53]
	s_waitcnt vmcnt(8)
	s_waitcnt lgkmcnt(0)
	s_barrier
	v_mfma_f32_16x16x32_bf16 v[134:137], v[114:117], v[162:165], v[134:137]
	v_mfma_f32_16x16x32_bf16 v[130:133], v[138:141], v[162:165], v[130:133]
	v_mfma_f32_16x16x32_bf16 v[110:113], v[114:117], v[170:173], v[110:113]
	v_mfma_f32_16x16x32_bf16 v[106:109], v[138:141], v[170:173], v[106:109]
	v_mfma_f32_16x16x32_bf16 v[94:97], v[114:117], v[178:181], v[94:97]
	v_mfma_f32_16x16x32_bf16 v[90:93], v[138:141], v[178:181], v[90:93]
	v_mfma_f32_16x16x32_bf16 v[78:81], v[114:117], v[204:207], v[78:81]
	v_mfma_f32_16x16x32_bf16 v[74:77], v[138:141], v[204:207], v[74:77]
	v_mfma_f32_16x16x32_bf16 v[134:137], v[126:129], v[166:169], v[134:137]
	v_mfma_f32_16x16x32_bf16 v[130:133], v[142:145], v[166:169], v[130:133]
	v_mfma_f32_16x16x32_bf16 v[110:113], v[126:129], v[174:177], v[110:113]
	v_mfma_f32_16x16x32_bf16 v[106:109], v[142:145], v[174:177], v[106:109]
	v_mfma_f32_16x16x32_bf16 v[94:97], v[126:129], v[182:185], v[94:97]
	v_mfma_f32_16x16x32_bf16 v[90:93], v[142:145], v[182:185], v[90:93]
	v_mfma_f32_16x16x32_bf16 v[78:81], v[126:129], v[208:211], v[78:81]
	v_mfma_f32_16x16x32_bf16 v[74:77], v[142:145], v[208:211], v[74:77]
	v_mfma_f32_16x16x32_bf16 v[122:125], v[146:149], v[162:165], v[122:125]
	v_mfma_f32_16x16x32_bf16 v[118:121], v[154:157], v[162:165], v[118:121]
	v_mfma_f32_16x16x32_bf16 v[102:105], v[146:149], v[170:173], v[102:105]
	v_mfma_f32_16x16x32_bf16 v[98:101], v[154:157], v[170:173], v[98:101]
	v_mfma_f32_16x16x32_bf16 v[86:89], v[146:149], v[178:181], v[86:89]
	v_mfma_f32_16x16x32_bf16 v[82:85], v[154:157], v[178:181], v[82:85]
	v_mfma_f32_16x16x32_bf16 v[70:73], v[146:149], v[204:207], v[70:73]
	v_mfma_f32_16x16x32_bf16 v[66:69], v[154:157], v[204:207], v[66:69]
	v_mfma_f32_16x16x32_bf16 v[122:125], v[150:153], v[166:169], v[122:125]
	v_mfma_f32_16x16x32_bf16 v[118:121], v[158:161], v[166:169], v[118:121]
	v_mfma_f32_16x16x32_bf16 v[102:105], v[150:153], v[174:177], v[102:105]
	v_mfma_f32_16x16x32_bf16 v[98:101], v[158:161], v[174:177], v[98:101]
	v_mfma_f32_16x16x32_bf16 v[86:89], v[150:153], v[182:185], v[86:89]
	v_mfma_f32_16x16x32_bf16 v[82:85], v[158:161], v[182:185], v[82:85]
	v_mfma_f32_16x16x32_bf16 v[70:73], v[150:153], v[208:211], v[70:73]
	v_mfma_f32_16x16x32_bf16 v[66:69], v[158:161], v[208:211], v[66:69]
	s_barrier
; #define PG8_STAGE(bufoff, gbase, voff) do { _Pragma("unroll") for (int _i = 0; _i < 2; ++_i) \
;         __builtin_amdgcn_global_load_lds((const unsigned*)((const char*)(gbase) + (voff)[_i]), (PG8_LAS unsigned*)(lds + (bufoff) + ldsw + _i * 8192), 16, 0, 0); } while (0)
; #define PG8_LDA(dst, b, h) do { _Pragma("unroll") for (int m = 0; m < 4; ++m) _Pragma("unroll") for (int k = 0; k < 2; ++k) dst[m][k] = *(const PG8_LAS bf16x8*)(lds + PG8_SA(b, h) + aoff + m * 2048 + k * 1024); } while (0)
; #define PG8_MMA(ai, bj, At, Bt) do { __builtin_amdgcn_s_setprio(1); _Pragma("unroll") for (int m = 0; m < 4; ++m) _Pragma("unroll") for (int n = 0; n < 2; ++n) _Pragma("unroll") for (int k = 0; k < 2; ++k) \
;         acc[ai][bj][m][n] = __builtin_amdgcn_mfma_f32_16x16x32_bf16(Bt[n][k], At[m][k], acc[ai][bj][m][n], 0, 0, 0); __builtin_amdgcn_s_setprio(0); } while (0)
; #define PG8_WAIT_V(n) asm volatile("s_waitcnt vmcnt(" #n ")" ::: "memory")
; #define PG8_WAIT_L(n) asm volatile("s_waitcnt lgkmcnt(" #n ")" ::: "memory")
; #define PG8_BAR __builtin_amdgcn_s_barrier()
; #define PG8_SCHED __builtin_amdgcn_sched_barrier(0)
; template <class Epi, class Sched, bool ALIGN_EPI = false, bool SP2 = false>
; __device__ __forceinline__ void gemm_phase(PG8_LAS unsigned char* lds, const Gemm g, const Sched& S, const Epi& E, const int wv) {
;     ...
;             PG8_LDA(At, 1, 1); PG8_STAGE(PG8_SB(1, 0), b3, voffB); PG8_STAGE(PG8_SB(1, 1), b3 + hstepB, voffB); PG8_STAGE(PG8_SA(1, 0), a3, voffA);
;             PG8_WAIT_V(8); PG8_WAIT_L(0); PG8_BAR; PG8_MMA(1, 0, At, B0); PG8_MMA(1, 1, At, B1); PG8_BAR; PG8_SCHED;
	s_add_i32 s52, s71, s3
	s_add_i32 m0, s52, 0xffffff80
	ds_read_b128 v[162:165], v235 offset:49152
	ds_read_b128 v[166:169], v235 offset:50176
	ds_read_b128 v[170:173], v235 offset:51200
	ds_read_b128 v[174:177], v235 offset:52224
	ds_read_b128 v[178:181], v235 offset:53248
	ds_read_b128 v[182:185], v235 offset:54272
	ds_read_b128 v[204:207], v235 offset:55296
	ds_read_b128 v[208:211], v235 offset:56320
	global_load_lds_dwordx4 v[190:191], off offset:128
	s_add_i32 m0, s52, 0x1f80
	s_add_i32 s52, s72, s3
	global_load_lds_dwordx4 v[192:193], off offset:128
	s_add_i32 m0, s52, 0xffffff80
	s_nop 0
	global_load_lds_dwordx4 v[212:213], off offset:128
	s_add_i32 m0, s52, 0x1f80
	s_nop 0
	global_load_lds_dwordx4 v[214:215], off offset:128
	s_add_i32 m0, s63, 0xffffff80
	s_nop 0
	global_load_lds_dwordx4 v[216:217], off offset:128
	s_add_i32 m0, s64, 0xffffff80
	s_nop 0
	global_load_lds_dwordx4 v[218:219], off offset:128
	s_waitcnt vmcnt(8)
	s_waitcnt lgkmcnt(0)
	s_barrier
	v_mfma_f32_16x16x32_bf16 v[62:65], v[114:117], v[162:165], v[62:65]
	v_mfma_f32_16x16x32_bf16 v[58:61], v[138:141], v[162:165], v[58:61]
	v_mfma_f32_16x16x32_bf16 v[46:49], v[114:117], v[170:173], v[46:49]
	v_mfma_f32_16x16x32_bf16 v[42:45], v[138:141], v[170:173], v[42:45]
	v_mfma_f32_16x16x32_bf16 v[30:33], v[114:117], v[178:181], v[30:33]
	v_mfma_f32_16x16x32_bf16 v[26:29], v[138:141], v[178:181], v[26:29]
	v_mfma_f32_16x16x32_bf16 v[14:17], v[114:117], v[204:207], v[14:17]
	v_mfma_f32_16x16x32_bf16 v[10:13], v[138:141], v[204:207], v[10:13]
	v_mfma_f32_16x16x32_bf16 v[62:65], v[126:129], v[166:169], v[62:65]
	v_mfma_f32_16x16x32_bf16 v[58:61], v[142:145], v[166:169], v[58:61]
	v_mfma_f32_16x16x32_bf16 v[46:49], v[126:129], v[174:177], v[46:49]
	v_mfma_f32_16x16x32_bf16 v[42:45], v[142:145], v[174:177], v[42:45]
	v_mfma_f32_16x16x32_bf16 v[30:33], v[126:129], v[182:185], v[30:33]
	v_mfma_f32_16x16x32_bf16 v[26:29], v[142:145], v[182:185], v[26:29]
	v_mfma_f32_16x16x32_bf16 v[14:17], v[126:129], v[208:211], v[14:17]
	v_mfma_f32_16x16x32_bf16 v[10:13], v[142:145], v[208:211], v[10:13]
	v_mfma_f32_16x16x32_bf16 v[54:57], v[146:149], v[162:165], v[54:57]
	v_mfma_f32_16x16x32_bf16 v[50:53], v[154:157], v[162:165], v[50:53]
	v_mfma_f32_16x16x32_bf16 v[38:41], v[146:149], v[170:173], v[38:41]
	v_mfma_f32_16x16x32_bf16 v[34:37], v[154:157], v[170:173], v[34:37]
	v_mfma_f32_16x16x32_bf16 v[22:25], v[146:149], v[178:181], v[22:25]
	v_mfma_f32_16x16x32_bf16 v[18:21], v[154:157], v[178:181], v[18:21]
	v_mfma_f32_16x16x32_bf16 v[6:9], v[146:149], v[204:207], v[6:9]
	v_mfma_f32_16x16x32_bf16 v[2:5], v[154:157], v[204:207], v[2:5]
	v_mfma_f32_16x16x32_bf16 v[54:57], v[150:153], v[166:169], v[54:57]
	v_mfma_f32_16x16x32_bf16 v[50:53], v[158:161], v[166:169], v[50:53]
	v_mfma_f32_16x16x32_bf16 v[38:41], v[150:153], v[174:177], v[38:41]
	v_mfma_f32_16x16x32_bf16 v[34:37], v[158:161], v[174:177], v[34:37]
	v_mfma_f32_16x16x32_bf16 v[22:25], v[150:153], v[182:185], v[22:25]
	v_mfma_f32_16x16x32_bf16 v[18:21], v[158:161], v[182:185], v[18:21]
	v_mfma_f32_16x16x32_bf16 v[6:9], v[150:153], v[208:211], v[6:9]
	v_mfma_f32_16x16x32_bf16 v[2:5], v[158:161], v[208:211], v[2:5]
	s_barrier
	s_add_u32 s44, s44, 0x100
	s_addc_u32 s45, s45, 0
	s_add_u32 s54, s54, 0x100
	s_addc_u32 s55, s55, 0
	s_cmp_ge_i32 s70, s62
	s_mov_b32 s52, s70
	s_cbranch_scc0 .LBB0_1385
	s_mov_b32 s72, 0x10000
	s_mov_b32 s73, 0x12000
	s_mov_b32 s74, 0x14000
	s_mov_b32 s70, 0x18000
	s_mov_b32 s71, 0x3f317217
	s_and_b64 vcc, exec, s[46:47]
	s_cbranch_vccz .LBB0_1361

; #define PG8_STAGE(bufoff, gbase, voff) do { _Pragma("unroll") for (int _i = 0; _i < 2; ++_i) \
;         __builtin_amdgcn_global_load_lds((const unsigned*)((const char*)(gbase) + (voff)[_i]), (PG8_LAS unsigned*)(lds + (bufoff) + ldsw + _i * 8192), 16, 0, 0); } while (0)
; #define PG8_LDA(dst, b, h) do { _Pragma("unroll") for (int m = 0; m < 4; ++m) _Pragma("unroll") for (int k = 0; k < 2; ++k) dst[m][k] = *(const PG8_LAS bf16x8*)(lds + PG8_SA(b, h) + aoff + m * 2048 + k * 1024); } while (0)
; #define PG8_LDB(dst, b, h) do { _Pragma("unroll") for (int n = 0; n < 2; ++n) _Pragma("unroll") for (int k = 0; k < 2; ++k) dst[n][k] = *(const PG8_LAS bf16x8*)(lds + PG8_SB(b, h) + boff + n * 2048 + k * 1024); } while (0)
; #define PG8_MMA(ai, bj, At, Bt) do { __builtin_amdgcn_s_setprio(1); _Pragma("unroll") for (int m = 0; m < 4; ++m) _Pragma("unroll") for (int n = 0; n < 2; ++n) _Pragma("unroll") for (int k = 0; k < 2; ++k) \
;         acc[ai][bj][m][n] = __builtin_amdgcn_mfma_f32_16x16x32_bf16(Bt[n][k], At[m][k], acc[ai][bj][m][n], 0, 0, 0); __builtin_amdgcn_s_setprio(0); } while (0)
; #define PG8_WAIT_V(n) asm volatile("s_waitcnt vmcnt(" #n ")" ::: "memory")
; #define PG8_WAIT_L(n) asm volatile("s_waitcnt lgkmcnt(" #n ")" ::: "memory")
; template <class Epi, class Sched, bool ALIGN_EPI = false, bool SP2 = false>
; __device__ __forceinline__ void gemm_phase(PG8_LAS unsigned char* lds, const Gemm g, const Sched& S, const Epi& E, const int wv) {
;     ...
;             const bool last = (t == nt - 2);
;             const char* a1 = cA + (size_t)(t + 1) * kstep;
;             const char* a2 = last ? nA : cA + (size_t)(t + 2) * kstep; const char* b2 = last ? nB : cB + (size_t)(t + 2) * kstep;
;             const char* a3 = a2 + kstep; const char* b3 = b2 + kstep;
;             if (last && has_next) S.a_ready(nxt);
;             if constexpr (SP2) {
;             PG8_LDB(B0, 0, 0); PG8_LDB(B1, 0, 1); PG8_SCHED; PG8_LDA(At, 0, 0); PG8_STAGE(PG8_SA(1, 1), a1 + hstepA, voffA);
;             PG8_WAIT_V(8); PG8_WAIT_L(0); PG8_BAR; PG8_MMA(0, 0, At, B0); PG8_MMA(0, 1, At, B1); PG8_BAR; PG8_SCHED;
;             PG8_LDA(At, 0, 1); PG8_STAGE(PG8_SB(0, 0), b2, voffB); PG8_STAGE(PG8_SB(0, 1), b2 + hstepB, voffB); PG8_STAGE(PG8_SA(0, 0), a2, voffA);
;             PG8_WAIT_V(8); PG8_WAIT_L(0); PG8_BAR; PG8_MMA(1, 0, At, B0); PG8_MMA(1, 1, At, B1); PG8_BAR; PG8_SCHED;
.LBB0_1495:
	s_add_i32 s52, s46, 2
	s_add_u32 s14, s48, 0x100
	s_addc_u32 s15, s49, 0
	s_add_i32 s53, 0, 0x10000
	s_cmp_eq_u32 s72, s46
	s_cselect_b32 s47, s11, s15
	s_cselect_b32 s46, s13, s14
	s_cselect_b32 s77, s87, s51
	s_cselect_b32 s76, s86, s35
	s_add_i32 s78, 0, 0x14000
	v_add_u32_e32 v150, s53, v208
	v_add_u32_e32 v166, s78, v208
	ds_read_b128 v[138:141], v150
	ds_read_b128 v[142:145], v150 offset:1024
	ds_read_b128 v[146:149], v150 offset:2048
	ds_read_b128 v[150:153], v150 offset:3072
	ds_read_b128 v[154:157], v166
	ds_read_b128 v[158:161], v166 offset:1024
	ds_read_b128 v[162:165], v166 offset:2048
	ds_read_b128 v[166:169], v166 offset:3072
	v_lshl_add_u64 v[190:191], s[48:49], 0, v[182:183]
	s_add_i32 m0, s64, 0xc000
	ds_read_b128 v[194:197], v211
	ds_read_b128 v[198:201], v211 offset:1024
	ds_read_b128 v[202:205], v211 offset:2048
	ds_read_b128 v[214:217], v211 offset:3072
	ds_read_b128 v[228:231], v211 offset:4096
	ds_read_b128 v[232:235], v211 offset:5120
	ds_read_b128 v[236:239], v211 offset:6144
	ds_read_b128 v[240:243], v211 offset:7168
	global_load_lds_dwordx4 v[190:191], off
	v_lshl_add_u64 v[190:191], s[48:49], 0, v[184:185]
	s_add_i32 m0, s64, 0xe000
	s_nop 0
	global_load_lds_dwordx4 v[190:191], off
	s_waitcnt vmcnt(8)
	s_waitcnt lgkmcnt(0)
	s_barrier
	v_mfma_f32_16x16x32_bf16 v[118:121], v[138:141], v[194:197], v[118:121]
	v_mfma_f32_16x16x32_bf16 v[46:49], v[146:149], v[194:197], v[46:49]
	v_mfma_f32_16x16x32_bf16 v[110:113], v[138:141], v[202:205], v[110:113]
	v_mfma_f32_16x16x32_bf16 v[38:41], v[146:149], v[202:205], v[38:41]
	v_mfma_f32_16x16x32_bf16 v[134:137], v[138:141], v[228:231], v[134:137]
	v_mfma_f32_16x16x32_bf16 v[62:65], v[146:149], v[228:231], v[62:65]
	v_mfma_f32_16x16x32_bf16 v[130:133], v[138:141], v[236:239], v[130:133]
	v_mfma_f32_16x16x32_bf16 v[58:61], v[146:149], v[236:239], v[58:61]
	v_mfma_f32_16x16x32_bf16 v[118:121], v[142:145], v[198:201], v[118:121]
	v_mfma_f32_16x16x32_bf16 v[46:49], v[150:153], v[198:201], v[46:49]
	v_mfma_f32_16x16x32_bf16 v[110:113], v[142:145], v[214:217], v[110:113]
	v_mfma_f32_16x16x32_bf16 v[38:41], v[150:153], v[214:217], v[38:41]
	v_mfma_f32_16x16x32_bf16 v[134:137], v[142:145], v[232:235], v[134:137]
	v_mfma_f32_16x16x32_bf16 v[62:65], v[150:153], v[232:235], v[62:65]
	v_mfma_f32_16x16x32_bf16 v[130:133], v[142:145], v[240:243], v[130:133]
	v_mfma_f32_16x16x32_bf16 v[58:61], v[150:153], v[240:243], v[58:61]
	v_mfma_f32_16x16x32_bf16 v[114:117], v[154:157], v[194:197], v[114:117]
	v_mfma_f32_16x16x32_bf16 v[42:45], v[162:165], v[194:197], v[42:45]
	v_mfma_f32_16x16x32_bf16 v[106:109], v[154:157], v[202:205], v[106:109]
	v_mfma_f32_16x16x32_bf16 v[34:37], v[162:165], v[202:205], v[34:37]
	v_mfma_f32_16x16x32_bf16 v[126:129], v[154:157], v[228:231], v[126:129]
	v_mfma_f32_16x16x32_bf16 v[54:57], v[162:165], v[228:231], v[54:57]
	v_mfma_f32_16x16x32_bf16 v[122:125], v[154:157], v[236:239], v[122:125]
	v_mfma_f32_16x16x32_bf16 v[50:53], v[162:165], v[236:239], v[50:53]
	v_mfma_f32_16x16x32_bf16 v[114:117], v[158:161], v[198:201], v[114:117]
	v_mfma_f32_16x16x32_bf16 v[42:45], v[166:169], v[198:201], v[42:45]
	v_mfma_f32_16x16x32_bf16 v[106:109], v[158:161], v[214:217], v[106:109]
	v_mfma_f32_16x16x32_bf16 v[34:37], v[166:169], v[214:217], v[34:37]
	v_mfma_f32_16x16x32_bf16 v[126:129], v[158:161], v[232:235], v[126:129]
	v_mfma_f32_16x16x32_bf16 v[54:57], v[166:169], v[232:235], v[54:57]
	v_mfma_f32_16x16x32_bf16 v[122:125], v[158:161], v[240:243], v[122:125]
	v_mfma_f32_16x16x32_bf16 v[50:53], v[166:169], v[240:243], v[50:53]
	s_barrier
	s_add_i32 s48, s53, s63
	s_mov_b32 m0, s48
	ds_read_b128 v[194:197], v211 offset:16384
	ds_read_b128 v[198:201], v211 offset:17408
	ds_read_b128 v[202:205], v211 offset:18432
	ds_read_b128 v[214:217], v211 offset:19456
	ds_read_b128 v[228:231], v211 offset:20480
	ds_read_b128 v[232:235], v211 offset:21504
	ds_read_b128 v[236:239], v211 offset:22528
	ds_read_b128 v[240:243], v211 offset:23552
	global_load_lds_dwordx4 v0, s[76:77]
	s_add_i32 m0, s48, 0x2000
	s_add_u32 s48, s76, s16
	s_addc_u32 s49, s77, s17
	s_add_i32 s53, s78, s63
	global_load_lds_dwordx4 v174, s[76:77]
	v_lshl_add_u64 v[218:219], s[48:49], 0, v[0:1]
	s_mov_b32 m0, s53
	v_lshl_add_u64 v[244:245], s[48:49], 0, v[174:175]
	global_load_lds_dwordx4 v[218:219], off
	s_add_i32 m0, s53, 0x2000
	v_lshl_add_u64 v[246:247], s[46:47], 0, v[170:171]
	global_load_lds_dwordx4 v[244:245], off
	s_mov_b32 m0, s64
	v_lshl_add_u64 v[248:249], s[46:47], 0, v[172:173]
	global_load_lds_dwordx4 v[246:247], off
	s_mov_b32 m0, s65
	s_nop 0
	global_load_lds_dwordx4 v[248:249], off
	s_waitcnt vmcnt(8)
	s_waitcnt lgkmcnt(0)
	s_barrier
; #define PG8_STAGE(bufoff, gbase, voff) do { _Pragma("unroll") for (int _i = 0; _i < 2; ++_i) \
;         __builtin_amdgcn_global_load_lds((const unsigned*)((const char*)(gbase) + (voff)[_i]), (PG8_LAS unsigned*)(lds + (bufoff) + ldsw + _i * 8192), 16, 0, 0); } while (0)
; #define PG8_LDA(dst, b, h) do { _Pragma("unroll") for (int m = 0; m < 4; ++m) _Pragma("unroll") for (int k = 0; k < 2; ++k) dst[m][k] = *(const PG8_LAS bf16x8*)(lds + PG8_SA(b, h) + aoff + m * 2048 + k * 1024); } while (0)
; #define PG8_LDB(dst, b, h) do { _Pragma("unroll") for (int n = 0; n < 2; ++n) _Pragma("unroll") for (int k = 0; k < 2; ++k) dst[n][k] = *(const PG8_LAS bf16x8*)(lds + PG8_SB(b, h) + boff + n * 2048 + k * 1024); } while (0)
; #define PG8_MMA(ai, bj, At, Bt) do { __builtin_amdgcn_s_setprio(1); _Pragma("unroll") for (int m = 0; m < 4; ++m) _Pragma("unroll") for (int n = 0; n < 2; ++n) _Pragma("unroll") for (int k = 0; k < 2; ++k) \
;         acc[ai][bj][m][n] = __builtin_amdgcn_mfma_f32_16x16x32_bf16(Bt[n][k], At[m][k], acc[ai][bj][m][n], 0, 0, 0); __builtin_amdgcn_s_setprio(0); } while (0)
; #define PG8_WAIT_V(n) asm volatile("s_waitcnt vmcnt(" #n ")" ::: "memory")
; #define PG8_WAIT_L(n) asm volatile("s_waitcnt lgkmcnt(" #n ")" ::: "memory")
; #define PG8_BAR __builtin_amdgcn_s_barrier()
; #define PG8_SCHED __builtin_amdgcn_sched_barrier(0)
; template <class Epi, class Sched, bool ALIGN_EPI = false, bool SP2 = false>
; __device__ __forceinline__ void gemm_phase(PG8_LAS unsigned char* lds, const Gemm g, const Sched& S, const Epi& E, const int wv) {
;     ...
;             PG8_WAIT_V(8); PG8_WAIT_L(0); PG8_BAR; PG8_MMA(1, 0, At, B0); PG8_MMA(1, 1, At, B1); PG8_BAR; PG8_SCHED;
;             PG8_LDB(B0, 1, 0); PG8_LDB(B1, 1, 1); PG8_SCHED; PG8_LDA(At, 1, 0); PG8_STAGE(PG8_SA(0, 1), a2 + hstepA, voffA);
;             PG8_WAIT_V(8); PG8_WAIT_L(0); PG8_BAR; PG8_MMA(0, 0, At, B0); PG8_MMA(0, 1, At, B1); PG8_BAR; PG8_SCHED;
	v_mfma_f32_16x16x32_bf16 v[86:89], v[138:141], v[194:197], v[86:89]
	v_mfma_f32_16x16x32_bf16 v[14:17], v[146:149], v[194:197], v[14:17]
	v_mfma_f32_16x16x32_bf16 v[70:73], v[138:141], v[202:205], v[70:73]
	v_mfma_f32_16x16x32_bf16 v[6:9], v[146:149], v[202:205], v[6:9]
	v_mfma_f32_16x16x32_bf16 v[102:105], v[138:141], v[228:231], v[102:105]
	v_mfma_f32_16x16x32_bf16 v[30:33], v[146:149], v[228:231], v[30:33]
	v_mfma_f32_16x16x32_bf16 v[98:101], v[138:141], v[236:239], v[98:101]
	v_mfma_f32_16x16x32_bf16 v[26:29], v[146:149], v[236:239], v[26:29]
	v_mfma_f32_16x16x32_bf16 v[86:89], v[142:145], v[198:201], v[86:89]
	v_mfma_f32_16x16x32_bf16 v[14:17], v[150:153], v[198:201], v[14:17]
	v_mfma_f32_16x16x32_bf16 v[70:73], v[142:145], v[214:217], v[70:73]
	v_mfma_f32_16x16x32_bf16 v[6:9], v[150:153], v[214:217], v[6:9]
	v_mfma_f32_16x16x32_bf16 v[102:105], v[142:145], v[232:235], v[102:105]
	v_mfma_f32_16x16x32_bf16 v[30:33], v[150:153], v[232:235], v[30:33]
	v_mfma_f32_16x16x32_bf16 v[98:101], v[142:145], v[240:243], v[98:101]
	v_mfma_f32_16x16x32_bf16 v[26:29], v[150:153], v[240:243], v[26:29]
	v_mfma_f32_16x16x32_bf16 v[82:85], v[154:157], v[194:197], v[82:85]
	v_mfma_f32_16x16x32_bf16 v[10:13], v[162:165], v[194:197], v[10:13]
	v_mfma_f32_16x16x32_bf16 v[66:69], v[154:157], v[202:205], v[66:69]
	v_mfma_f32_16x16x32_bf16 v[2:5], v[162:165], v[202:205], v[2:5]
	v_mfma_f32_16x16x32_bf16 v[94:97], v[154:157], v[228:231], v[94:97]
	v_mfma_f32_16x16x32_bf16 v[22:25], v[162:165], v[228:231], v[22:25]
	v_mfma_f32_16x16x32_bf16 v[90:93], v[154:157], v[236:239], v[90:93]
	v_mfma_f32_16x16x32_bf16 v[18:21], v[162:165], v[236:239], v[18:21]
	v_mfma_f32_16x16x32_bf16 v[82:85], v[158:161], v[198:201], v[82:85]
	v_mfma_f32_16x16x32_bf16 v[10:13], v[166:169], v[198:201], v[10:13]
	v_mfma_f32_16x16x32_bf16 v[66:69], v[158:161], v[214:217], v[66:69]
	v_mfma_f32_16x16x32_bf16 v[2:5], v[166:169], v[214:217], v[2:5]
	v_mfma_f32_16x16x32_bf16 v[94:97], v[158:161], v[232:235], v[94:97]
	v_mfma_f32_16x16x32_bf16 v[22:25], v[166:169], v[232:235], v[22:25]
	v_mfma_f32_16x16x32_bf16 v[90:93], v[158:161], v[240:243], v[90:93]
	v_mfma_f32_16x16x32_bf16 v[18:21], v[166:169], v[240:243], v[18:21]
	s_barrier
	s_add_i32 s48, 0, 0x18000
	s_add_i32 s49, 0, 0x1c000
	v_add_u32_e32 v150, s48, v208
	v_add_u32_e32 v166, s49, v208
	ds_read_b128 v[138:141], v150
	ds_read_b128 v[142:145], v150 offset:1024
	ds_read_b128 v[146:149], v150 offset:2048
	ds_read_b128 v[150:153], v150 offset:3072
	ds_read_b128 v[154:157], v166
	ds_read_b128 v[158:161], v166 offset:1024
	ds_read_b128 v[162:165], v166 offset:2048
	ds_read_b128 v[166:169], v166 offset:3072
	s_add_u32 s46, s46, 0x80000
	s_addc_u32 s47, s47, 0
	s_mov_b32 m0, s66
	ds_read_b128 v[194:197], v211 offset:32768
	ds_read_b128 v[198:201], v211 offset:33792
	ds_read_b128 v[202:205], v211 offset:34816
	ds_read_b128 v[214:217], v211 offset:35840
	ds_read_b128 v[228:231], v211 offset:36864
	ds_read_b128 v[232:235], v211 offset:37888
	ds_read_b128 v[236:239], v211 offset:38912
	ds_read_b128 v[240:243], v211 offset:39936
	global_load_lds_dwordx4 v170, s[46:47]
	s_mov_b32 m0, s67
	s_nop 0
	global_load_lds_dwordx4 v172, s[46:47]
	s_waitcnt vmcnt(8)
	s_waitcnt lgkmcnt(0)
	s_barrier
	v_mfma_f32_16x16x32_bf16 v[118:121], v[138:141], v[194:197], v[118:121]
	v_mfma_f32_16x16x32_bf16 v[46:49], v[146:149], v[194:197], v[46:49]
	v_mfma_f32_16x16x32_bf16 v[110:113], v[138:141], v[202:205], v[110:113]
	v_mfma_f32_16x16x32_bf16 v[38:41], v[146:149], v[202:205], v[38:41]
	v_mfma_f32_16x16x32_bf16 v[134:137], v[138:141], v[228:231], v[134:137]
	v_mfma_f32_16x16x32_bf16 v[62:65], v[146:149], v[228:231], v[62:65]
	v_mfma_f32_16x16x32_bf16 v[130:133], v[138:141], v[236:239], v[130:133]
	v_mfma_f32_16x16x32_bf16 v[58:61], v[146:149], v[236:239], v[58:61]
	v_mfma_f32_16x16x32_bf16 v[118:121], v[142:145], v[198:201], v[118:121]
	v_mfma_f32_16x16x32_bf16 v[46:49], v[150:153], v[198:201], v[46:49]
	v_mfma_f32_16x16x32_bf16 v[110:113], v[142:145], v[214:217], v[110:113]
	v_mfma_f32_16x16x32_bf16 v[38:41], v[150:153], v[214:217], v[38:41]
	v_mfma_f32_16x16x32_bf16 v[134:137], v[142:145], v[232:235], v[134:137]
	v_mfma_f32_16x16x32_bf16 v[62:65], v[150:153], v[232:235], v[62:65]
	v_mfma_f32_16x16x32_bf16 v[130:133], v[142:145], v[240:243], v[130:133]
	v_mfma_f32_16x16x32_bf16 v[58:61], v[150:153], v[240:243], v[58:61]
	v_mfma_f32_16x16x32_bf16 v[114:117], v[154:157], v[194:197], v[114:117]
	v_mfma_f32_16x16x32_bf16 v[42:45], v[162:165], v[194:197], v[42:45]
	v_mfma_f32_16x16x32_bf16 v[106:109], v[154:157], v[202:205], v[106:109]
	v_mfma_f32_16x16x32_bf16 v[34:37], v[162:165], v[202:205], v[34:37]
	v_mfma_f32_16x16x32_bf16 v[126:129], v[154:157], v[228:231], v[126:129]
	v_mfma_f32_16x16x32_bf16 v[54:57], v[162:165], v[228:231], v[54:57]
	v_mfma_f32_16x16x32_bf16 v[122:125], v[154:157], v[236:239], v[122:125]
	v_mfma_f32_16x16x32_bf16 v[50:53], v[162:165], v[236:239], v[50:53]
	v_mfma_f32_16x16x32_bf16 v[114:117], v[158:161], v[198:201], v[114:117]
	v_mfma_f32_16x16x32_bf16 v[42:45], v[166:169], v[198:201], v[42:45]
	v_mfma_f32_16x16x32_bf16 v[106:109], v[158:161], v[214:217], v[106:109]
	v_mfma_f32_16x16x32_bf16 v[34:37], v[166:169], v[214:217], v[34:37]
	v_mfma_f32_16x16x32_bf16 v[126:129], v[158:161], v[232:235], v[126:129]
	v_mfma_f32_16x16x32_bf16 v[54:57], v[166:169], v[232:235], v[54:57]
	v_mfma_f32_16x16x32_bf16 v[122:125], v[158:161], v[240:243], v[122:125]
	v_mfma_f32_16x16x32_bf16 v[50:53], v[166:169], v[240:243], v[50:53]
	s_barrier
; #define PG8_STAGE(bufoff, gbase, voff) do { _Pragma("unroll") for (int _i = 0; _i < 2; ++_i) \
;         __builtin_amdgcn_global_load_lds((const unsigned*)((const char*)(gbase) + (voff)[_i]), (PG8_LAS unsigned*)(lds + (bufoff) + ldsw + _i * 8192), 16, 0, 0); } while (0)
; #define PG8_LDA(dst, b, h) do { _Pragma("unroll") for (int m = 0; m < 4; ++m) _Pragma("unroll") for (int k = 0; k < 2; ++k) dst[m][k] = *(const PG8_LAS bf16x8*)(lds + PG8_SA(b, h) + aoff + m * 2048 + k * 1024); } while (0)
; #define PG8_MMA(ai, bj, At, Bt) do { __builtin_amdgcn_s_setprio(1); _Pragma("unroll") for (int m = 0; m < 4; ++m) _Pragma("unroll") for (int n = 0; n < 2; ++n) _Pragma("unroll") for (int k = 0; k < 2; ++k) \
;         acc[ai][bj][m][n] = __builtin_amdgcn_mfma_f32_16x16x32_bf16(Bt[n][k], At[m][k], acc[ai][bj][m][n], 0, 0, 0); __builtin_amdgcn_s_setprio(0); } while (0)
; #define PG8_WAIT_V(n) asm volatile("s_waitcnt vmcnt(" #n ")" ::: "memory")
; #define PG8_WAIT_L(n) asm volatile("s_waitcnt lgkmcnt(" #n ")" ::: "memory")
; #define PG8_BAR __builtin_amdgcn_s_barrier()
; #define PG8_SCHED __builtin_amdgcn_sched_barrier(0)
; template <class Epi, class Sched, bool ALIGN_EPI = false, bool SP2 = false>
; __device__ __forceinline__ void gemm_phase(PG8_LAS unsigned char* lds, const Gemm g, const Sched& S, const Epi& E, const int wv) {
;     ...
;             PG8_LDA(At, 1, 1); PG8_STAGE(PG8_SB(1, 0), b3, voffB); PG8_STAGE(PG8_SB(1, 1), b3 + hstepB, voffB); PG8_STAGE(PG8_SA(1, 0), a3, voffA);
;             PG8_WAIT_V(8); PG8_WAIT_L(0); PG8_BAR; PG8_MMA(1, 0, At, B0); PG8_MMA(1, 1, At, B1); PG8_BAR; PG8_SCHED;
	s_add_i32 s46, s48, s63
	s_add_i32 m0, s46, 0xffffff80
	ds_read_b128 v[194:197], v211 offset:49152
	ds_read_b128 v[198:201], v211 offset:50176
	ds_read_b128 v[202:205], v211 offset:51200
	ds_read_b128 v[214:217], v211 offset:52224
	ds_read_b128 v[228:231], v211 offset:53248
	ds_read_b128 v[232:235], v211 offset:54272
	ds_read_b128 v[236:239], v211 offset:55296
	ds_read_b128 v[240:243], v211 offset:56320
	global_load_lds_dwordx4 v0, s[76:77] offset:128
	s_add_i32 m0, s46, 0x1f80
	s_add_i32 s46, s49, s63
	global_load_lds_dwordx4 v174, s[76:77] offset:128
	s_add_i32 m0, s46, 0xffffff80
	s_nop 0
	global_load_lds_dwordx4 v[218:219], off offset:128
	s_add_i32 m0, s46, 0x1f80
	s_nop 0
	global_load_lds_dwordx4 v[244:245], off offset:128
	s_add_i32 m0, s70, 0xffffff80
	s_nop 0
	global_load_lds_dwordx4 v[246:247], off offset:128
	s_add_i32 m0, s71, 0xffffff80
	s_nop 0
	global_load_lds_dwordx4 v[248:249], off offset:128
	s_waitcnt vmcnt(8)
	s_waitcnt lgkmcnt(0)
	s_barrier
	v_mfma_f32_16x16x32_bf16 v[86:89], v[138:141], v[194:197], v[86:89]
	v_mfma_f32_16x16x32_bf16 v[14:17], v[146:149], v[194:197], v[14:17]
	v_mfma_f32_16x16x32_bf16 v[70:73], v[138:141], v[202:205], v[70:73]
	v_mfma_f32_16x16x32_bf16 v[6:9], v[146:149], v[202:205], v[6:9]
	v_mfma_f32_16x16x32_bf16 v[102:105], v[138:141], v[228:231], v[102:105]
	v_mfma_f32_16x16x32_bf16 v[30:33], v[146:149], v[228:231], v[30:33]
	v_mfma_f32_16x16x32_bf16 v[98:101], v[138:141], v[236:239], v[98:101]
	v_mfma_f32_16x16x32_bf16 v[26:29], v[146:149], v[236:239], v[26:29]
	v_mfma_f32_16x16x32_bf16 v[86:89], v[142:145], v[198:201], v[86:89]
	v_mfma_f32_16x16x32_bf16 v[14:17], v[150:153], v[198:201], v[14:17]
	v_mfma_f32_16x16x32_bf16 v[70:73], v[142:145], v[214:217], v[70:73]
	v_mfma_f32_16x16x32_bf16 v[6:9], v[150:153], v[214:217], v[6:9]
	v_mfma_f32_16x16x32_bf16 v[102:105], v[142:145], v[232:235], v[102:105]
	v_mfma_f32_16x16x32_bf16 v[30:33], v[150:153], v[232:235], v[30:33]
	v_mfma_f32_16x16x32_bf16 v[98:101], v[142:145], v[240:243], v[98:101]
	v_mfma_f32_16x16x32_bf16 v[26:29], v[150:153], v[240:243], v[26:29]
	v_mfma_f32_16x16x32_bf16 v[82:85], v[154:157], v[194:197], v[82:85]
	v_mfma_f32_16x16x32_bf16 v[10:13], v[162:165], v[194:197], v[10:13]
	v_mfma_f32_16x16x32_bf16 v[66:69], v[154:157], v[202:205], v[66:69]
	v_mfma_f32_16x16x32_bf16 v[2:5], v[162:165], v[202:205], v[2:5]
	v_mfma_f32_16x16x32_bf16 v[94:97], v[154:157], v[228:231], v[94:97]
	v_mfma_f32_16x16x32_bf16 v[22:25], v[162:165], v[228:231], v[22:25]
	v_mfma_f32_16x16x32_bf16 v[90:93], v[154:157], v[236:239], v[90:93]
	v_mfma_f32_16x16x32_bf16 v[18:21], v[162:165], v[236:239], v[18:21]
	v_mfma_f32_16x16x32_bf16 v[82:85], v[158:161], v[198:201], v[82:85]
	v_mfma_f32_16x16x32_bf16 v[10:13], v[166:169], v[198:201], v[10:13]
	v_mfma_f32_16x16x32_bf16 v[66:69], v[158:161], v[214:217], v[66:69]
	v_mfma_f32_16x16x32_bf16 v[2:5], v[166:169], v[214:217], v[2:5]
	v_mfma_f32_16x16x32_bf16 v[94:97], v[158:161], v[232:235], v[94:97]
	v_mfma_f32_16x16x32_bf16 v[22:25], v[166:169], v[232:235], v[22:25]
	v_mfma_f32_16x16x32_bf16 v[90:93], v[158:161], v[240:243], v[90:93]
	v_mfma_f32_16x16x32_bf16 v[18:21], v[166:169], v[240:243], v[18:21]
	s_barrier
	s_add_u32 s35, s35, 0x100
	s_addc_u32 s51, s51, 0
	s_cmp_ge_i32 s52, s68
	s_mov_b64 s[48:49], s[14:15]
	s_mov_b32 s46, s52
	s_cbranch_scc0 .LBB0_1495
	s_movk_i32 s78, 0x7ff
	s_movk_i32 s76, 0x3000
	s_and_b64 vcc, exec, s[30:31]
	s_cbranch_vccz .LBB0_1470

; #define PG8_STAGE(bufoff, gbase, voff) do { _Pragma("unroll") for (int _i = 0; _i < 2; ++_i) \
;         __builtin_amdgcn_global_load_lds((const unsigned*)((const char*)(gbase) + (voff)[_i]), (PG8_LAS unsigned*)(lds + (bufoff) + ldsw + _i * 8192), 16, 0, 0); } while (0)
; #define PG8_LDA(dst, b, h) do { _Pragma("unroll") for (int m = 0; m < 4; ++m) _Pragma("unroll") for (int k = 0; k < 2; ++k) dst[m][k] = *(const PG8_LAS bf16x8*)(lds + PG8_SA(b, h) + aoff + m * 2048 + k * 1024); } while (0)
; #define PG8_LDB(dst, b, h) do { _Pragma("unroll") for (int n = 0; n < 2; ++n) _Pragma("unroll") for (int k = 0; k < 2; ++k) dst[n][k] = *(const PG8_LAS bf16x8*)(lds + PG8_SB(b, h) + boff + n * 2048 + k * 1024); } while (0)
; #define PG8_MMA(ai, bj, At, Bt) do { __builtin_amdgcn_s_setprio(1); _Pragma("unroll") for (int m = 0; m < 4; ++m) _Pragma("unroll") for (int n = 0; n < 2; ++n) _Pragma("unroll") for (int k = 0; k < 2; ++k) \
;         acc[ai][bj][m][n] = __builtin_amdgcn_mfma_f32_16x16x32_bf16(Bt[n][k], At[m][k], acc[ai][bj][m][n], 0, 0, 0); __builtin_amdgcn_s_setprio(0); } while (0)
; #define PG8_WAIT_V(n) asm volatile("s_waitcnt vmcnt(" #n ")" ::: "memory")
; #define PG8_WAIT_L(n) asm volatile("s_waitcnt lgkmcnt(" #n ")" ::: "memory")
; template <class Epi, class Sched, bool ALIGN_EPI = false, bool SP2 = false>
; __device__ __forceinline__ void gemm_phase(PG8_LAS unsigned char* lds, const Gemm g, const Sched& S, const Epi& E, const int wv) {
;     ...
;             const bool last = (t == nt - 2);
;             const char* a1 = cA + (size_t)(t + 1) * kstep;
;             const char* a2 = last ? nA : cA + (size_t)(t + 2) * kstep; const char* b2 = last ? nB : cB + (size_t)(t + 2) * kstep;
;             const char* a3 = a2 + kstep; const char* b3 = b2 + kstep;
;             if (last && has_next) S.a_ready(nxt);
;             if constexpr (SP2) {
;             PG8_LDB(B0, 0, 0); PG8_LDB(B1, 0, 1); PG8_SCHED; PG8_LDA(At, 0, 0); PG8_STAGE(PG8_SA(1, 1), a1 + hstepA, voffA);
;             PG8_WAIT_V(8); PG8_WAIT_L(0); PG8_BAR; PG8_MMA(0, 0, At, B0); PG8_MMA(0, 1, At, B1); PG8_BAR; PG8_SCHED;
;             PG8_LDA(At, 0, 1); PG8_STAGE(PG8_SB(0, 0), b2, voffB); PG8_STAGE(PG8_SB(0, 1), b2 + hstepB, voffB); PG8_STAGE(PG8_SA(0, 0), a2, voffA);
;             PG8_WAIT_V(8); PG8_WAIT_L(0); PG8_BAR; PG8_MMA(1, 0, At, B0); PG8_MMA(1, 1, At, B1); PG8_BAR; PG8_SCHED;
.LBB0_1676:
	s_add_i32 s67, s44, 2
	s_add_u32 s34, s30, 0x100
	s_addc_u32 s35, s31, 0
	s_add_i32 s70, 0, 0x10000
	s_cmp_eq_u32 s59, s44
	s_cselect_b32 s45, s13, s35
	s_cselect_b32 s44, s12, s34
	s_cselect_b32 s69, s15, s66
	s_cselect_b32 s68, s14, s65
	s_add_i32 s71, 0, 0x14000
	v_add_u32_e32 v142, s70, v230
	v_add_u32_e32 v158, s71, v230
	ds_read_b128 v[114:117], v142
	ds_read_b128 v[126:129], v142 offset:1024
	ds_read_b128 v[138:141], v142 offset:2048
	ds_read_b128 v[142:145], v142 offset:3072
	ds_read_b128 v[146:149], v158
	ds_read_b128 v[150:153], v158 offset:1024
	ds_read_b128 v[154:157], v158 offset:2048
	ds_read_b128 v[158:161], v158 offset:3072
	v_lshl_add_u64 v[190:191], s[30:31], 0, v[200:201]
	s_add_i32 m0, s52, 0xc000
	ds_read_b128 v[162:165], v235
	ds_read_b128 v[166:169], v235 offset:1024
	ds_read_b128 v[170:173], v235 offset:2048
	ds_read_b128 v[174:177], v235 offset:3072
	ds_read_b128 v[178:181], v235 offset:4096
	ds_read_b128 v[182:185], v235 offset:5120
	ds_read_b128 v[204:207], v235 offset:6144
	ds_read_b128 v[208:211], v235 offset:7168
	global_load_lds_dwordx4 v[190:191], off
	v_lshl_add_u64 v[190:191], s[30:31], 0, v[202:203]
	s_add_i32 m0, s52, 0xe000
	s_nop 0
	global_load_lds_dwordx4 v[190:191], off
	s_waitcnt vmcnt(8)
	s_waitcnt lgkmcnt(0)
	s_barrier
	v_mfma_f32_16x16x32_bf16 v[134:137], v[114:117], v[162:165], v[134:137]
	v_mfma_f32_16x16x32_bf16 v[130:133], v[138:141], v[162:165], v[130:133]
	v_mfma_f32_16x16x32_bf16 v[110:113], v[114:117], v[170:173], v[110:113]
	v_mfma_f32_16x16x32_bf16 v[106:109], v[138:141], v[170:173], v[106:109]
	v_mfma_f32_16x16x32_bf16 v[94:97], v[114:117], v[178:181], v[94:97]
	v_mfma_f32_16x16x32_bf16 v[90:93], v[138:141], v[178:181], v[90:93]
	v_mfma_f32_16x16x32_bf16 v[78:81], v[114:117], v[204:207], v[78:81]
	v_mfma_f32_16x16x32_bf16 v[74:77], v[138:141], v[204:207], v[74:77]
	v_mfma_f32_16x16x32_bf16 v[134:137], v[126:129], v[166:169], v[134:137]
	v_mfma_f32_16x16x32_bf16 v[130:133], v[142:145], v[166:169], v[130:133]
	v_mfma_f32_16x16x32_bf16 v[110:113], v[126:129], v[174:177], v[110:113]
	v_mfma_f32_16x16x32_bf16 v[106:109], v[142:145], v[174:177], v[106:109]
	v_mfma_f32_16x16x32_bf16 v[94:97], v[126:129], v[182:185], v[94:97]
	v_mfma_f32_16x16x32_bf16 v[90:93], v[142:145], v[182:185], v[90:93]
	v_mfma_f32_16x16x32_bf16 v[78:81], v[126:129], v[208:211], v[78:81]
	v_mfma_f32_16x16x32_bf16 v[74:77], v[142:145], v[208:211], v[74:77]
	v_mfma_f32_16x16x32_bf16 v[122:125], v[146:149], v[162:165], v[122:125]
	v_mfma_f32_16x16x32_bf16 v[118:121], v[154:157], v[162:165], v[118:121]
	v_mfma_f32_16x16x32_bf16 v[102:105], v[146:149], v[170:173], v[102:105]
	v_mfma_f32_16x16x32_bf16 v[98:101], v[154:157], v[170:173], v[98:101]
	v_mfma_f32_16x16x32_bf16 v[86:89], v[146:149], v[178:181], v[86:89]
	v_mfma_f32_16x16x32_bf16 v[82:85], v[154:157], v[178:181], v[82:85]
	v_mfma_f32_16x16x32_bf16 v[70:73], v[146:149], v[204:207], v[70:73]
	v_mfma_f32_16x16x32_bf16 v[66:69], v[154:157], v[204:207], v[66:69]
	v_mfma_f32_16x16x32_bf16 v[122:125], v[150:153], v[166:169], v[122:125]
	v_mfma_f32_16x16x32_bf16 v[118:121], v[158:161], v[166:169], v[118:121]
	v_mfma_f32_16x16x32_bf16 v[102:105], v[150:153], v[174:177], v[102:105]
	v_mfma_f32_16x16x32_bf16 v[98:101], v[158:161], v[174:177], v[98:101]
	v_mfma_f32_16x16x32_bf16 v[86:89], v[150:153], v[182:185], v[86:89]
	v_mfma_f32_16x16x32_bf16 v[82:85], v[158:161], v[182:185], v[82:85]
	v_mfma_f32_16x16x32_bf16 v[70:73], v[150:153], v[208:211], v[70:73]
	v_mfma_f32_16x16x32_bf16 v[66:69], v[158:161], v[208:211], v[66:69]
	s_barrier
	s_add_i32 s30, s70, s47
	v_lshl_add_u64 v[190:191], s[68:69], 0, v[0:1]
	s_mov_b32 m0, s30
	ds_read_b128 v[162:165], v235 offset:16384
	ds_read_b128 v[166:169], v235 offset:17408
	ds_read_b128 v[170:173], v235 offset:18432
	ds_read_b128 v[174:177], v235 offset:19456
	ds_read_b128 v[178:181], v235 offset:20480
	ds_read_b128 v[182:185], v235 offset:21504
	ds_read_b128 v[204:207], v235 offset:22528
	ds_read_b128 v[208:211], v235 offset:23552
	global_load_lds_dwordx4 v[190:191], off
	s_add_i32 m0, s30, 0x2000
	s_add_u32 s30, s68, s2
	v_lshl_add_u64 v[192:193], s[68:69], 0, v[198:199]
	s_addc_u32 s31, s69, s3
	s_add_i32 s68, s71, s47
	global_load_lds_dwordx4 v[192:193], off
	v_lshl_add_u64 v[212:213], s[30:31], 0, v[0:1]
	s_mov_b32 m0, s68
	v_lshl_add_u64 v[214:215], s[30:31], 0, v[198:199]
	global_load_lds_dwordx4 v[212:213], off
	s_add_i32 m0, s68, 0x2000
	global_load_lds_dwordx4 v[214:215], off
	s_mov_b32 m0, s52
	global_load_lds_dwordx4 v194, s[44:45]
	s_mov_b32 m0, s53
	s_nop 0
	global_load_lds_dwordx4 v196, s[44:45]
	s_waitcnt vmcnt(8)
	s_waitcnt lgkmcnt(0)
	s_barrier
; #define PG8_STAGE(bufoff, gbase, voff) do { _Pragma("unroll") for (int _i = 0; _i < 2; ++_i) \
;         __builtin_amdgcn_global_load_lds((const unsigned*)((const char*)(gbase) + (voff)[_i]), (PG8_LAS unsigned*)(lds + (bufoff) + ldsw + _i * 8192), 16, 0, 0); } while (0)
; #define PG8_LDA(dst, b, h) do { _Pragma("unroll") for (int m = 0; m < 4; ++m) _Pragma("unroll") for (int k = 0; k < 2; ++k) dst[m][k] = *(const PG8_LAS bf16x8*)(lds + PG8_SA(b, h) + aoff + m * 2048 + k * 1024); } while (0)
; #define PG8_LDB(dst, b, h) do { _Pragma("unroll") for (int n = 0; n < 2; ++n) _Pragma("unroll") for (int k = 0; k < 2; ++k) dst[n][k] = *(const PG8_LAS bf16x8*)(lds + PG8_SB(b, h) + boff + n * 2048 + k * 1024); } while (0)
; #define PG8_MMA(ai, bj, At, Bt) do { __builtin_amdgcn_s_setprio(1); _Pragma("unroll") for (int m = 0; m < 4; ++m) _Pragma("unroll") for (int n = 0; n < 2; ++n) _Pragma("unroll") for (int k = 0; k < 2; ++k) \
;         acc[ai][bj][m][n] = __builtin_amdgcn_mfma_f32_16x16x32_bf16(Bt[n][k], At[m][k], acc[ai][bj][m][n], 0, 0, 0); __builtin_amdgcn_s_setprio(0); } while (0)
; #define PG8_WAIT_V(n) asm volatile("s_waitcnt vmcnt(" #n ")" ::: "memory")
; #define PG8_WAIT_L(n) asm volatile("s_waitcnt lgkmcnt(" #n ")" ::: "memory")
; #define PG8_BAR __builtin_amdgcn_s_barrier()
; #define PG8_SCHED __builtin_amdgcn_sched_barrier(0)
; template <class Epi, class Sched, bool ALIGN_EPI = false, bool SP2 = false>
; __device__ __forceinline__ void gemm_phase(PG8_LAS unsigned char* lds, const Gemm g, const Sched& S, const Epi& E, const int wv) {
;     ...
;             PG8_WAIT_V(8); PG8_WAIT_L(0); PG8_BAR; PG8_MMA(1, 0, At, B0); PG8_MMA(1, 1, At, B1); PG8_BAR; PG8_SCHED;
;             PG8_LDB(B0, 1, 0); PG8_LDB(B1, 1, 1); PG8_SCHED; PG8_LDA(At, 1, 0); PG8_STAGE(PG8_SA(0, 1), a2 + hstepA, voffA);
;             PG8_WAIT_V(8); PG8_WAIT_L(0); PG8_BAR; PG8_MMA(0, 0, At, B0); PG8_MMA(0, 1, At, B1); PG8_BAR; PG8_SCHED;
	v_mfma_f32_16x16x32_bf16 v[62:65], v[114:117], v[162:165], v[62:65]
	v_mfma_f32_16x16x32_bf16 v[58:61], v[138:141], v[162:165], v[58:61]
	v_mfma_f32_16x16x32_bf16 v[46:49], v[114:117], v[170:173], v[46:49]
	v_mfma_f32_16x16x32_bf16 v[42:45], v[138:141], v[170:173], v[42:45]
	v_mfma_f32_16x16x32_bf16 v[30:33], v[114:117], v[178:181], v[30:33]
	v_mfma_f32_16x16x32_bf16 v[26:29], v[138:141], v[178:181], v[26:29]
	v_mfma_f32_16x16x32_bf16 v[14:17], v[114:117], v[204:207], v[14:17]
	v_mfma_f32_16x16x32_bf16 v[10:13], v[138:141], v[204:207], v[10:13]
	v_mfma_f32_16x16x32_bf16 v[62:65], v[126:129], v[166:169], v[62:65]
	v_mfma_f32_16x16x32_bf16 v[58:61], v[142:145], v[166:169], v[58:61]
	v_mfma_f32_16x16x32_bf16 v[46:49], v[126:129], v[174:177], v[46:49]
	v_mfma_f32_16x16x32_bf16 v[42:45], v[142:145], v[174:177], v[42:45]
	v_mfma_f32_16x16x32_bf16 v[30:33], v[126:129], v[182:185], v[30:33]
	v_mfma_f32_16x16x32_bf16 v[26:29], v[142:145], v[182:185], v[26:29]
	v_mfma_f32_16x16x32_bf16 v[14:17], v[126:129], v[208:211], v[14:17]
	v_mfma_f32_16x16x32_bf16 v[10:13], v[142:145], v[208:211], v[10:13]
	v_mfma_f32_16x16x32_bf16 v[54:57], v[146:149], v[162:165], v[54:57]
	v_mfma_f32_16x16x32_bf16 v[50:53], v[154:157], v[162:165], v[50:53]
	v_mfma_f32_16x16x32_bf16 v[38:41], v[146:149], v[170:173], v[38:41]
	v_mfma_f32_16x16x32_bf16 v[34:37], v[154:157], v[170:173], v[34:37]
	v_mfma_f32_16x16x32_bf16 v[22:25], v[146:149], v[178:181], v[22:25]
	v_mfma_f32_16x16x32_bf16 v[18:21], v[154:157], v[178:181], v[18:21]
	v_mfma_f32_16x16x32_bf16 v[6:9], v[146:149], v[204:207], v[6:9]
	v_mfma_f32_16x16x32_bf16 v[2:5], v[154:157], v[204:207], v[2:5]
	v_mfma_f32_16x16x32_bf16 v[54:57], v[150:153], v[166:169], v[54:57]
	v_mfma_f32_16x16x32_bf16 v[50:53], v[158:161], v[166:169], v[50:53]
	v_mfma_f32_16x16x32_bf16 v[38:41], v[150:153], v[174:177], v[38:41]
	v_mfma_f32_16x16x32_bf16 v[34:37], v[158:161], v[174:177], v[34:37]
	v_mfma_f32_16x16x32_bf16 v[22:25], v[150:153], v[182:185], v[22:25]
	v_mfma_f32_16x16x32_bf16 v[18:21], v[158:161], v[182:185], v[18:21]
	v_mfma_f32_16x16x32_bf16 v[6:9], v[150:153], v[208:211], v[6:9]
	v_mfma_f32_16x16x32_bf16 v[2:5], v[158:161], v[208:211], v[2:5]
	s_barrier
	s_add_i32 s68, 0, 0x18000
	s_add_i32 s69, 0, 0x1c000
	v_add_u32_e32 v142, s68, v230
	v_add_u32_e32 v158, s69, v230
	ds_read_b128 v[114:117], v142
	ds_read_b128 v[126:129], v142 offset:1024
	ds_read_b128 v[138:141], v142 offset:2048
	ds_read_b128 v[142:145], v142 offset:3072
	ds_read_b128 v[146:149], v158
	ds_read_b128 v[150:153], v158 offset:1024
	ds_read_b128 v[154:157], v158 offset:2048
	ds_read_b128 v[158:161], v158 offset:3072
	s_add_u32 s30, s44, 0x180000
	s_addc_u32 s31, s45, 0
	s_mov_b32 m0, s54
	ds_read_b128 v[162:165], v235 offset:32768
	ds_read_b128 v[166:169], v235 offset:33792
	ds_read_b128 v[170:173], v235 offset:34816
	ds_read_b128 v[174:177], v235 offset:35840
	ds_read_b128 v[178:181], v235 offset:36864
	ds_read_b128 v[182:185], v235 offset:37888
	ds_read_b128 v[204:207], v235 offset:38912
	ds_read_b128 v[208:211], v235 offset:39936
	global_load_lds_dwordx4 v194, s[30:31]
	s_mov_b32 m0, s55
	s_nop 0
	global_load_lds_dwordx4 v196, s[30:31]
	s_waitcnt vmcnt(8)
	s_waitcnt lgkmcnt(0)
	s_barrier
	v_mfma_f32_16x16x32_bf16 v[134:137], v[114:117], v[162:165], v[134:137]
	v_mfma_f32_16x16x32_bf16 v[130:133], v[138:141], v[162:165], v[130:133]
	v_mfma_f32_16x16x32_bf16 v[110:113], v[114:117], v[170:173], v[110:113]
	v_mfma_f32_16x16x32_bf16 v[106:109], v[138:141], v[170:173], v[106:109]
	v_mfma_f32_16x16x32_bf16 v[94:97], v[114:117], v[178:181], v[94:97]
	v_mfma_f32_16x16x32_bf16 v[90:93], v[138:141], v[178:181], v[90:93]
	v_mfma_f32_16x16x32_bf16 v[78:81], v[114:117], v[204:207], v[78:81]
	v_mfma_f32_16x16x32_bf16 v[74:77], v[138:141], v[204:207], v[74:77]
	v_mfma_f32_16x16x32_bf16 v[134:137], v[126:129], v[166:169], v[134:137]
	v_mfma_f32_16x16x32_bf16 v[130:133], v[142:145], v[166:169], v[130:133]
	v_mfma_f32_16x16x32_bf16 v[110:113], v[126:129], v[174:177], v[110:113]
	v_mfma_f32_16x16x32_bf16 v[106:109], v[142:145], v[174:177], v[106:109]
	v_mfma_f32_16x16x32_bf16 v[94:97], v[126:129], v[182:185], v[94:97]
	v_mfma_f32_16x16x32_bf16 v[90:93], v[142:145], v[182:185], v[90:93]
	v_mfma_f32_16x16x32_bf16 v[78:81], v[126:129], v[208:211], v[78:81]
	v_mfma_f32_16x16x32_bf16 v[74:77], v[142:145], v[208:211], v[74:77]
	v_mfma_f32_16x16x32_bf16 v[122:125], v[146:149], v[162:165], v[122:125]
	v_mfma_f32_16x16x32_bf16 v[118:121], v[154:157], v[162:165], v[118:121]
	v_mfma_f32_16x16x32_bf16 v[102:105], v[146:149], v[170:173], v[102:105]
	v_mfma_f32_16x16x32_bf16 v[98:101], v[154:157], v[170:173], v[98:101]
	v_mfma_f32_16x16x32_bf16 v[86:89], v[146:149], v[178:181], v[86:89]
	v_mfma_f32_16x16x32_bf16 v[82:85], v[154:157], v[178:181], v[82:85]
	v_mfma_f32_16x16x32_bf16 v[70:73], v[146:149], v[204:207], v[70:73]
	v_mfma_f32_16x16x32_bf16 v[66:69], v[154:157], v[204:207], v[66:69]
	v_mfma_f32_16x16x32_bf16 v[122:125], v[150:153], v[166:169], v[122:125]
	v_mfma_f32_16x16x32_bf16 v[118:121], v[158:161], v[166:169], v[118:121]
	v_mfma_f32_16x16x32_bf16 v[102:105], v[150:153], v[174:177], v[102:105]
	v_mfma_f32_16x16x32_bf16 v[98:101], v[158:161], v[174:177], v[98:101]
	v_mfma_f32_16x16x32_bf16 v[86:89], v[150:153], v[182:185], v[86:89]
	v_mfma_f32_16x16x32_bf16 v[82:85], v[158:161], v[182:185], v[82:85]
	v_mfma_f32_16x16x32_bf16 v[70:73], v[150:153], v[208:211], v[70:73]
	v_mfma_f32_16x16x32_bf16 v[66:69], v[158:161], v[208:211], v[66:69]
	s_barrier
; #define PG8_STAGE(bufoff, gbase, voff) do { _Pragma("unroll") for (int _i = 0; _i < 2; ++_i) \
;         __builtin_amdgcn_global_load_lds((const unsigned*)((const char*)(gbase) + (voff)[_i]), (PG8_LAS unsigned*)(lds + (bufoff) + ldsw + _i * 8192), 16, 0, 0); } while (0)
; #define PG8_LDA(dst, b, h) do { _Pragma("unroll") for (int m = 0; m < 4; ++m) _Pragma("unroll") for (int k = 0; k < 2; ++k) dst[m][k] = *(const PG8_LAS bf16x8*)(lds + PG8_SA(b, h) + aoff + m * 2048 + k * 1024); } while (0)
; #define PG8_MMA(ai, bj, At, Bt) do { __builtin_amdgcn_s_setprio(1); _Pragma("unroll") for (int m = 0; m < 4; ++m) _Pragma("unroll") for (int n = 0; n < 2; ++n) _Pragma("unroll") for (int k = 0; k < 2; ++k) \
;         acc[ai][bj][m][n] = __builtin_amdgcn_mfma_f32_16x16x32_bf16(Bt[n][k], At[m][k], acc[ai][bj][m][n], 0, 0, 0); __builtin_amdgcn_s_setprio(0); } while (0)
; #define PG8_WAIT_V(n) asm volatile("s_waitcnt vmcnt(" #n ")" ::: "memory")
; #define PG8_WAIT_L(n) asm volatile("s_waitcnt lgkmcnt(" #n ")" ::: "memory")
; #define PG8_BAR __builtin_amdgcn_s_barrier()
; #define PG8_SCHED __builtin_amdgcn_sched_barrier(0)
; template <class Epi, class Sched, bool ALIGN_EPI = false, bool SP2 = false>
; __device__ __forceinline__ void gemm_phase(PG8_LAS unsigned char* lds, const Gemm g, const Sched& S, const Epi& E, const int wv) {
;     ...
;             PG8_LDA(At, 1, 1); PG8_STAGE(PG8_SB(1, 0), b3, voffB); PG8_STAGE(PG8_SB(1, 1), b3 + hstepB, voffB); PG8_STAGE(PG8_SA(1, 0), a3, voffA);
;             PG8_WAIT_V(8); PG8_WAIT_L(0); PG8_BAR; PG8_MMA(1, 0, At, B0); PG8_MMA(1, 1, At, B1); PG8_BAR; PG8_SCHED;
	s_add_i32 s30, s68, s47
	s_add_i32 m0, s30, 0xffffff80
	ds_read_b128 v[162:165], v235 offset:49152
	ds_read_b128 v[166:169], v235 offset:50176
	ds_read_b128 v[170:173], v235 offset:51200
	ds_read_b128 v[174:177], v235 offset:52224
	ds_read_b128 v[178:181], v235 offset:53248
	ds_read_b128 v[182:185], v235 offset:54272
	ds_read_b128 v[204:207], v235 offset:55296
	ds_read_b128 v[208:211], v235 offset:56320
	global_load_lds_dwordx4 v[190:191], off offset:128
	s_add_i32 m0, s30, 0x1f80
	s_add_i32 s30, s69, s47
	global_load_lds_dwordx4 v[192:193], off offset:128
	s_add_i32 m0, s30, 0xffffff80
	s_nop 0
	global_load_lds_dwordx4 v[212:213], off offset:128
	s_add_i32 m0, s30, 0x1f80
	s_nop 0
	global_load_lds_dwordx4 v[214:215], off offset:128
	s_add_i32 m0, s57, 0xffffff80
	s_nop 0
	global_load_lds_dwordx4 v194, s[44:45] offset:128
	s_add_i32 m0, s58, 0xffffff80
	s_nop 0
	global_load_lds_dwordx4 v196, s[44:45] offset:128
	s_waitcnt vmcnt(8)
	s_waitcnt lgkmcnt(0)
	s_barrier
	v_mfma_f32_16x16x32_bf16 v[62:65], v[114:117], v[162:165], v[62:65]
	v_mfma_f32_16x16x32_bf16 v[58:61], v[138:141], v[162:165], v[58:61]
	v_mfma_f32_16x16x32_bf16 v[46:49], v[114:117], v[170:173], v[46:49]
	v_mfma_f32_16x16x32_bf16 v[42:45], v[138:141], v[170:173], v[42:45]
	v_mfma_f32_16x16x32_bf16 v[30:33], v[114:117], v[178:181], v[30:33]
	v_mfma_f32_16x16x32_bf16 v[26:29], v[138:141], v[178:181], v[26:29]
	v_mfma_f32_16x16x32_bf16 v[14:17], v[114:117], v[204:207], v[14:17]
	v_mfma_f32_16x16x32_bf16 v[10:13], v[138:141], v[204:207], v[10:13]
	v_mfma_f32_16x16x32_bf16 v[62:65], v[126:129], v[166:169], v[62:65]
	v_mfma_f32_16x16x32_bf16 v[58:61], v[142:145], v[166:169], v[58:61]
	v_mfma_f32_16x16x32_bf16 v[46:49], v[126:129], v[174:177], v[46:49]
	v_mfma_f32_16x16x32_bf16 v[42:45], v[142:145], v[174:177], v[42:45]
	v_mfma_f32_16x16x32_bf16 v[30:33], v[126:129], v[182:185], v[30:33]
	v_mfma_f32_16x16x32_bf16 v[26:29], v[142:145], v[182:185], v[26:29]
	v_mfma_f32_16x16x32_bf16 v[14:17], v[126:129], v[208:211], v[14:17]
	v_mfma_f32_16x16x32_bf16 v[10:13], v[142:145], v[208:211], v[10:13]
	v_mfma_f32_16x16x32_bf16 v[54:57], v[146:149], v[162:165], v[54:57]
	v_mfma_f32_16x16x32_bf16 v[50:53], v[154:157], v[162:165], v[50:53]
	v_mfma_f32_16x16x32_bf16 v[38:41], v[146:149], v[170:173], v[38:41]
	v_mfma_f32_16x16x32_bf16 v[34:37], v[154:157], v[170:173], v[34:37]
	v_mfma_f32_16x16x32_bf16 v[22:25], v[146:149], v[178:181], v[22:25]
	v_mfma_f32_16x16x32_bf16 v[18:21], v[154:157], v[178:181], v[18:21]
	v_mfma_f32_16x16x32_bf16 v[6:9], v[146:149], v[204:207], v[6:9]
	v_mfma_f32_16x16x32_bf16 v[2:5], v[154:157], v[204:207], v[2:5]
	v_mfma_f32_16x16x32_bf16 v[54:57], v[150:153], v[166:169], v[54:57]
	v_mfma_f32_16x16x32_bf16 v[50:53], v[158:161], v[166:169], v[50:53]
	v_mfma_f32_16x16x32_bf16 v[38:41], v[150:153], v[174:177], v[38:41]
	v_mfma_f32_16x16x32_bf16 v[34:37], v[158:161], v[174:177], v[34:37]
	v_mfma_f32_16x16x32_bf16 v[22:25], v[150:153], v[182:185], v[22:25]
	v_mfma_f32_16x16x32_bf16 v[18:21], v[158:161], v[182:185], v[18:21]
	v_mfma_f32_16x16x32_bf16 v[6:9], v[150:153], v[208:211], v[6:9]
	v_mfma_f32_16x16x32_bf16 v[2:5], v[158:161], v[208:211], v[2:5]
	s_barrier
	s_add_u32 s65, s65, 0x100
	s_addc_u32 s66, s66, 0
	s_cmp_ge_i32 s67, s56
	s_mov_b64 s[30:31], s[34:35]
	s_mov_b32 s44, s67
	s_cbranch_scc0 .LBB0_1676
	s_movk_i32 s68, 0x4000
	s_movk_i32 s69, 0x6000
	s_mov_b32 s70, 0x18000
	s_mov_b32 s71, 0x3f317217
	s_and_b64 vcc, exec, s[28:29]
	s_cbranch_vccz .LBB0_1652
